# write-through (sc1) epilogue stores in the two in-projection phases (no loads in those epilogues), shortening the L2 write-back at the following grid barrier
# baseline (speedup 1.0000x reference)
; __device__ __forceinline__ u32x2 pack4(f32x4 v) { u32x2 w; w.x = cvt_pk_bf16(v[0], v[1]); w.y = cvt_pk_bf16(v[2], v[3]); return w; }
; template <int EK>
; __device__ __forceinline__ void epi_tile(const f32x4 (&acc)[2][2][4][2], const Unit& u, int wr, int wc, int fr, int fq, const EpiArgs& E, const LAS float* rt) {
;     const int rowb = u.pm * BM + wr * 64 + fr;
;     float rr[2][4];
;     if (EK != EK_RES) {
; #pragma unroll
;         for (int ai = 0; ai < 2; ++ai)
; #pragma unroll
;             for (int m = 0; m < 4; ++m) rr[ai][m] = rt[ai * HALF + wr * 64 + m * 16 + fr];
;     }
; #pragma unroll
;     for (int ai = 0; ai < 2; ++ai) {
; #pragma unroll
;         for (int m = 0; m < 4; ++m) {
;             const int row = rowb + ai * HALF + m * 16;
;             if (EK == EK_SCALE) {
;                 const float r = rr[ai][m];
; #pragma unroll
;                 for (int bj = 0; bj < 2; ++bj) { const int col = u.pn * BM + bj * HALF + wc * 32 + fq * 8;
;                     const u32x2 lo = pack4(acc[ai][bj][m][0] * r), hi = pack4(acc[ai][bj][m][1] * r);
;                     *(u32x4*)(E.ob + (size_t)row * E.ldb + col) = (u32x4){lo.x, lo.y, hi.x, hi.y}; }
.LBB0_201:
	v_lshl_add_u32 v146, s56, 10, v153
	ds_read2_b32 v[160:161], v146 offset1:16
	ds_read2_b32 v[162:163], v146 offset0:32 offset1:48
	ds_read2_b32 v[150:151], v146 offset0:128 offset1:144
	ds_read2_b32 v[146:147], v146 offset0:160 offset1:176
	v_lshl_add_u32 v164, s66, 8, v1
	s_waitcnt lgkmcnt(0)
	v_pk_mul_f32 v[158:159], v[112:113], v[160:161] op_sel_hi:[1,0]
	v_pk_mul_f32 v[156:157], v[110:111], v[160:161] op_sel_hi:[1,0]
	v_lshl_or_b32 v148, s68, 8, v154
	v_ashrrev_i32_e32 v165, 31, v164
	v_cvt_pk_bf16_f32 v156, v156, v157
	v_cvt_pk_bf16_f32 v157, v158, v159
	v_pk_mul_f32 v[166:167], v[108:109], v[160:161] op_sel_hi:[1,0]
	v_pk_mul_f32 v[158:159], v[106:107], v[160:161] op_sel_hi:[1,0]
	v_ashrrev_i32_e32 v149, 31, v148
	v_cvt_pk_bf16_f32 v158, v158, v159
	v_cvt_pk_bf16_f32 v159, v166, v167
	v_lshlrev_b64 v[166:167], 12, v[164:165]
	v_lshl_add_u64 v[166:167], s[64:65], 0, v[166:167]
	v_lshlrev_b64 v[168:169], 1, v[148:149]
	v_lshl_add_u64 v[148:149], v[166:167], 0, v[168:169]
	global_store_dwordx4 v[148:149], v[156:159], off sc1
	v_pk_mul_f32 v[166:167], v[76:77], v[160:161] op_sel_hi:[1,0]
	s_add_u32 s78, s58, 0xffffff00
	v_pk_mul_f32 v[158:159], v[80:81], v[160:161] op_sel_hi:[1,0]
	v_pk_mul_f32 v[156:157], v[78:79], v[160:161] op_sel_hi:[1,0]
	s_addc_u32 s79, s59, -1
	v_cvt_pk_bf16_f32 v156, v156, v157
	v_cvt_pk_bf16_f32 v157, v158, v159
	v_pk_mul_f32 v[158:159], v[74:75], v[160:161] op_sel_hi:[1,0]
	v_mov_b32_e32 v160, v161
	v_cvt_pk_bf16_f32 v158, v158, v159
	v_cvt_pk_bf16_f32 v159, v166, v167
	v_or_b32_e32 v166, 16, v164
	v_ashrrev_i32_e32 v167, 31, v166
	global_store_dwordx4 v[148:149], v[156:159], off offset:256 sc1
	v_lshlrev_b64 v[166:167], 12, v[166:167]
	v_lshl_add_u64 v[166:167], s[64:65], 0, v[166:167]
	v_pk_mul_f32 v[158:159], v[104:105], v[160:161] op_sel_hi:[1,0]
	v_pk_mul_f32 v[156:157], v[102:103], v[160:161] op_sel_hi:[1,0]
	v_pk_mul_f32 v[170:171], v[100:101], v[160:161] op_sel_hi:[1,0]
	v_cvt_pk_bf16_f32 v156, v156, v157
	v_cvt_pk_bf16_f32 v157, v158, v159
	v_pk_mul_f32 v[158:159], v[98:99], v[160:161] op_sel_hi:[1,0]
	v_lshl_add_u64 v[166:167], v[166:167], 0, v[168:169]
	v_cvt_pk_bf16_f32 v158, v158, v159
	v_cvt_pk_bf16_f32 v159, v170, v171
	global_store_dwordx4 v[166:167], v[156:159], off sc1
	v_pk_mul_f32 v[170:171], v[68:69], v[160:161] op_sel_hi:[1,0]
	s_mov_b64 s[58:59], 0x80000
	v_pk_mul_f32 v[158:159], v[72:73], v[160:161] op_sel_hi:[1,0]
	v_pk_mul_f32 v[156:157], v[70:71], v[160:161] op_sel_hi:[1,0]
	s_nop 0
	v_cvt_pk_bf16_f32 v156, v156, v157
	v_cvt_pk_bf16_f32 v157, v158, v159
	v_pk_mul_f32 v[158:159], v[66:67], v[160:161] op_sel_hi:[1,0]
	v_or_b32_e32 v160, 32, v164
	v_cvt_pk_bf16_f32 v158, v158, v159
	v_cvt_pk_bf16_f32 v159, v170, v171
	v_ashrrev_i32_e32 v161, 31, v160
	global_store_dwordx4 v[166:167], v[156:159], off offset:256 sc1
	v_lshlrev_b64 v[160:161], 12, v[160:161]
	v_lshl_add_u64 v[160:161], s[64:65], 0, v[160:161]
	v_pk_mul_f32 v[158:159], v[96:97], v[162:163] op_sel_hi:[1,0]
	v_pk_mul_f32 v[156:157], v[94:95], v[162:163] op_sel_hi:[1,0]
	v_pk_mul_f32 v[166:167], v[92:93], v[162:163] op_sel_hi:[1,0]
	v_cvt_pk_bf16_f32 v156, v156, v157
	v_cvt_pk_bf16_f32 v157, v158, v159
	v_pk_mul_f32 v[158:159], v[90:91], v[162:163] op_sel_hi:[1,0]
	v_lshl_add_u64 v[160:161], v[160:161], 0, v[168:169]
	v_cvt_pk_bf16_f32 v158, v158, v159
	v_cvt_pk_bf16_f32 v159, v166, v167
	global_store_dwordx4 v[160:161], v[156:159], off sc1
	v_pk_mul_f32 v[166:167], v[60:61], v[162:163] op_sel_hi:[1,0]
	s_nop 0
	v_pk_mul_f32 v[158:159], v[64:65], v[162:163] op_sel_hi:[1,0]
	v_pk_mul_f32 v[156:157], v[62:63], v[162:163] op_sel_hi:[1,0]
	s_nop 0
	v_cvt_pk_bf16_f32 v156, v156, v157
	v_cvt_pk_bf16_f32 v157, v158, v159
	v_pk_mul_f32 v[158:159], v[58:59], v[162:163] op_sel_hi:[1,0]
	v_mov_b32_e32 v162, v163
	v_cvt_pk_bf16_f32 v158, v158, v159
	v_cvt_pk_bf16_f32 v159, v166, v167
	global_store_dwordx4 v[160:161], v[156:159], off offset:256 sc1
	v_or_b32_e32 v160, 48, v164
	v_ashrrev_i32_e32 v161, 31, v160
	v_pk_mul_f32 v[158:159], v[88:89], v[162:163] op_sel_hi:[1,0]
	v_pk_mul_f32 v[156:157], v[86:87], v[162:163] op_sel_hi:[1,0]
	v_lshlrev_b64 v[160:161], 12, v[160:161]
	v_cvt_pk_bf16_f32 v156, v156, v157
	v_cvt_pk_bf16_f32 v157, v158, v159
	v_pk_mul_f32 v[158:159], v[82:83], v[162:163] op_sel_hi:[1,0]
	v_lshl_add_u64 v[160:161], s[64:65], 0, v[160:161]
	v_pk_mul_f32 v[164:165], v[84:85], v[162:163] op_sel_hi:[1,0]
	v_cvt_pk_bf16_f32 v158, v158, v159
	v_lshl_add_u64 v[160:161], v[160:161], 0, v[168:169]
	v_cvt_pk_bf16_f32 v159, v164, v165
	global_store_dwordx4 v[160:161], v[156:159], off sc1
	v_pk_mul_f32 v[164:165], v[52:53], v[162:163] op_sel_hi:[1,0]
	s_nop 0
	v_pk_mul_f32 v[158:159], v[56:57], v[162:163] op_sel_hi:[1,0]
	v_pk_mul_f32 v[156:157], v[54:55], v[162:163] op_sel_hi:[1,0]
	s_nop 0
	v_cvt_pk_bf16_f32 v156, v156, v157
	v_cvt_pk_bf16_f32 v157, v158, v159
	v_pk_mul_f32 v[158:159], v[50:51], v[162:163] op_sel_hi:[1,0]
; __device__ __forceinline__ u32x2 pack4(f32x4 v) { u32x2 w; w.x = cvt_pk_bf16(v[0], v[1]); w.y = cvt_pk_bf16(v[2], v[3]); return w; }
; #define PG8_BAR __builtin_amdgcn_s_barrier()
; template <int EK>
; __device__ __forceinline__ void epi_tile(const f32x4 (&acc)[2][2][4][2], const Unit& u, int wr, int wc, int fr, int fq, const EpiArgs& E, const LAS float* rt) {
;     ...
;             if (EK == EK_SCALE) {
;                 const float r = rr[ai][m];
; #pragma unroll
;                 for (int bj = 0; bj < 2; ++bj) { const int col = u.pn * BM + bj * HALF + wc * 32 + fq * 8;
;                     const u32x2 lo = pack4(acc[ai][bj][m][0] * r), hi = pack4(acc[ai][bj][m][1] * r);
;                     *(u32x4*)(E.ob + (size_t)row * E.ldb + col) = (u32x4){lo.x, lo.y, hi.x, hi.y}; }
; template <int EK, int SK = -1>
; __device__ __forceinline__ void gemm_phase(LAS unsigned char* lds, const bf16_t* A, const bf16_t* Bt, int nM, int N, int K, const EpiArgs& E) {
;     ...
;         if (EK != EK_FINAL) epi_tile<EK>(acc, cur, wr, wc, fr, fq, E, rtab + ui * 256);
;         if (!has_next) break;
; #pragma unroll
;         for (int a = 0; a < 2; ++a)
; #pragma unroll
;             for (int b = 0; b < 2; ++b)
; #pragma unroll
;                 for (int m = 0; m < 4; ++m)
; #pragma unroll
;                     for (int n = 0; n < 2; ++n) acc[a][b][m][n] = (f32x4){0.f, 0.f, 0.f, 0.f};
;         cur = nxt; cA = nA; cB = nB; ++ui;
;         if (wr == 1) PG8_BAR;
	s_nop 0
	v_cvt_pk_bf16_f32 v158, v158, v159
	v_cvt_pk_bf16_f32 v159, v164, v165
	global_store_dwordx4 v[160:161], v[156:159], off offset:256 sc1
	v_pk_mul_f32 v[160:161], v[44:45], v[150:151] op_sel_hi:[1,0]
	s_nop 0
	v_pk_mul_f32 v[158:159], v[48:49], v[150:151] op_sel_hi:[1,0]
	v_pk_mul_f32 v[156:157], v[46:47], v[150:151] op_sel_hi:[1,0]
	s_nop 0
	v_cvt_pk_bf16_f32 v156, v156, v157
	v_cvt_pk_bf16_f32 v157, v158, v159
	v_pk_mul_f32 v[158:159], v[42:43], v[150:151] op_sel_hi:[1,0]
	s_nop 0
	v_cvt_pk_bf16_f32 v158, v158, v159
	v_cvt_pk_bf16_f32 v159, v160, v161
	v_lshl_add_u64 v[160:161], v[148:149], 0, s[58:59]
	s_mov_b32 s58, 0x80000
	v_add_co_u32_e32 v162, vcc, s58, v148
	s_mov_b64 s[58:59], 0x90000
	s_nop 0
	v_addc_co_u32_e32 v163, vcc, 0, v149, vcc
	global_store_dwordx4 v[162:163], v[156:159], off sc1
	v_pk_mul_f32 v[162:163], v[12:13], v[150:151] op_sel_hi:[1,0]
	s_nop 0
	v_pk_mul_f32 v[158:159], v[16:17], v[150:151] op_sel_hi:[1,0]
	v_pk_mul_f32 v[156:157], v[14:15], v[150:151] op_sel_hi:[1,0]
	s_nop 0
	v_cvt_pk_bf16_f32 v156, v156, v157
	v_cvt_pk_bf16_f32 v157, v158, v159
	v_pk_mul_f32 v[158:159], v[10:11], v[150:151] op_sel_hi:[1,0]
	v_mov_b32_e32 v150, v151
	v_cvt_pk_bf16_f32 v158, v158, v159
	v_cvt_pk_bf16_f32 v159, v162, v163
	global_store_dwordx4 v[160:161], v[156:159], off offset:256 sc1
	v_pk_mul_f32 v[160:161], v[36:37], v[150:151] op_sel_hi:[1,0]
	s_nop 0
	v_pk_mul_f32 v[158:159], v[40:41], v[150:151] op_sel_hi:[1,0]
	v_pk_mul_f32 v[156:157], v[38:39], v[150:151] op_sel_hi:[1,0]
	s_nop 0
	v_cvt_pk_bf16_f32 v156, v156, v157
	v_cvt_pk_bf16_f32 v157, v158, v159
	v_pk_mul_f32 v[158:159], v[34:35], v[150:151] op_sel_hi:[1,0]
	s_nop 0
	v_cvt_pk_bf16_f32 v158, v158, v159
	v_cvt_pk_bf16_f32 v159, v160, v161
	v_lshl_add_u64 v[160:161], v[148:149], 0, s[58:59]
	s_mov_b32 s58, 0x90000
	v_add_co_u32_e32 v162, vcc, s58, v148
	s_mov_b64 s[58:59], 0xa0000
	s_nop 0
	v_addc_co_u32_e32 v163, vcc, 0, v149, vcc
	global_store_dwordx4 v[162:163], v[156:159], off sc1
	v_pk_mul_f32 v[162:163], v[4:5], v[150:151] op_sel_hi:[1,0]
	s_nop 0
	v_pk_mul_f32 v[156:157], v[6:7], v[150:151] op_sel_hi:[1,0]
	v_pk_mul_f32 v[158:159], v[8:9], v[150:151] op_sel_hi:[1,0]
	v_cvt_pk_bf16_f32 v156, v156, v157
	v_pk_mul_f32 v[150:151], v[2:3], v[150:151] op_sel_hi:[1,0]
	v_cvt_pk_bf16_f32 v157, v158, v159
	v_cvt_pk_bf16_f32 v159, v162, v163
	s_nop 0
	v_cvt_pk_bf16_f32 v158, v150, v151
	global_store_dwordx4 v[160:161], v[156:159], off offset:256 sc1
	v_pk_mul_f32 v[150:151], v[32:33], v[146:147] op_sel_hi:[1,0]
	s_nop 0
	v_pk_mul_f32 v[156:157], v[30:31], v[146:147] op_sel_hi:[1,0]
	v_pk_mul_f32 v[158:159], v[26:27], v[146:147] op_sel_hi:[1,0]
	v_cvt_pk_bf16_f32 v156, v156, v157
	v_cvt_pk_bf16_f32 v157, v150, v151
	v_pk_mul_f32 v[150:151], v[28:29], v[146:147] op_sel_hi:[1,0]
	v_cvt_pk_bf16_f32 v158, v158, v159
	s_nop 0
	v_cvt_pk_bf16_f32 v159, v150, v151
	v_lshl_add_u64 v[150:151], v[148:149], 0, s[58:59]
	s_mov_b32 s58, 0xa0000
	v_add_co_u32_e32 v160, vcc, s58, v148
	s_mov_b64 s[58:59], 0xb0000
	s_nop 0
	v_addc_co_u32_e32 v161, vcc, 0, v149, vcc
	global_store_dwordx4 v[160:161], v[156:159], off sc1
	v_pk_mul_f32 v[160:161], v[120:121], v[146:147] op_sel_hi:[1,0]
	s_nop 0
	v_pk_mul_f32 v[158:159], v[116:117], v[146:147] op_sel_hi:[1,0]
	v_pk_mul_f32 v[156:157], v[114:115], v[146:147] op_sel_hi:[1,0]
	s_nop 0
	v_cvt_pk_bf16_f32 v156, v156, v157
	v_cvt_pk_bf16_f32 v157, v158, v159
	v_pk_mul_f32 v[158:159], v[118:119], v[146:147] op_sel_hi:[1,0]
	s_nop 0
	v_cvt_pk_bf16_f32 v158, v158, v159
	v_cvt_pk_bf16_f32 v159, v160, v161
	global_store_dwordx4 v[150:151], v[156:159], off offset:256 sc1
	v_mov_b32_e32 v150, v147
	v_pk_mul_f32 v[146:147], v[24:25], v[150:151] op_sel_hi:[1,0]
	v_pk_mul_f32 v[156:157], v[22:23], v[150:151] op_sel_hi:[1,0]
	v_pk_mul_f32 v[158:159], v[18:19], v[150:151] op_sel_hi:[1,0]
	v_cvt_pk_bf16_f32 v156, v156, v157
	v_cvt_pk_bf16_f32 v157, v146, v147
	v_pk_mul_f32 v[146:147], v[20:21], v[150:151] op_sel_hi:[1,0]
	v_lshl_add_u64 v[160:161], v[148:149], 0, s[58:59]
	s_mov_b32 s58, 0xb0000
	v_cvt_pk_bf16_f32 v158, v158, v159
	v_cvt_pk_bf16_f32 v159, v146, v147
	v_add_co_u32_e32 v146, vcc, s58, v148
	s_nop 1
	v_addc_co_u32_e32 v147, vcc, 0, v149, vcc
	global_store_dwordx4 v[146:147], v[156:159], off sc1
	v_pk_mul_f32 v[148:149], v[124:125], v[150:151] op_sel_hi:[1,0]
	v_pk_mul_f32 v[146:147], v[122:123], v[150:151] op_sel_hi:[1,0]
	v_pk_mul_f32 v[156:157], v[128:129], v[150:151] op_sel_hi:[1,0]
	v_cvt_pk_bf16_f32 v146, v146, v147
	v_cvt_pk_bf16_f32 v147, v148, v149
	v_pk_mul_f32 v[148:149], v[126:127], v[150:151] op_sel_hi:[1,0]
	s_andn2_b64 vcc, exec, s[6:7]
	v_cvt_pk_bf16_f32 v148, v148, v149
	v_cvt_pk_bf16_f32 v149, v156, v157
	global_store_dwordx4 v[160:161], v[146:149], off offset:256 sc1
	s_cbranch_vccnz .LBB0_204
	s_andn2_b64 vcc, exec, s[8:9]
	s_cbranch_vccnz .LBB0_190
	s_barrier
	s_branch .LBB0_190

; __device__ __forceinline__ float dot4(f32x4 v) { return (v[0] * v[0] + v[1] * v[1]) + (v[2] * v[2] + v[3] * v[3]); }
; __device__ __forceinline__ u32x2 pack4(f32x4 v) { u32x2 w; w.x = cvt_pk_bf16(v[0], v[1]); w.y = cvt_pk_bf16(v[2], v[3]); return w; }
; __device__ __forceinline__ f32x2 gelu_pk(f32x2 v) {
;     const f32x2 av = __builtin_elementwise_abs(v), d = av * 0.2316418882f + 1.0f;
;     f32x2 t; t.x = __builtin_amdgcn_rcpf(d.x); t.y = __builtin_amdgcn_rcpf(d.y);
;     f32x2 q = t * 0.5307027145f + (-0.7265760135f); q = q * t + 0.7107068705f; q = q * t + (-0.142248368f); q = q * t + 0.127414796f; q = q * t;
;     const f32x2 s = (v * v) * (-0.72134752044f);
;     f32x2 e; e.x = __builtin_amdgcn_exp2f(s.x); e.y = __builtin_amdgcn_exp2f(s.y);
;     const f32x2 m = v * (q * e), r = v - m;
;     f32x2 o; o.x = v.x < 0.f ? m.x : r.x; o.y = v.y < 0.f ? m.y : r.y; return o;
; }
; __device__ __forceinline__ f32x4 gelu4(f32x4 v) { f32x2 a = gelu_pk((f32x2){v[0], v[1]}), b = gelu_pk((f32x2){v[2], v[3]}); return (f32x4){a.x, a.y, b.x, b.y}; }
; template <int EK>
; __device__ __forceinline__ void epi_tile(const f32x4 (&acc)[2][2][4][2], const Unit& u, int wr, int wc, int fr, int fq, const EpiArgs& E, const LAS float* rt) {
;     ...
;             } else if (EK == EK_GELU) {
;                 const float r = rr[ai][m]; float ss = 0.f;
; #pragma unroll
;                 for (int bj = 0; bj < 2; ++bj) { const int col = u.pn * BM + bj * HALF + wc * 32 + fq * 8;
;                     const f32x4 z0 = gelu4(acc[ai][bj][m][0] * r), z1 = gelu4(acc[ai][bj][m][1] * r); ss += dot4(z0) + dot4(z1);
;                     const u32x2 lo = pack4(z0), hi = pack4(z1);
;                     *(u32x4*)(E.ob + (size_t)row * E.ldb + col) = (u32x4){lo.x, lo.y, hi.x, hi.y}; }
.LBB0_932:
	v_lshl_add_u32 v146, s84, 10, v161
	ds_read2_b32 v[156:157], v146 offset1:16
	ds_read2_b32 v[154:155], v146 offset0:32 offset1:48
	ds_read2_b32 v[152:153], v146 offset0:128 offset1:144
	ds_read2_b32 v[148:149], v146 offset0:160 offset1:176
	v_lshl_add_u32 v150, s22, 8, v1
	s_waitcnt lgkmcnt(0)
	v_pk_mul_f32 v[166:167], v[110:111], v[156:157] op_sel_hi:[1,0]
	v_pk_mul_f32 v[170:171], v[112:113], v[156:157] op_sel_hi:[1,0]
	v_and_b32_e32 v159, 0x7fffffff, v167
	v_and_b32_e32 v158, 0x7fffffff, v166
	v_pk_fma_f32 v[158:159], v[158:159], s[40:41], 1.0 op_sel_hi:[1,0,0]
	v_pk_mul_f32 v[174:175], v[166:167], v[166:167]
	v_rcp_f32_e32 v168, v158
	v_rcp_f32_e32 v169, v159
	v_mov_b64_e32 v[158:159], s[44:45]
	v_pk_mul_f32 v[174:175], v[174:175], s[58:59] op_sel_hi:[1,0]
	v_and_b32_e32 v177, 0x7fffffff, v171
	v_pk_fma_f32 v[172:173], v[168:169], s[42:43], v[158:159] op_sel_hi:[1,0,0]
	v_exp_f32_e32 v174, v174
	v_pk_fma_f32 v[172:173], v[168:169], v[172:173], s[52:53] op_sel_hi:[1,1,0]
	v_exp_f32_e32 v175, v175
	v_pk_fma_f32 v[172:173], v[168:169], v[172:173], s[54:55] op_sel_hi:[1,1,0]
	v_and_b32_e32 v176, 0x7fffffff, v170
	v_pk_fma_f32 v[172:173], v[168:169], v[172:173], s[56:57] op_sel_hi:[1,1,0]
	v_pk_fma_f32 v[176:177], v[176:177], s[40:41], 1.0 op_sel_hi:[1,0,0]
	v_pk_mul_f32 v[168:169], v[168:169], v[172:173]
	v_rcp_f32_e32 v176, v176
	v_rcp_f32_e32 v177, v177
	v_pk_mul_f32 v[168:169], v[174:175], v[168:169]
	v_cmp_gt_f32_e32 vcc, 0, v166
	v_pk_mul_f32 v[174:175], v[166:167], v[168:169]
	v_pk_fma_f32 v[168:169], v[166:167], v[168:169], v[166:167] neg_lo:[1,0,0] neg_hi:[1,0,0]
	v_pk_mul_f32 v[172:173], v[170:171], v[170:171]
	v_cndmask_b32_e32 v165, v168, v174, vcc
	v_cmp_gt_f32_e32 vcc, 0, v167
	v_pk_mul_f32 v[172:173], v[172:173], s[58:59] op_sel_hi:[1,0]
	v_ashrrev_i32_e32 v151, 31, v150
	v_cndmask_b32_e32 v166, v169, v175, vcc
	v_pk_fma_f32 v[168:169], v[176:177], s[42:43], v[158:159] op_sel_hi:[1,0,0]
	v_exp_f32_e32 v172, v172
	v_pk_fma_f32 v[168:169], v[176:177], v[168:169], s[52:53] op_sel_hi:[1,1,0]
	v_exp_f32_e32 v173, v173
	v_pk_fma_f32 v[168:169], v[176:177], v[168:169], s[54:55] op_sel_hi:[1,1,0]
	v_pk_mul_f32 v[174:175], v[106:107], v[156:157] op_sel_hi:[1,0]
	v_pk_fma_f32 v[168:169], v[176:177], v[168:169], s[56:57] op_sel_hi:[1,1,0]
	v_cmp_gt_f32_e32 vcc, 0, v170
	v_pk_mul_f32 v[168:169], v[176:177], v[168:169]
	v_and_b32_e32 v177, 0x7fffffff, v175
	v_and_b32_e32 v176, 0x7fffffff, v174
	v_pk_fma_f32 v[176:177], v[176:177], s[40:41], 1.0 op_sel_hi:[1,0,0]
	v_pk_mul_f32 v[168:169], v[172:173], v[168:169]
	v_rcp_f32_e32 v176, v176
	v_rcp_f32_e32 v177, v177
	v_pk_mul_f32 v[172:173], v[170:171], v[168:169]
	v_pk_fma_f32 v[168:169], v[170:171], v[168:169], v[170:171] neg_lo:[1,0,0] neg_hi:[1,0,0]
	v_pk_mul_f32 v[178:179], v[174:175], v[174:175]
	v_cndmask_b32_e32 v167, v168, v172, vcc
	v_cmp_gt_f32_e32 vcc, 0, v171
	v_pk_fma_f32 v[170:171], v[176:177], s[42:43], v[158:159] op_sel_hi:[1,0,0]
	v_pk_mul_f32 v[178:179], v[178:179], s[58:59] op_sel_hi:[1,0]
	v_cndmask_b32_e32 v168, v169, v173, vcc
	v_pk_mul_f32 v[172:173], v[108:109], v[156:157] op_sel_hi:[1,0]
	v_pk_fma_f32 v[170:171], v[176:177], v[170:171], s[52:53] op_sel_hi:[1,1,0]
	v_exp_f32_e32 v178, v178
	v_exp_f32_e32 v179, v179
	v_and_b32_e32 v181, 0x7fffffff, v173
	v_and_b32_e32 v180, 0x7fffffff, v172
	v_pk_fma_f32 v[170:171], v[176:177], v[170:171], s[54:55] op_sel_hi:[1,1,0]
	v_pk_fma_f32 v[180:181], v[180:181], s[40:41], 1.0 op_sel_hi:[1,0,0]
	v_pk_fma_f32 v[170:171], v[176:177], v[170:171], s[56:57] op_sel_hi:[1,1,0]
	v_rcp_f32_e32 v180, v180
	v_rcp_f32_e32 v181, v181
	v_pk_mul_f32 v[170:171], v[176:177], v[170:171]
	v_cmp_gt_f32_e32 vcc, 0, v174
	v_pk_mul_f32 v[170:171], v[178:179], v[170:171]
	v_pk_mul_f32 v[176:177], v[172:173], v[172:173]
	v_pk_mul_f32 v[178:179], v[174:175], v[170:171]
	v_pk_fma_f32 v[170:171], v[174:175], v[170:171], v[174:175] neg_lo:[1,0,0] neg_hi:[1,0,0]
	v_pk_mul_f32 v[176:177], v[176:177], s[58:59] op_sel_hi:[1,0]
	v_cndmask_b32_e32 v169, v170, v178, vcc
	v_cmp_gt_f32_e32 vcc, 0, v175
	v_pk_fma_f32 v[174:175], v[180:181], s[42:43], v[158:159] op_sel_hi:[1,0,0]
	v_exp_f32_e32 v176, v176
	v_pk_fma_f32 v[174:175], v[180:181], v[174:175], s[52:53] op_sel_hi:[1,1,0]
	v_exp_f32_e32 v177, v177
	v_pk_fma_f32 v[174:175], v[180:181], v[174:175], s[54:55] op_sel_hi:[1,1,0]
	v_lshl_or_b32 v146, s26, 8, v162
	v_pk_fma_f32 v[174:175], v[180:181], v[174:175], s[56:57] op_sel_hi:[1,1,0]
	v_cndmask_b32_e32 v170, v171, v179, vcc
	v_pk_mul_f32 v[174:175], v[180:181], v[174:175]
	v_pk_mul_f32 v[180:181], v[78:79], v[156:157] op_sel_hi:[1,0]
	v_pk_mul_f32 v[174:175], v[176:177], v[174:175]
	v_and_b32_e32 v183, 0x7fffffff, v181
	v_and_b32_e32 v182, 0x7fffffff, v180
	v_pk_fma_f32 v[182:183], v[182:183], s[40:41], 1.0 op_sel_hi:[1,0,0]
	v_pk_mul_f32 v[176:177], v[172:173], v[174:175]
	v_rcp_f32_e32 v182, v182
	v_rcp_f32_e32 v183, v183
	v_pk_fma_f32 v[174:175], v[172:173], v[174:175], v[172:173] neg_lo:[1,0,0] neg_hi:[1,0,0]
	v_cmp_gt_f32_e32 vcc, 0, v172
	v_lshlrev_b64 v[178:179], 12, v[150:151]
	v_lshl_add_u64 v[178:179], s[64:65], 0, v[178:179]
	v_cndmask_b32_e32 v171, v174, v176, vcc
	v_cmp_gt_f32_e32 vcc, 0, v173
	v_ashrrev_i32_e32 v147, 31, v146
	v_cvt_pk_bf16_f32 v174, v165, v166
	v_lshl_add_u64 v[184:185], v[146:147], 1, v[178:179]
	v_cndmask_b32_e32 v172, v175, v177, vcc
	v_cvt_pk_bf16_f32 v175, v167, v168
	v_pk_mul_f32 v[178:179], v[180:181], v[180:181]
	v_cvt_pk_bf16_f32 v176, v169, v170
	v_cvt_pk_bf16_f32 v177, v171, v172
	global_store_dwordx4 v[184:185], v[174:177], off sc1
	v_pk_mul_f32 v[178:179], v[178:179], s[58:59] op_sel_hi:[1,0]
; __device__ __forceinline__ float dot4(f32x4 v) { return (v[0] * v[0] + v[1] * v[1]) + (v[2] * v[2] + v[3] * v[3]); }
; __device__ __forceinline__ u32x2 pack4(f32x4 v) { u32x2 w; w.x = cvt_pk_bf16(v[0], v[1]); w.y = cvt_pk_bf16(v[2], v[3]); return w; }
; __device__ __forceinline__ float quad_sum(float s) { s += __shfl_xor(s, 16); s += __shfl_xor(s, 32); return s; }
; __device__ __forceinline__ f32x4 gelu4(f32x4 v) { f32x2 a = gelu_pk((f32x2){v[0], v[1]}), b = gelu_pk((f32x2){v[2], v[3]}); return (f32x4){a.x, a.y, b.x, b.y}; }
; template <int EK>
; __device__ __forceinline__ void epi_tile(const f32x4 (&acc)[2][2][4][2], const Unit& u, int wr, int wc, int fr, int fq, const EpiArgs& E, const LAS float* rt) {
;     ...
;             } else if (EK == EK_GELU) {
;                 const float r = rr[ai][m]; float ss = 0.f;
; #pragma unroll
;                 for (int bj = 0; bj < 2; ++bj) { const int col = u.pn * BM + bj * HALF + wc * 32 + fq * 8;
;                     const f32x4 z0 = gelu4(acc[ai][bj][m][0] * r), z1 = gelu4(acc[ai][bj][m][1] * r); ss += dot4(z0) + dot4(z1);
;                     const u32x2 lo = pack4(z0), hi = pack4(z1);
;                     *(u32x4*)(E.ob + (size_t)row * E.ldb + col) = (u32x4){lo.x, lo.y, hi.x, hi.y}; }
;                 if (u.pn >= 4) { ss = quad_sum(ss); if (fq == 0) E.stOut[(size_t)row * 16 + (u.pn - 4) * 4 + wc] = ss; }
	v_cmp_gt_f32_e32 vcc, 0, v180
	v_pk_fma_f32 v[174:175], v[182:183], s[42:43], v[158:159] op_sel_hi:[1,0,0]
	v_pk_mul_f32 v[176:177], v[80:81], v[156:157] op_sel_hi:[1,0]
	v_pk_fma_f32 v[174:175], v[182:183], v[174:175], s[52:53] op_sel_hi:[1,1,0]
	v_exp_f32_e32 v178, v178
	v_exp_f32_e32 v179, v179
	v_pk_fma_f32 v[174:175], v[182:183], v[174:175], s[54:55] op_sel_hi:[1,1,0]
	v_and_b32_e32 v187, 0x7fffffff, v177
	v_and_b32_e32 v186, 0x7fffffff, v176
	v_pk_fma_f32 v[174:175], v[182:183], v[174:175], s[56:57] op_sel_hi:[1,1,0]
	v_pk_fma_f32 v[186:187], v[186:187], s[40:41], 1.0 op_sel_hi:[1,0,0]
	v_pk_mul_f32 v[174:175], v[182:183], v[174:175]
	v_rcp_f32_e32 v186, v186
	v_rcp_f32_e32 v187, v187
	v_pk_mul_f32 v[174:175], v[178:179], v[174:175]
	v_pk_mul_f32 v[182:183], v[176:177], v[176:177]
	v_pk_mul_f32 v[178:179], v[180:181], v[174:175]
	v_pk_fma_f32 v[174:175], v[180:181], v[174:175], v[180:181] neg_lo:[1,0,0] neg_hi:[1,0,0]
	s_cmp_gt_i32 s26, 3
	v_cndmask_b32_e32 v173, v174, v178, vcc
	v_cmp_gt_f32_e32 vcc, 0, v181
	v_pk_mul_f32 v[180:181], v[182:183], s[58:59] op_sel_hi:[1,0]
	v_pk_mul_f32 v[182:183], v[74:75], v[156:157] op_sel_hi:[1,0]
	v_cndmask_b32_e32 v174, v175, v179, vcc
	v_pk_fma_f32 v[178:179], v[186:187], s[42:43], v[158:159] op_sel_hi:[1,0,0]
	v_exp_f32_e32 v180, v180
	v_pk_fma_f32 v[178:179], v[186:187], v[178:179], s[52:53] op_sel_hi:[1,1,0]
	v_exp_f32_e32 v181, v181
	v_pk_fma_f32 v[178:179], v[186:187], v[178:179], s[54:55] op_sel_hi:[1,1,0]
	v_cmp_gt_f32_e32 vcc, 0, v176
	v_pk_fma_f32 v[178:179], v[186:187], v[178:179], s[56:57] op_sel_hi:[1,1,0]
	v_pk_mul_f32 v[188:189], v[182:183], v[182:183]
	v_pk_mul_f32 v[178:179], v[186:187], v[178:179]
	v_and_b32_e32 v187, 0x7fffffff, v183
	v_and_b32_e32 v186, 0x7fffffff, v182
	v_pk_fma_f32 v[186:187], v[186:187], s[40:41], 1.0 op_sel_hi:[1,0,0]
	v_pk_mul_f32 v[178:179], v[180:181], v[178:179]
	v_rcp_f32_e32 v186, v186
	v_rcp_f32_e32 v187, v187
	v_pk_mul_f32 v[180:181], v[176:177], v[178:179]
	v_pk_fma_f32 v[178:179], v[176:177], v[178:179], v[176:177] neg_lo:[1,0,0] neg_hi:[1,0,0]
	v_pk_mul_f32 v[188:189], v[188:189], s[58:59] op_sel_hi:[1,0]
	v_cndmask_b32_e32 v175, v178, v180, vcc
	v_cmp_gt_f32_e32 vcc, 0, v177
	v_exp_f32_e32 v188, v188
	v_exp_f32_e32 v189, v189
	v_cndmask_b32_e32 v176, v179, v181, vcc
	v_pk_fma_f32 v[180:181], v[186:187], s[42:43], v[158:159] op_sel_hi:[1,0,0]
	v_pk_mul_f32 v[178:179], v[76:77], v[156:157] op_sel_hi:[1,0]
	v_pk_fma_f32 v[180:181], v[186:187], v[180:181], s[52:53] op_sel_hi:[1,1,0]
	v_and_b32_e32 v191, 0x7fffffff, v179
	v_pk_fma_f32 v[180:181], v[186:187], v[180:181], s[54:55] op_sel_hi:[1,1,0]
	v_and_b32_e32 v190, 0x7fffffff, v178
	v_pk_fma_f32 v[180:181], v[186:187], v[180:181], s[56:57] op_sel_hi:[1,1,0]
	v_pk_fma_f32 v[190:191], v[190:191], s[40:41], 1.0 op_sel_hi:[1,0,0]
	v_pk_mul_f32 v[180:181], v[186:187], v[180:181]
	v_rcp_f32_e32 v190, v190
	v_rcp_f32_e32 v191, v191
	v_pk_mul_f32 v[180:181], v[188:189], v[180:181]
	v_cmp_gt_f32_e32 vcc, 0, v182
	v_pk_mul_f32 v[188:189], v[182:183], v[180:181]
	v_pk_fma_f32 v[180:181], v[182:183], v[180:181], v[182:183] neg_lo:[1,0,0] neg_hi:[1,0,0]
	v_pk_mul_f32 v[186:187], v[178:179], v[178:179]
	v_cndmask_b32_e32 v156, v180, v188, vcc
	v_cmp_gt_f32_e32 vcc, 0, v183
	v_pk_fma_f32 v[158:159], v[190:191], s[42:43], v[158:159] op_sel_hi:[1,0,0]
	s_cselect_b64 s[78:79], -1, 0
	v_cndmask_b32_e32 v177, v181, v189, vcc
	v_pk_mul_f32 v[180:181], v[186:187], s[58:59] op_sel_hi:[1,0]
	v_pk_fma_f32 v[158:159], v[190:191], v[158:159], s[52:53] op_sel_hi:[1,1,0]
	v_exp_f32_e32 v180, v180
	v_exp_f32_e32 v181, v181
	v_pk_fma_f32 v[158:159], v[190:191], v[158:159], s[54:55] op_sel_hi:[1,1,0]
	s_lshl_b32 s10, s26, 2
	v_pk_fma_f32 v[158:159], v[190:191], v[158:159], s[56:57] op_sel_hi:[1,1,0]
	s_add_i32 s76, s10, -16
	v_pk_mul_f32 v[158:159], v[190:191], v[158:159]
	v_cmp_gt_f32_e32 vcc, 0, v178
	v_pk_mul_f32 v[158:159], v[180:181], v[158:159]
	s_ashr_i32 s77, s76, 31
	v_pk_mul_f32 v[180:181], v[178:179], v[158:159]
	v_pk_fma_f32 v[158:159], v[178:179], v[158:159], v[178:179] neg_lo:[1,0,0] neg_hi:[1,0,0]
	s_cmp_lt_i32 s26, 4
	v_cndmask_b32_e32 v158, v158, v180, vcc
	v_cmp_gt_f32_e32 vcc, 0, v179
	v_cvt_pk_bf16_f32 v178, v173, v174
	v_cvt_pk_bf16_f32 v179, v175, v176
	v_cvt_pk_bf16_f32 v180, v156, v177
	s_nop 1
	v_cndmask_b32_e32 v159, v159, v181, vcc
	v_cvt_pk_bf16_f32 v181, v158, v159
	global_store_dwordx4 v[184:185], v[178:181], off offset:256 sc1
	s_cbranch_scc1 .LBB0_936
	v_mul_f32_e32 v166, v166, v166
	v_fmac_f32_e32 v166, v165, v165
	v_mul_f32_e32 v165, v168, v168
	v_fmac_f32_e32 v165, v167, v167
	v_add_f32_e32 v165, v166, v165
	v_mul_f32_e32 v166, v170, v170
	v_mul_f32_e32 v167, v172, v172
	v_fmac_f32_e32 v166, v169, v169
	v_fmac_f32_e32 v167, v171, v171
	v_add_f32_e32 v166, v166, v167
	v_add_f32_e32 v165, v165, v166
	v_mul_f32_e32 v166, v174, v174
	v_mul_f32_e32 v167, v176, v176
	v_fmac_f32_e32 v166, v173, v173
	v_fmac_f32_e32 v167, v175, v175
	v_add_f32_e32 v166, v166, v167
	v_mul_f32_e32 v167, v177, v177
	v_fmac_f32_e32 v167, v156, v156
	v_mul_f32_e32 v156, v159, v159
	v_and_b32_e32 v159, 64, v164
	v_fmac_f32_e32 v156, v158, v158
	v_xor_b32_e32 v158, 16, v164
	v_add_u32_e32 v159, 64, v159
	v_add_f32_e32 v156, v167, v156
	v_cmp_lt_i32_e32 vcc, v158, v159
	v_add_f32_e32 v156, v166, v156
	v_add_f32_e32 v156, v165, v156
	v_cndmask_b32_e32 v158, v164, v158, vcc
	v_lshlrev_b32_e32 v158, 2, v158
	ds_bpermute_b32 v158, v158, v156
	s_waitcnt lgkmcnt(0)
	v_add_f32_e32 v156, v156, v158
	v_xor_b32_e32 v158, 32, v164
	v_cmp_lt_i32_e32 vcc, v158, v159
	s_nop 1
	v_cndmask_b32_e32 v158, v164, v158, vcc
	v_lshlrev_b32_e32 v158, 2, v158
	ds_bpermute_b32 v158, v158, v156
	s_and_saveexec_b64 s[10:11], s[4:5]
	s_cbranch_execz .LBB0_935
	v_lshlrev_b64 v[166:167], 6, v[150:151]
	v_lshl_add_u64 v[166:167], s[18:19], 0, v[166:167]
	v_lshl_add_u64 v[166:167], s[76:77], 2, v[166:167]
	s_lshl_b32 s14, s59, 2
	v_lshl_add_u64 v[166:167], v[166:167], 0, s[14:15]
	s_waitcnt lgkmcnt(0)
	v_add_f32_e32 v151, v156, v158
	global_store_dword v[166:167], v151, off sc1

; __device__ __forceinline__ float dot4(f32x4 v) { return (v[0] * v[0] + v[1] * v[1]) + (v[2] * v[2] + v[3] * v[3]); }
; __device__ __forceinline__ u32x2 pack4(f32x4 v) { u32x2 w; w.x = cvt_pk_bf16(v[0], v[1]); w.y = cvt_pk_bf16(v[2], v[3]); return w; }
; __device__ __forceinline__ f32x2 gelu_pk(f32x2 v) {
;     const f32x2 av = __builtin_elementwise_abs(v), d = av * 0.2316418882f + 1.0f;
;     f32x2 t; t.x = __builtin_amdgcn_rcpf(d.x); t.y = __builtin_amdgcn_rcpf(d.y);
;     f32x2 q = t * 0.5307027145f + (-0.7265760135f); q = q * t + 0.7107068705f; q = q * t + (-0.142248368f); q = q * t + 0.127414796f; q = q * t;
;     const f32x2 s = (v * v) * (-0.72134752044f);
;     f32x2 e; e.x = __builtin_amdgcn_exp2f(s.x); e.y = __builtin_amdgcn_exp2f(s.y);
;     const f32x2 m = v * (q * e), r = v - m;
;     f32x2 o; o.x = v.x < 0.f ? m.x : r.x; o.y = v.y < 0.f ? m.y : r.y; return o;
; }
; __device__ __forceinline__ f32x4 gelu4(f32x4 v) { f32x2 a = gelu_pk((f32x2){v[0], v[1]}), b = gelu_pk((f32x2){v[2], v[3]}); return (f32x4){a.x, a.y, b.x, b.y}; }
; template <int EK>
; __device__ __forceinline__ void epi_tile(const f32x4 (&acc)[2][2][4][2], const Unit& u, int wr, int wc, int fr, int fq, const EpiArgs& E, const LAS float* rt) {
;     ...
;             } else if (EK == EK_GELU) {
;                 const float r = rr[ai][m]; float ss = 0.f;
; #pragma unroll
;                 for (int bj = 0; bj < 2; ++bj) { const int col = u.pn * BM + bj * HALF + wc * 32 + fq * 8;
;                     const f32x4 z0 = gelu4(acc[ai][bj][m][0] * r), z1 = gelu4(acc[ai][bj][m][1] * r); ss += dot4(z0) + dot4(z1);
;                     const u32x2 lo = pack4(z0), hi = pack4(z1);
;                     *(u32x4*)(E.ob + (size_t)row * E.ldb + col) = (u32x4){lo.x, lo.y, hi.x, hi.y}; }
.LBB0_936:
	v_mov_b32_e32 v176, v157
	v_pk_mul_f32 v[166:167], v[102:103], v[176:177] op_sel_hi:[1,0]
	v_pk_mul_f32 v[170:171], v[104:105], v[176:177] op_sel_hi:[1,0]
	v_and_b32_e32 v159, 0x7fffffff, v167
	s_waitcnt lgkmcnt(0)
	v_and_b32_e32 v158, 0x7fffffff, v166
	v_pk_fma_f32 v[158:159], v[158:159], s[40:41], 1.0 op_sel_hi:[1,0,0]
	v_pk_mul_f32 v[174:175], v[166:167], v[166:167]
	v_rcp_f32_e32 v168, v158
	v_rcp_f32_e32 v169, v159
	v_mov_b64_e32 v[158:159], s[44:45]
	v_pk_mul_f32 v[174:175], v[174:175], s[58:59] op_sel_hi:[1,0]
	v_and_b32_e32 v179, 0x7fffffff, v171
	v_pk_fma_f32 v[172:173], v[168:169], s[42:43], v[158:159] op_sel_hi:[1,0,0]
	v_exp_f32_e32 v174, v174
	v_pk_fma_f32 v[172:173], v[168:169], v[172:173], s[52:53] op_sel_hi:[1,1,0]
	v_exp_f32_e32 v175, v175
	v_pk_fma_f32 v[172:173], v[168:169], v[172:173], s[54:55] op_sel_hi:[1,1,0]
	v_and_b32_e32 v178, 0x7fffffff, v170
	v_pk_fma_f32 v[172:173], v[168:169], v[172:173], s[56:57] op_sel_hi:[1,1,0]
	v_pk_fma_f32 v[178:179], v[178:179], s[40:41], 1.0 op_sel_hi:[1,0,0]
	v_pk_mul_f32 v[168:169], v[168:169], v[172:173]
	v_rcp_f32_e32 v178, v178
	v_rcp_f32_e32 v179, v179
	v_pk_mul_f32 v[168:169], v[174:175], v[168:169]
	v_cmp_gt_f32_e32 vcc, 0, v166
	v_pk_mul_f32 v[174:175], v[166:167], v[168:169]
	v_pk_fma_f32 v[168:169], v[166:167], v[168:169], v[166:167] neg_lo:[1,0,0] neg_hi:[1,0,0]
	v_pk_mul_f32 v[172:173], v[170:171], v[170:171]
	v_cndmask_b32_e32 v151, v168, v174, vcc
	v_cmp_gt_f32_e32 vcc, 0, v167
	v_pk_fma_f32 v[166:167], v[178:179], s[42:43], v[158:159] op_sel_hi:[1,0,0]
	v_or_b32_e32 v156, 16, v150
	v_cndmask_b32_e32 v165, v169, v175, vcc
	v_pk_mul_f32 v[168:169], v[172:173], s[58:59] op_sel_hi:[1,0]
	v_pk_fma_f32 v[166:167], v[178:179], v[166:167], s[52:53] op_sel_hi:[1,1,0]
	v_exp_f32_e32 v168, v168
	v_exp_f32_e32 v169, v169
	v_pk_mul_f32 v[172:173], v[98:99], v[176:177] op_sel_hi:[1,0]
	v_pk_fma_f32 v[166:167], v[178:179], v[166:167], s[54:55] op_sel_hi:[1,1,0]
	v_and_b32_e32 v175, 0x7fffffff, v173
	v_and_b32_e32 v174, 0x7fffffff, v172
	v_pk_fma_f32 v[166:167], v[178:179], v[166:167], s[56:57] op_sel_hi:[1,1,0]
	v_pk_fma_f32 v[174:175], v[174:175], s[40:41], 1.0 op_sel_hi:[1,0,0]
	v_pk_mul_f32 v[166:167], v[178:179], v[166:167]
	v_rcp_f32_e32 v174, v174
	v_rcp_f32_e32 v175, v175
	v_pk_mul_f32 v[166:167], v[168:169], v[166:167]
	v_cmp_gt_f32_e32 vcc, 0, v170
	v_pk_mul_f32 v[168:169], v[170:171], v[166:167]
	v_pk_fma_f32 v[166:167], v[170:171], v[166:167], v[170:171] neg_lo:[1,0,0] neg_hi:[1,0,0]
	v_pk_mul_f32 v[178:179], v[172:173], v[172:173]
	v_cndmask_b32_e32 v166, v166, v168, vcc
	v_cmp_gt_f32_e32 vcc, 0, v171
	v_pk_mul_f32 v[170:171], v[100:101], v[176:177] op_sel_hi:[1,0]
	v_pk_mul_f32 v[178:179], v[178:179], s[58:59] op_sel_hi:[1,0]
	v_cndmask_b32_e32 v167, v167, v169, vcc
	v_pk_fma_f32 v[168:169], v[174:175], s[42:43], v[158:159] op_sel_hi:[1,0,0]
	v_exp_f32_e32 v178, v178
	v_pk_fma_f32 v[168:169], v[174:175], v[168:169], s[52:53] op_sel_hi:[1,1,0]
	v_exp_f32_e32 v179, v179
	v_and_b32_e32 v181, 0x7fffffff, v171
	v_and_b32_e32 v180, 0x7fffffff, v170
	v_pk_fma_f32 v[168:169], v[174:175], v[168:169], s[54:55] op_sel_hi:[1,1,0]
	v_pk_fma_f32 v[180:181], v[180:181], s[40:41], 1.0 op_sel_hi:[1,0,0]
	v_pk_fma_f32 v[168:169], v[174:175], v[168:169], s[56:57] op_sel_hi:[1,1,0]
	v_rcp_f32_e32 v180, v180
	v_rcp_f32_e32 v181, v181
	v_pk_mul_f32 v[168:169], v[174:175], v[168:169]
	v_cmp_gt_f32_e32 vcc, 0, v172
	v_pk_mul_f32 v[168:169], v[178:179], v[168:169]
	v_pk_mul_f32 v[174:175], v[170:171], v[170:171]
	v_pk_mul_f32 v[178:179], v[172:173], v[168:169]
	v_pk_fma_f32 v[168:169], v[172:173], v[168:169], v[172:173] neg_lo:[1,0,0] neg_hi:[1,0,0]
	v_pk_mul_f32 v[174:175], v[174:175], s[58:59] op_sel_hi:[1,0]
	v_cndmask_b32_e32 v168, v168, v178, vcc
	v_cmp_gt_f32_e32 vcc, 0, v173
	v_pk_fma_f32 v[172:173], v[180:181], s[42:43], v[158:159] op_sel_hi:[1,0,0]
	v_exp_f32_e32 v174, v174
	v_pk_fma_f32 v[172:173], v[180:181], v[172:173], s[52:53] op_sel_hi:[1,1,0]
	v_exp_f32_e32 v175, v175
	v_pk_fma_f32 v[172:173], v[180:181], v[172:173], s[54:55] op_sel_hi:[1,1,0]
	v_ashrrev_i32_e32 v157, 31, v156
	v_pk_fma_f32 v[172:173], v[180:181], v[172:173], s[56:57] op_sel_hi:[1,1,0]
	v_cndmask_b32_e32 v169, v169, v179, vcc
	v_pk_mul_f32 v[172:173], v[180:181], v[172:173]
	v_pk_mul_f32 v[180:181], v[70:71], v[176:177] op_sel_hi:[1,0]
	v_pk_mul_f32 v[172:173], v[174:175], v[172:173]
	v_and_b32_e32 v183, 0x7fffffff, v181
	v_and_b32_e32 v182, 0x7fffffff, v180
	v_pk_fma_f32 v[182:183], v[182:183], s[40:41], 1.0 op_sel_hi:[1,0,0]
	v_pk_mul_f32 v[174:175], v[170:171], v[172:173]
	v_rcp_f32_e32 v182, v182
	v_rcp_f32_e32 v183, v183
	v_pk_fma_f32 v[172:173], v[170:171], v[172:173], v[170:171] neg_lo:[1,0,0] neg_hi:[1,0,0]
	v_cmp_gt_f32_e32 vcc, 0, v170
	v_lshlrev_b64 v[178:179], 12, v[156:157]
	v_lshl_add_u64 v[178:179], s[64:65], 0, v[178:179]
	v_cndmask_b32_e32 v170, v172, v174, vcc
	v_cmp_gt_f32_e32 vcc, 0, v171
	v_cvt_pk_bf16_f32 v172, v151, v165
	v_lshl_add_u64 v[184:185], v[146:147], 1, v[178:179]
	v_pk_mul_f32 v[178:179], v[180:181], v[180:181]
	v_cndmask_b32_e32 v171, v173, v175, vcc
	v_cvt_pk_bf16_f32 v173, v166, v167
	v_cvt_pk_bf16_f32 v174, v168, v169
	v_cvt_pk_bf16_f32 v175, v170, v171
	global_store_dwordx4 v[184:185], v[172:175], off sc1
	v_pk_mul_f32 v[178:179], v[178:179], s[58:59] op_sel_hi:[1,0]
	v_cmp_gt_f32_e32 vcc, 0, v180
	v_pk_fma_f32 v[172:173], v[182:183], s[42:43], v[158:159] op_sel_hi:[1,0,0]
	v_pk_mul_f32 v[174:175], v[72:73], v[176:177] op_sel_hi:[1,0]
	v_pk_fma_f32 v[172:173], v[182:183], v[172:173], s[52:53] op_sel_hi:[1,1,0]
	v_exp_f32_e32 v178, v178
	v_exp_f32_e32 v179, v179
; __device__ __forceinline__ float dot4(f32x4 v) { return (v[0] * v[0] + v[1] * v[1]) + (v[2] * v[2] + v[3] * v[3]); }
; __device__ __forceinline__ u32x2 pack4(f32x4 v) { u32x2 w; w.x = cvt_pk_bf16(v[0], v[1]); w.y = cvt_pk_bf16(v[2], v[3]); return w; }
; __device__ __forceinline__ float quad_sum(float s) { s += __shfl_xor(s, 16); s += __shfl_xor(s, 32); return s; }
; __device__ __forceinline__ f32x4 gelu4(f32x4 v) { f32x2 a = gelu_pk((f32x2){v[0], v[1]}), b = gelu_pk((f32x2){v[2], v[3]}); return (f32x4){a.x, a.y, b.x, b.y}; }
; template <int EK>
; __device__ __forceinline__ void epi_tile(const f32x4 (&acc)[2][2][4][2], const Unit& u, int wr, int wc, int fr, int fq, const EpiArgs& E, const LAS float* rt) {
;     ...
;             } else if (EK == EK_GELU) {
;                 const float r = rr[ai][m]; float ss = 0.f;
; #pragma unroll
;                 for (int bj = 0; bj < 2; ++bj) { const int col = u.pn * BM + bj * HALF + wc * 32 + fq * 8;
;                     const f32x4 z0 = gelu4(acc[ai][bj][m][0] * r), z1 = gelu4(acc[ai][bj][m][1] * r); ss += dot4(z0) + dot4(z1);
;                     const u32x2 lo = pack4(z0), hi = pack4(z1);
;                     *(u32x4*)(E.ob + (size_t)row * E.ldb + col) = (u32x4){lo.x, lo.y, hi.x, hi.y}; }
;                 if (u.pn >= 4) { ss = quad_sum(ss); if (fq == 0) E.stOut[(size_t)row * 16 + (u.pn - 4) * 4 + wc] = ss; }
	v_pk_fma_f32 v[172:173], v[182:183], v[172:173], s[54:55] op_sel_hi:[1,1,0]
	v_and_b32_e32 v187, 0x7fffffff, v175
	v_and_b32_e32 v186, 0x7fffffff, v174
	v_pk_fma_f32 v[172:173], v[182:183], v[172:173], s[56:57] op_sel_hi:[1,1,0]
	v_pk_fma_f32 v[186:187], v[186:187], s[40:41], 1.0 op_sel_hi:[1,0,0]
	v_pk_mul_f32 v[172:173], v[182:183], v[172:173]
	v_rcp_f32_e32 v186, v186
	v_rcp_f32_e32 v187, v187
	v_pk_mul_f32 v[172:173], v[178:179], v[172:173]
	v_pk_mul_f32 v[182:183], v[174:175], v[174:175]
	v_pk_mul_f32 v[178:179], v[180:181], v[172:173]
	v_pk_fma_f32 v[172:173], v[180:181], v[172:173], v[180:181] neg_lo:[1,0,0] neg_hi:[1,0,0]
	s_nop 0
	v_cndmask_b32_e32 v172, v172, v178, vcc
	v_cmp_gt_f32_e32 vcc, 0, v181
	v_pk_mul_f32 v[180:181], v[182:183], s[58:59] op_sel_hi:[1,0]
	v_pk_mul_f32 v[182:183], v[66:67], v[176:177] op_sel_hi:[1,0]
	v_cndmask_b32_e32 v173, v173, v179, vcc
	v_pk_fma_f32 v[178:179], v[186:187], s[42:43], v[158:159] op_sel_hi:[1,0,0]
	v_exp_f32_e32 v180, v180
	v_pk_fma_f32 v[178:179], v[186:187], v[178:179], s[52:53] op_sel_hi:[1,1,0]
	v_exp_f32_e32 v181, v181
	v_pk_fma_f32 v[178:179], v[186:187], v[178:179], s[54:55] op_sel_hi:[1,1,0]
	v_cmp_gt_f32_e32 vcc, 0, v174
	v_pk_fma_f32 v[178:179], v[186:187], v[178:179], s[56:57] op_sel_hi:[1,1,0]
	s_nop 0
	v_pk_mul_f32 v[178:179], v[186:187], v[178:179]
	v_and_b32_e32 v187, 0x7fffffff, v183
	v_and_b32_e32 v186, 0x7fffffff, v182
	v_pk_fma_f32 v[186:187], v[186:187], s[40:41], 1.0 op_sel_hi:[1,0,0]
	v_pk_mul_f32 v[178:179], v[180:181], v[178:179]
	v_rcp_f32_e32 v186, v186
	v_rcp_f32_e32 v187, v187
	v_pk_mul_f32 v[180:181], v[174:175], v[178:179]
	v_pk_fma_f32 v[178:179], v[174:175], v[178:179], v[174:175] neg_lo:[1,0,0] neg_hi:[1,0,0]
	s_nop 0
	v_cndmask_b32_e32 v174, v178, v180, vcc
	v_cmp_gt_f32_e32 vcc, 0, v175
	s_nop 1
	v_cndmask_b32_e32 v175, v179, v181, vcc
	v_pk_mul_f32 v[180:181], v[182:183], v[182:183]
	v_pk_mul_f32 v[178:179], v[68:69], v[176:177] op_sel_hi:[1,0]
	v_pk_fma_f32 v[176:177], v[186:187], s[42:43], v[158:159] op_sel_hi:[1,0,0]
	v_pk_mul_f32 v[180:181], v[180:181], s[58:59] op_sel_hi:[1,0]
	v_pk_fma_f32 v[176:177], v[186:187], v[176:177], s[52:53] op_sel_hi:[1,1,0]
	v_exp_f32_e32 v180, v180
	v_exp_f32_e32 v181, v181
	v_pk_fma_f32 v[176:177], v[186:187], v[176:177], s[54:55] op_sel_hi:[1,1,0]
	v_and_b32_e32 v189, 0x7fffffff, v179
	v_and_b32_e32 v188, 0x7fffffff, v178
	v_pk_fma_f32 v[176:177], v[186:187], v[176:177], s[56:57] op_sel_hi:[1,1,0]
	v_pk_fma_f32 v[188:189], v[188:189], s[40:41], 1.0 op_sel_hi:[1,0,0]
	v_pk_mul_f32 v[176:177], v[186:187], v[176:177]
	v_rcp_f32_e32 v188, v188
	v_rcp_f32_e32 v189, v189
	v_pk_mul_f32 v[176:177], v[180:181], v[176:177]
	v_cmp_gt_f32_e32 vcc, 0, v182
	v_pk_mul_f32 v[180:181], v[182:183], v[176:177]
	v_pk_fma_f32 v[176:177], v[182:183], v[176:177], v[182:183] neg_lo:[1,0,0] neg_hi:[1,0,0]
	v_pk_mul_f32 v[186:187], v[178:179], v[178:179]
	v_cndmask_b32_e32 v176, v176, v180, vcc
	v_cmp_gt_f32_e32 vcc, 0, v183
	v_pk_fma_f32 v[158:159], v[188:189], s[42:43], v[158:159] op_sel_hi:[1,0,0]
	v_cndmask_b32_e64 v182, 0, 1, s[78:79]
	v_cndmask_b32_e32 v177, v177, v181, vcc
	v_pk_mul_f32 v[180:181], v[186:187], s[58:59] op_sel_hi:[1,0]
	v_pk_fma_f32 v[158:159], v[188:189], v[158:159], s[52:53] op_sel_hi:[1,1,0]
	v_exp_f32_e32 v180, v180
	v_exp_f32_e32 v181, v181
	v_pk_fma_f32 v[158:159], v[188:189], v[158:159], s[54:55] op_sel_hi:[1,1,0]
	v_cmp_gt_f32_e32 vcc, 0, v178
	v_pk_fma_f32 v[158:159], v[188:189], v[158:159], s[56:57] op_sel_hi:[1,1,0]
	v_cmp_ne_u32_e64 s[10:11], 1, v182
	v_pk_mul_f32 v[158:159], v[188:189], v[158:159]
	s_nop 0
	v_pk_mul_f32 v[158:159], v[180:181], v[158:159]
	s_nop 0
	v_pk_mul_f32 v[180:181], v[178:179], v[158:159]
	v_pk_fma_f32 v[158:159], v[178:179], v[158:159], v[178:179] neg_lo:[1,0,0] neg_hi:[1,0,0]
	v_cvt_pk_bf16_f32 v178, v172, v173
	s_nop 0
	v_cndmask_b32_e32 v158, v158, v180, vcc
	v_cmp_gt_f32_e32 vcc, 0, v179
	v_cvt_pk_bf16_f32 v179, v174, v175
	v_cvt_pk_bf16_f32 v180, v176, v177
	s_nop 1
	v_cndmask_b32_e32 v159, v159, v181, vcc
	s_andn2_b64 vcc, exec, s[78:79]
	v_cvt_pk_bf16_f32 v181, v158, v159
	global_store_dwordx4 v[184:185], v[178:181], off offset:256 sc1
	s_cbranch_vccnz .LBB0_940
	v_mul_f32_e32 v165, v165, v165
	v_fmac_f32_e32 v165, v151, v151
	v_mul_f32_e32 v151, v167, v167
	v_fmac_f32_e32 v151, v166, v166
	v_add_f32_e32 v151, v165, v151
	v_mul_f32_e32 v165, v169, v169
	v_mul_f32_e32 v166, v171, v171
	v_fmac_f32_e32 v165, v168, v168
	v_fmac_f32_e32 v166, v170, v170
	v_add_f32_e32 v165, v165, v166
	v_add_f32_e32 v151, v151, v165
	v_mul_f32_e32 v165, v173, v173
	v_mul_f32_e32 v166, v175, v175
	v_fmac_f32_e32 v165, v172, v172
	v_fmac_f32_e32 v166, v174, v174
	v_add_f32_e32 v165, v165, v166
	v_mul_f32_e32 v166, v177, v177
	v_mul_f32_e32 v159, v159, v159
	v_fmac_f32_e32 v166, v176, v176
	v_fmac_f32_e32 v159, v158, v158
	v_add_f32_e32 v158, v166, v159
	v_add_f32_e32 v158, v165, v158
	v_and_b32_e32 v159, 64, v164
	v_add_f32_e32 v151, v151, v158
	v_xor_b32_e32 v158, 16, v164
	v_add_u32_e32 v159, 64, v159
	v_cmp_lt_i32_e32 vcc, v158, v159
	s_nop 1
	v_cndmask_b32_e32 v158, v164, v158, vcc
	v_lshlrev_b32_e32 v158, 2, v158
	ds_bpermute_b32 v158, v158, v151
	s_waitcnt lgkmcnt(0)
	v_add_f32_e32 v151, v151, v158
	v_xor_b32_e32 v158, 32, v164
	v_cmp_lt_i32_e32 vcc, v158, v159
	s_nop 1
	v_cndmask_b32_e32 v158, v164, v158, vcc
	v_lshlrev_b32_e32 v158, 2, v158
	ds_bpermute_b32 v158, v158, v151
	s_and_saveexec_b64 s[78:79], s[4:5]
	s_cbranch_execz .LBB0_939
	v_lshlrev_b64 v[156:157], 6, v[156:157]
	v_lshl_add_u64 v[156:157], s[18:19], 0, v[156:157]
	v_lshl_add_u64 v[156:157], s[76:77], 2, v[156:157]
	s_lshl_b32 s14, s59, 2
	v_lshl_add_u64 v[156:157], v[156:157], 0, s[14:15]
	s_waitcnt lgkmcnt(0)
	v_add_f32_e32 v151, v151, v158
	global_store_dword v[156:157], v151, off sc1

; __device__ __forceinline__ float dot4(f32x4 v) { return (v[0] * v[0] + v[1] * v[1]) + (v[2] * v[2] + v[3] * v[3]); }
; __device__ __forceinline__ u32x2 pack4(f32x4 v) { u32x2 w; w.x = cvt_pk_bf16(v[0], v[1]); w.y = cvt_pk_bf16(v[2], v[3]); return w; }
; __device__ __forceinline__ f32x2 gelu_pk(f32x2 v) {
;     const f32x2 av = __builtin_elementwise_abs(v), d = av * 0.2316418882f + 1.0f;
;     f32x2 t; t.x = __builtin_amdgcn_rcpf(d.x); t.y = __builtin_amdgcn_rcpf(d.y);
;     f32x2 q = t * 0.5307027145f + (-0.7265760135f); q = q * t + 0.7107068705f; q = q * t + (-0.142248368f); q = q * t + 0.127414796f; q = q * t;
;     const f32x2 s = (v * v) * (-0.72134752044f);
;     f32x2 e; e.x = __builtin_amdgcn_exp2f(s.x); e.y = __builtin_amdgcn_exp2f(s.y);
;     const f32x2 m = v * (q * e), r = v - m;
;     f32x2 o; o.x = v.x < 0.f ? m.x : r.x; o.y = v.y < 0.f ? m.y : r.y; return o;
; }
; __device__ __forceinline__ f32x4 gelu4(f32x4 v) { f32x2 a = gelu_pk((f32x2){v[0], v[1]}), b = gelu_pk((f32x2){v[2], v[3]}); return (f32x4){a.x, a.y, b.x, b.y}; }
; template <int EK>
; __device__ __forceinline__ void epi_tile(const f32x4 (&acc)[2][2][4][2], const Unit& u, int wr, int wc, int fr, int fq, const EpiArgs& E, const LAS float* rt) {
;     ...
;             } else if (EK == EK_GELU) {
;                 const float r = rr[ai][m]; float ss = 0.f;
; #pragma unroll
;                 for (int bj = 0; bj < 2; ++bj) { const int col = u.pn * BM + bj * HALF + wc * 32 + fq * 8;
;                     const f32x4 z0 = gelu4(acc[ai][bj][m][0] * r), z1 = gelu4(acc[ai][bj][m][1] * r); ss += dot4(z0) + dot4(z1);
;                     const u32x2 lo = pack4(z0), hi = pack4(z1);
;                     *(u32x4*)(E.ob + (size_t)row * E.ldb + col) = (u32x4){lo.x, lo.y, hi.x, hi.y}; }
.LBB0_940:
	v_pk_mul_f32 v[166:167], v[94:95], v[154:155] op_sel_hi:[1,0]
	v_pk_mul_f32 v[170:171], v[96:97], v[154:155] op_sel_hi:[1,0]
	v_and_b32_e32 v159, 0x7fffffff, v167
	s_waitcnt lgkmcnt(0)
	v_and_b32_e32 v158, 0x7fffffff, v166
	v_pk_fma_f32 v[158:159], v[158:159], s[40:41], 1.0 op_sel_hi:[1,0,0]
	v_pk_mul_f32 v[174:175], v[166:167], v[166:167]
	v_rcp_f32_e32 v168, v158
	v_rcp_f32_e32 v169, v159
	v_mov_b64_e32 v[158:159], s[44:45]
	v_pk_mul_f32 v[174:175], v[174:175], s[58:59] op_sel_hi:[1,0]
	v_and_b32_e32 v177, 0x7fffffff, v171
	v_pk_fma_f32 v[172:173], v[168:169], s[42:43], v[158:159] op_sel_hi:[1,0,0]
	v_exp_f32_e32 v174, v174
	v_pk_fma_f32 v[172:173], v[168:169], v[172:173], s[52:53] op_sel_hi:[1,1,0]
	v_exp_f32_e32 v175, v175
	v_pk_fma_f32 v[172:173], v[168:169], v[172:173], s[54:55] op_sel_hi:[1,1,0]
	v_and_b32_e32 v176, 0x7fffffff, v170
	v_pk_fma_f32 v[172:173], v[168:169], v[172:173], s[56:57] op_sel_hi:[1,1,0]
	v_pk_fma_f32 v[176:177], v[176:177], s[40:41], 1.0 op_sel_hi:[1,0,0]
	v_pk_mul_f32 v[168:169], v[168:169], v[172:173]
	v_rcp_f32_e32 v176, v176
	v_rcp_f32_e32 v177, v177
	v_pk_mul_f32 v[168:169], v[174:175], v[168:169]
	v_cmp_gt_f32_e32 vcc, 0, v166
	v_pk_mul_f32 v[174:175], v[166:167], v[168:169]
	v_pk_fma_f32 v[168:169], v[166:167], v[168:169], v[166:167] neg_lo:[1,0,0] neg_hi:[1,0,0]
	v_pk_mul_f32 v[172:173], v[170:171], v[170:171]
	v_cndmask_b32_e32 v151, v168, v174, vcc
	v_cmp_gt_f32_e32 vcc, 0, v167
	v_pk_fma_f32 v[166:167], v[176:177], s[42:43], v[158:159] op_sel_hi:[1,0,0]
	v_or_b32_e32 v156, 32, v150
	v_cndmask_b32_e32 v165, v169, v175, vcc
	v_pk_mul_f32 v[168:169], v[172:173], s[58:59] op_sel_hi:[1,0]
	v_pk_fma_f32 v[166:167], v[176:177], v[166:167], s[52:53] op_sel_hi:[1,1,0]
	v_exp_f32_e32 v168, v168
	v_exp_f32_e32 v169, v169
	v_pk_mul_f32 v[172:173], v[90:91], v[154:155] op_sel_hi:[1,0]
	v_pk_fma_f32 v[166:167], v[176:177], v[166:167], s[54:55] op_sel_hi:[1,1,0]
	v_and_b32_e32 v175, 0x7fffffff, v173
	v_and_b32_e32 v174, 0x7fffffff, v172
	v_pk_fma_f32 v[166:167], v[176:177], v[166:167], s[56:57] op_sel_hi:[1,1,0]
	v_pk_fma_f32 v[174:175], v[174:175], s[40:41], 1.0 op_sel_hi:[1,0,0]
	v_pk_mul_f32 v[166:167], v[176:177], v[166:167]
	v_rcp_f32_e32 v174, v174
	v_rcp_f32_e32 v175, v175
	v_pk_mul_f32 v[166:167], v[168:169], v[166:167]
	v_cmp_gt_f32_e32 vcc, 0, v170
	v_pk_mul_f32 v[168:169], v[170:171], v[166:167]
	v_pk_fma_f32 v[166:167], v[170:171], v[166:167], v[170:171] neg_lo:[1,0,0] neg_hi:[1,0,0]
	v_pk_mul_f32 v[176:177], v[172:173], v[172:173]
	v_cndmask_b32_e32 v166, v166, v168, vcc
	v_cmp_gt_f32_e32 vcc, 0, v171
	v_pk_mul_f32 v[170:171], v[92:93], v[154:155] op_sel_hi:[1,0]
	v_pk_mul_f32 v[176:177], v[176:177], s[58:59] op_sel_hi:[1,0]
	v_cndmask_b32_e32 v167, v167, v169, vcc
	v_pk_fma_f32 v[168:169], v[174:175], s[42:43], v[158:159] op_sel_hi:[1,0,0]
	v_exp_f32_e32 v176, v176
	v_pk_fma_f32 v[168:169], v[174:175], v[168:169], s[52:53] op_sel_hi:[1,1,0]
	v_exp_f32_e32 v177, v177
	v_and_b32_e32 v179, 0x7fffffff, v171
	v_and_b32_e32 v178, 0x7fffffff, v170
	v_pk_fma_f32 v[168:169], v[174:175], v[168:169], s[54:55] op_sel_hi:[1,1,0]
	v_pk_fma_f32 v[178:179], v[178:179], s[40:41], 1.0 op_sel_hi:[1,0,0]
	v_pk_fma_f32 v[168:169], v[174:175], v[168:169], s[56:57] op_sel_hi:[1,1,0]
	v_rcp_f32_e32 v178, v178
	v_rcp_f32_e32 v179, v179
	v_pk_mul_f32 v[168:169], v[174:175], v[168:169]
	v_cmp_gt_f32_e32 vcc, 0, v172
	v_pk_mul_f32 v[168:169], v[176:177], v[168:169]
	v_pk_mul_f32 v[174:175], v[170:171], v[170:171]
	v_pk_mul_f32 v[176:177], v[172:173], v[168:169]
	v_pk_fma_f32 v[168:169], v[172:173], v[168:169], v[172:173] neg_lo:[1,0,0] neg_hi:[1,0,0]
	v_pk_mul_f32 v[174:175], v[174:175], s[58:59] op_sel_hi:[1,0]
	v_cndmask_b32_e32 v168, v168, v176, vcc
	v_cmp_gt_f32_e32 vcc, 0, v173
	v_pk_fma_f32 v[172:173], v[178:179], s[42:43], v[158:159] op_sel_hi:[1,0,0]
	v_exp_f32_e32 v174, v174
	v_pk_fma_f32 v[172:173], v[178:179], v[172:173], s[52:53] op_sel_hi:[1,1,0]
	v_exp_f32_e32 v175, v175
	v_pk_fma_f32 v[172:173], v[178:179], v[172:173], s[54:55] op_sel_hi:[1,1,0]
	v_ashrrev_i32_e32 v157, 31, v156
	v_pk_fma_f32 v[172:173], v[178:179], v[172:173], s[56:57] op_sel_hi:[1,1,0]
	v_cndmask_b32_e32 v169, v169, v177, vcc
	v_pk_mul_f32 v[172:173], v[178:179], v[172:173]
	v_pk_mul_f32 v[178:179], v[62:63], v[154:155] op_sel_hi:[1,0]
	v_pk_mul_f32 v[172:173], v[174:175], v[172:173]
	v_and_b32_e32 v181, 0x7fffffff, v179
	v_and_b32_e32 v180, 0x7fffffff, v178
	v_pk_fma_f32 v[180:181], v[180:181], s[40:41], 1.0 op_sel_hi:[1,0,0]
	v_pk_mul_f32 v[174:175], v[170:171], v[172:173]
	v_rcp_f32_e32 v180, v180
	v_rcp_f32_e32 v181, v181
	v_pk_fma_f32 v[172:173], v[170:171], v[172:173], v[170:171] neg_lo:[1,0,0] neg_hi:[1,0,0]
	v_cmp_gt_f32_e32 vcc, 0, v170
	v_lshlrev_b64 v[176:177], 12, v[156:157]
	v_lshl_add_u64 v[176:177], s[64:65], 0, v[176:177]
	v_cndmask_b32_e32 v170, v172, v174, vcc
	v_cmp_gt_f32_e32 vcc, 0, v171
	v_cvt_pk_bf16_f32 v172, v151, v165
	v_lshl_add_u64 v[182:183], v[146:147], 1, v[176:177]
	v_pk_mul_f32 v[176:177], v[178:179], v[178:179]
	v_cndmask_b32_e32 v171, v173, v175, vcc
	v_cvt_pk_bf16_f32 v173, v166, v167
	v_cvt_pk_bf16_f32 v174, v168, v169
	v_cvt_pk_bf16_f32 v175, v170, v171
	global_store_dwordx4 v[182:183], v[172:175], off sc1
	v_pk_mul_f32 v[176:177], v[176:177], s[58:59] op_sel_hi:[1,0]
	v_cmp_gt_f32_e32 vcc, 0, v178
	v_pk_fma_f32 v[172:173], v[180:181], s[42:43], v[158:159] op_sel_hi:[1,0,0]
	v_pk_mul_f32 v[174:175], v[64:65], v[154:155] op_sel_hi:[1,0]
	v_pk_fma_f32 v[172:173], v[180:181], v[172:173], s[52:53] op_sel_hi:[1,1,0]
	v_exp_f32_e32 v176, v176
	v_exp_f32_e32 v177, v177
; __device__ __forceinline__ float dot4(f32x4 v) { return (v[0] * v[0] + v[1] * v[1]) + (v[2] * v[2] + v[3] * v[3]); }
; __device__ __forceinline__ u32x2 pack4(f32x4 v) { u32x2 w; w.x = cvt_pk_bf16(v[0], v[1]); w.y = cvt_pk_bf16(v[2], v[3]); return w; }
; __device__ __forceinline__ float quad_sum(float s) { s += __shfl_xor(s, 16); s += __shfl_xor(s, 32); return s; }
; __device__ __forceinline__ f32x4 gelu4(f32x4 v) { f32x2 a = gelu_pk((f32x2){v[0], v[1]}), b = gelu_pk((f32x2){v[2], v[3]}); return (f32x4){a.x, a.y, b.x, b.y}; }
; template <int EK>
; __device__ __forceinline__ void epi_tile(const f32x4 (&acc)[2][2][4][2], const Unit& u, int wr, int wc, int fr, int fq, const EpiArgs& E, const LAS float* rt) {
;     ...
;             } else if (EK == EK_GELU) {
;                 const float r = rr[ai][m]; float ss = 0.f;
; #pragma unroll
;                 for (int bj = 0; bj < 2; ++bj) { const int col = u.pn * BM + bj * HALF + wc * 32 + fq * 8;
;                     const f32x4 z0 = gelu4(acc[ai][bj][m][0] * r), z1 = gelu4(acc[ai][bj][m][1] * r); ss += dot4(z0) + dot4(z1);
;                     const u32x2 lo = pack4(z0), hi = pack4(z1);
;                     *(u32x4*)(E.ob + (size_t)row * E.ldb + col) = (u32x4){lo.x, lo.y, hi.x, hi.y}; }
;                 if (u.pn >= 4) { ss = quad_sum(ss); if (fq == 0) E.stOut[(size_t)row * 16 + (u.pn - 4) * 4 + wc] = ss; }
	v_pk_fma_f32 v[172:173], v[180:181], v[172:173], s[54:55] op_sel_hi:[1,1,0]
	v_and_b32_e32 v185, 0x7fffffff, v175
	v_and_b32_e32 v184, 0x7fffffff, v174
	v_pk_fma_f32 v[172:173], v[180:181], v[172:173], s[56:57] op_sel_hi:[1,1,0]
	v_pk_fma_f32 v[184:185], v[184:185], s[40:41], 1.0 op_sel_hi:[1,0,0]
	v_pk_mul_f32 v[172:173], v[180:181], v[172:173]
	v_rcp_f32_e32 v184, v184
	v_rcp_f32_e32 v185, v185
	v_pk_mul_f32 v[172:173], v[176:177], v[172:173]
	v_pk_mul_f32 v[180:181], v[174:175], v[174:175]
	v_pk_mul_f32 v[176:177], v[178:179], v[172:173]
	v_pk_fma_f32 v[172:173], v[178:179], v[172:173], v[178:179] neg_lo:[1,0,0] neg_hi:[1,0,0]
	s_nop 0
	v_cndmask_b32_e32 v172, v172, v176, vcc
	v_cmp_gt_f32_e32 vcc, 0, v179
	v_pk_mul_f32 v[178:179], v[180:181], s[58:59] op_sel_hi:[1,0]
	v_pk_mul_f32 v[180:181], v[58:59], v[154:155] op_sel_hi:[1,0]
	v_cndmask_b32_e32 v173, v173, v177, vcc
	v_pk_fma_f32 v[176:177], v[184:185], s[42:43], v[158:159] op_sel_hi:[1,0,0]
	v_exp_f32_e32 v178, v178
	v_pk_fma_f32 v[176:177], v[184:185], v[176:177], s[52:53] op_sel_hi:[1,1,0]
	v_exp_f32_e32 v179, v179
	v_pk_fma_f32 v[176:177], v[184:185], v[176:177], s[54:55] op_sel_hi:[1,1,0]
	v_cmp_gt_f32_e32 vcc, 0, v174
	v_pk_fma_f32 v[176:177], v[184:185], v[176:177], s[56:57] op_sel_hi:[1,1,0]
	v_pk_mul_f32 v[186:187], v[180:181], v[180:181]
	v_pk_mul_f32 v[176:177], v[184:185], v[176:177]
	v_and_b32_e32 v185, 0x7fffffff, v181
	v_and_b32_e32 v184, 0x7fffffff, v180
	v_pk_fma_f32 v[184:185], v[184:185], s[40:41], 1.0 op_sel_hi:[1,0,0]
	v_pk_mul_f32 v[176:177], v[178:179], v[176:177]
	v_rcp_f32_e32 v184, v184
	v_rcp_f32_e32 v185, v185
	v_pk_mul_f32 v[178:179], v[174:175], v[176:177]
	v_pk_fma_f32 v[176:177], v[174:175], v[176:177], v[174:175] neg_lo:[1,0,0] neg_hi:[1,0,0]
	v_pk_mul_f32 v[186:187], v[186:187], s[58:59] op_sel_hi:[1,0]
	v_cndmask_b32_e32 v174, v176, v178, vcc
	v_cmp_gt_f32_e32 vcc, 0, v175
	v_exp_f32_e32 v186, v186
	v_exp_f32_e32 v187, v187
	v_cndmask_b32_e32 v175, v177, v179, vcc
	v_pk_mul_f32 v[178:179], v[60:61], v[154:155] op_sel_hi:[1,0]
	v_pk_fma_f32 v[176:177], v[184:185], s[42:43], v[158:159] op_sel_hi:[1,0,0]
	v_and_b32_e32 v189, 0x7fffffff, v179
	v_pk_fma_f32 v[176:177], v[184:185], v[176:177], s[52:53] op_sel_hi:[1,1,0]
	v_and_b32_e32 v188, 0x7fffffff, v178
	v_pk_fma_f32 v[176:177], v[184:185], v[176:177], s[54:55] op_sel_hi:[1,1,0]
	v_pk_fma_f32 v[188:189], v[188:189], s[40:41], 1.0 op_sel_hi:[1,0,0]
	v_pk_fma_f32 v[176:177], v[184:185], v[176:177], s[56:57] op_sel_hi:[1,1,0]
	v_rcp_f32_e32 v188, v188
	v_rcp_f32_e32 v189, v189
	v_pk_mul_f32 v[176:177], v[184:185], v[176:177]
	v_pk_mul_f32 v[184:185], v[178:179], v[178:179]
	v_pk_mul_f32 v[176:177], v[186:187], v[176:177]
	v_cmp_gt_f32_e32 vcc, 0, v180
	v_pk_mul_f32 v[186:187], v[180:181], v[176:177]
	v_pk_fma_f32 v[176:177], v[180:181], v[176:177], v[180:181] neg_lo:[1,0,0] neg_hi:[1,0,0]
	v_pk_fma_f32 v[158:159], v[188:189], s[42:43], v[158:159] op_sel_hi:[1,0,0]
	v_cndmask_b32_e32 v154, v176, v186, vcc
	v_cmp_gt_f32_e32 vcc, 0, v181
	v_pk_mul_f32 v[180:181], v[184:185], s[58:59] op_sel_hi:[1,0]
	v_pk_fma_f32 v[158:159], v[188:189], v[158:159], s[52:53] op_sel_hi:[1,1,0]
	v_exp_f32_e32 v180, v180
	v_exp_f32_e32 v181, v181
	v_pk_fma_f32 v[158:159], v[188:189], v[158:159], s[54:55] op_sel_hi:[1,1,0]
	v_cndmask_b32_e32 v176, v177, v187, vcc
	v_pk_fma_f32 v[158:159], v[188:189], v[158:159], s[56:57] op_sel_hi:[1,1,0]
	v_cmp_gt_f32_e32 vcc, 0, v178
	v_pk_mul_f32 v[158:159], v[188:189], v[158:159]
	s_nop 0
	v_pk_mul_f32 v[158:159], v[180:181], v[158:159]
	s_nop 0
	v_pk_mul_f32 v[180:181], v[178:179], v[158:159]
	v_pk_fma_f32 v[158:159], v[178:179], v[158:159], v[178:179] neg_lo:[1,0,0] neg_hi:[1,0,0]
	v_cvt_pk_bf16_f32 v178, v172, v173
	s_nop 0
	v_cndmask_b32_e32 v158, v158, v180, vcc
	v_cmp_gt_f32_e32 vcc, 0, v179
	v_cvt_pk_bf16_f32 v179, v174, v175
	v_cvt_pk_bf16_f32 v180, v154, v176
	s_nop 1
	v_cndmask_b32_e32 v159, v159, v181, vcc
	s_and_b64 vcc, exec, s[10:11]
	v_cvt_pk_bf16_f32 v181, v158, v159
	global_store_dwordx4 v[182:183], v[178:181], off offset:256 sc1
	s_cbranch_vccnz .LBB0_944
	v_mul_f32_e32 v165, v165, v165
	v_fmac_f32_e32 v165, v151, v151
	v_mul_f32_e32 v151, v167, v167
	v_fmac_f32_e32 v151, v166, v166
	v_add_f32_e32 v151, v165, v151
	v_mul_f32_e32 v165, v169, v169
	v_mul_f32_e32 v166, v171, v171
	v_fmac_f32_e32 v165, v168, v168
	v_fmac_f32_e32 v166, v170, v170
	v_add_f32_e32 v165, v165, v166
	v_add_f32_e32 v151, v151, v165
	v_mul_f32_e32 v165, v173, v173
	v_mul_f32_e32 v166, v175, v175
	v_fmac_f32_e32 v165, v172, v172
	v_fmac_f32_e32 v166, v174, v174
	v_add_f32_e32 v165, v165, v166
	v_mul_f32_e32 v166, v176, v176
	v_fmac_f32_e32 v166, v154, v154
	v_mul_f32_e32 v154, v159, v159
	v_fmac_f32_e32 v154, v158, v158
	v_add_f32_e32 v154, v166, v154
	v_add_f32_e32 v154, v165, v154
	v_and_b32_e32 v158, 64, v164
	v_add_f32_e32 v151, v151, v154
	v_xor_b32_e32 v154, 16, v164
	v_add_u32_e32 v158, 64, v158
	v_cmp_lt_i32_e32 vcc, v154, v158
	s_nop 1
	v_cndmask_b32_e32 v154, v164, v154, vcc
	v_lshlrev_b32_e32 v154, 2, v154
	ds_bpermute_b32 v154, v154, v151
	s_waitcnt lgkmcnt(0)
	v_add_f32_e32 v151, v151, v154
	v_xor_b32_e32 v154, 32, v164
	v_cmp_lt_i32_e32 vcc, v154, v158
	s_nop 1
	v_cndmask_b32_e32 v154, v164, v154, vcc
	v_lshlrev_b32_e32 v154, 2, v154
	ds_bpermute_b32 v154, v154, v151
	s_and_saveexec_b64 s[78:79], s[4:5]
	s_cbranch_execz .LBB0_943
	v_lshlrev_b64 v[156:157], 6, v[156:157]
	v_lshl_add_u64 v[156:157], s[18:19], 0, v[156:157]
	v_lshl_add_u64 v[156:157], s[76:77], 2, v[156:157]
	s_lshl_b32 s14, s59, 2
	v_lshl_add_u64 v[156:157], v[156:157], 0, s[14:15]
	s_waitcnt lgkmcnt(0)
	v_add_f32_e32 v151, v151, v154
	global_store_dword v[156:157], v151, off sc1

; __device__ __forceinline__ float dot4(f32x4 v) { return (v[0] * v[0] + v[1] * v[1]) + (v[2] * v[2] + v[3] * v[3]); }
; __device__ __forceinline__ u32x2 pack4(f32x4 v) { u32x2 w; w.x = cvt_pk_bf16(v[0], v[1]); w.y = cvt_pk_bf16(v[2], v[3]); return w; }
; __device__ __forceinline__ f32x2 gelu_pk(f32x2 v) {
;     const f32x2 av = __builtin_elementwise_abs(v), d = av * 0.2316418882f + 1.0f;
;     f32x2 t; t.x = __builtin_amdgcn_rcpf(d.x); t.y = __builtin_amdgcn_rcpf(d.y);
;     f32x2 q = t * 0.5307027145f + (-0.7265760135f); q = q * t + 0.7107068705f; q = q * t + (-0.142248368f); q = q * t + 0.127414796f; q = q * t;
;     const f32x2 s = (v * v) * (-0.72134752044f);
;     f32x2 e; e.x = __builtin_amdgcn_exp2f(s.x); e.y = __builtin_amdgcn_exp2f(s.y);
;     const f32x2 m = v * (q * e), r = v - m;
;     f32x2 o; o.x = v.x < 0.f ? m.x : r.x; o.y = v.y < 0.f ? m.y : r.y; return o;
; }
; __device__ __forceinline__ f32x4 gelu4(f32x4 v) { f32x2 a = gelu_pk((f32x2){v[0], v[1]}), b = gelu_pk((f32x2){v[2], v[3]}); return (f32x4){a.x, a.y, b.x, b.y}; }
; template <int EK>
; __device__ __forceinline__ void epi_tile(const f32x4 (&acc)[2][2][4][2], const Unit& u, int wr, int wc, int fr, int fq, const EpiArgs& E, const LAS float* rt) {
;     ...
;             } else if (EK == EK_GELU) {
;                 const float r = rr[ai][m]; float ss = 0.f;
; #pragma unroll
;                 for (int bj = 0; bj < 2; ++bj) { const int col = u.pn * BM + bj * HALF + wc * 32 + fq * 8;
;                     const f32x4 z0 = gelu4(acc[ai][bj][m][0] * r), z1 = gelu4(acc[ai][bj][m][1] * r); ss += dot4(z0) + dot4(z1);
;                     const u32x2 lo = pack4(z0), hi = pack4(z1);
;                     *(u32x4*)(E.ob + (size_t)row * E.ldb + col) = (u32x4){lo.x, lo.y, hi.x, hi.y}; }
.LBB0_944:
	v_mov_b32_e32 v174, v155
	v_pk_mul_f32 v[158:159], v[86:87], v[174:175] op_sel_hi:[1,0]
	v_pk_mul_f32 v[168:169], v[88:89], v[174:175] op_sel_hi:[1,0]
	v_and_b32_e32 v157, 0x7fffffff, v159
	v_and_b32_e32 v156, 0x7fffffff, v158
	v_pk_fma_f32 v[156:157], v[156:157], s[40:41], 1.0 op_sel_hi:[1,0,0]
	v_pk_mul_f32 v[172:173], v[158:159], v[158:159]
	v_rcp_f32_e32 v166, v156
	v_rcp_f32_e32 v167, v157
	v_mov_b64_e32 v[156:157], s[44:45]
	v_pk_mul_f32 v[172:173], v[172:173], s[58:59] op_sel_hi:[1,0]
	v_and_b32_e32 v177, 0x7fffffff, v169
	v_pk_fma_f32 v[170:171], v[166:167], s[42:43], v[156:157] op_sel_hi:[1,0,0]
	v_exp_f32_e32 v172, v172
	v_pk_fma_f32 v[170:171], v[166:167], v[170:171], s[52:53] op_sel_hi:[1,1,0]
	v_exp_f32_e32 v173, v173
	v_pk_fma_f32 v[170:171], v[166:167], v[170:171], s[54:55] op_sel_hi:[1,1,0]
	v_and_b32_e32 v176, 0x7fffffff, v168
	v_pk_fma_f32 v[170:171], v[166:167], v[170:171], s[56:57] op_sel_hi:[1,1,0]
	v_pk_fma_f32 v[176:177], v[176:177], s[40:41], 1.0 op_sel_hi:[1,0,0]
	v_pk_mul_f32 v[166:167], v[166:167], v[170:171]
	v_rcp_f32_e32 v176, v176
	v_rcp_f32_e32 v177, v177
	v_pk_mul_f32 v[166:167], v[172:173], v[166:167]
	v_cmp_gt_f32_e32 vcc, 0, v158
	v_pk_mul_f32 v[172:173], v[158:159], v[166:167]
	v_pk_fma_f32 v[166:167], v[158:159], v[166:167], v[158:159] neg_lo:[1,0,0] neg_hi:[1,0,0]
	v_pk_mul_f32 v[170:171], v[168:169], v[168:169]
	v_cndmask_b32_e32 v151, v166, v172, vcc
	v_cmp_gt_f32_e32 vcc, 0, v159
	v_pk_mul_f32 v[170:171], v[170:171], s[58:59] op_sel_hi:[1,0]
	s_waitcnt lgkmcnt(0)
	v_or_b32_e32 v154, 48, v150
	v_cndmask_b32_e32 v158, v167, v173, vcc
	v_pk_fma_f32 v[166:167], v[176:177], s[42:43], v[156:157] op_sel_hi:[1,0,0]
	v_exp_f32_e32 v170, v170
	v_pk_fma_f32 v[166:167], v[176:177], v[166:167], s[52:53] op_sel_hi:[1,1,0]
	v_exp_f32_e32 v171, v171
	v_pk_fma_f32 v[166:167], v[176:177], v[166:167], s[54:55] op_sel_hi:[1,1,0]
	v_pk_mul_f32 v[172:173], v[82:83], v[174:175] op_sel_hi:[1,0]
	v_pk_fma_f32 v[166:167], v[176:177], v[166:167], s[56:57] op_sel_hi:[1,1,0]
	v_cmp_gt_f32_e32 vcc, 0, v168
	v_pk_mul_f32 v[166:167], v[176:177], v[166:167]
	v_and_b32_e32 v177, 0x7fffffff, v173
	v_and_b32_e32 v176, 0x7fffffff, v172
	v_pk_fma_f32 v[176:177], v[176:177], s[40:41], 1.0 op_sel_hi:[1,0,0]
	v_pk_mul_f32 v[166:167], v[170:171], v[166:167]
	v_rcp_f32_e32 v176, v176
	v_rcp_f32_e32 v177, v177
	v_pk_mul_f32 v[170:171], v[168:169], v[166:167]
	v_pk_fma_f32 v[166:167], v[168:169], v[166:167], v[168:169] neg_lo:[1,0,0] neg_hi:[1,0,0]
	v_ashrrev_i32_e32 v155, 31, v154
	v_cndmask_b32_e32 v159, v166, v170, vcc
	v_cmp_gt_f32_e32 vcc, 0, v169
	v_pk_mul_f32 v[168:169], v[84:85], v[174:175] op_sel_hi:[1,0]
	s_nop 0
	v_cndmask_b32_e32 v165, v167, v171, vcc
	v_pk_mul_f32 v[170:171], v[172:173], v[172:173]
	v_pk_fma_f32 v[166:167], v[176:177], s[42:43], v[156:157] op_sel_hi:[1,0,0]
	v_pk_mul_f32 v[170:171], v[170:171], s[58:59] op_sel_hi:[1,0]
	v_pk_fma_f32 v[166:167], v[176:177], v[166:167], s[52:53] op_sel_hi:[1,1,0]
	v_exp_f32_e32 v170, v170
	v_exp_f32_e32 v171, v171
	v_pk_fma_f32 v[166:167], v[176:177], v[166:167], s[54:55] op_sel_hi:[1,1,0]
	v_and_b32_e32 v179, 0x7fffffff, v169
	v_and_b32_e32 v178, 0x7fffffff, v168
	v_pk_fma_f32 v[166:167], v[176:177], v[166:167], s[56:57] op_sel_hi:[1,1,0]
	v_pk_fma_f32 v[178:179], v[178:179], s[40:41], 1.0 op_sel_hi:[1,0,0]
	v_pk_mul_f32 v[166:167], v[176:177], v[166:167]
	v_rcp_f32_e32 v178, v178
	v_rcp_f32_e32 v179, v179
	v_pk_mul_f32 v[166:167], v[170:171], v[166:167]
	v_cmp_gt_f32_e32 vcc, 0, v172
	v_pk_mul_f32 v[170:171], v[172:173], v[166:167]
	v_pk_fma_f32 v[166:167], v[172:173], v[166:167], v[172:173] neg_lo:[1,0,0] neg_hi:[1,0,0]
	v_pk_mul_f32 v[176:177], v[168:169], v[168:169]
	v_cndmask_b32_e32 v166, v166, v170, vcc
	v_cmp_gt_f32_e32 vcc, 0, v173
	v_pk_mul_f32 v[172:173], v[176:177], s[58:59] op_sel_hi:[1,0]
	v_lshlrev_b64 v[176:177], 12, v[154:155]
	v_cndmask_b32_e32 v167, v167, v171, vcc
	v_pk_fma_f32 v[170:171], v[178:179], s[42:43], v[156:157] op_sel_hi:[1,0,0]
	v_exp_f32_e32 v172, v172
	v_pk_fma_f32 v[170:171], v[178:179], v[170:171], s[52:53] op_sel_hi:[1,1,0]
	v_exp_f32_e32 v173, v173
	v_pk_fma_f32 v[170:171], v[178:179], v[170:171], s[54:55] op_sel_hi:[1,1,0]
	v_cmp_gt_f32_e32 vcc, 0, v168
	v_pk_fma_f32 v[170:171], v[178:179], v[170:171], s[56:57] op_sel_hi:[1,1,0]
	v_lshl_add_u64 v[176:177], s[64:65], 0, v[176:177]
	v_pk_mul_f32 v[170:171], v[178:179], v[170:171]
	v_pk_mul_f32 v[178:179], v[54:55], v[174:175] op_sel_hi:[1,0]
	v_pk_mul_f32 v[170:171], v[172:173], v[170:171]
	v_and_b32_e32 v181, 0x7fffffff, v179
	v_and_b32_e32 v180, 0x7fffffff, v178
	v_pk_fma_f32 v[180:181], v[180:181], s[40:41], 1.0 op_sel_hi:[1,0,0]
	v_pk_mul_f32 v[172:173], v[168:169], v[170:171]
	v_rcp_f32_e32 v180, v180
	v_rcp_f32_e32 v181, v181
	v_pk_fma_f32 v[170:171], v[168:169], v[170:171], v[168:169] neg_lo:[1,0,0] neg_hi:[1,0,0]
	v_lshl_add_u64 v[182:183], v[146:147], 1, v[176:177]
	v_cndmask_b32_e32 v168, v170, v172, vcc
	v_cmp_gt_f32_e32 vcc, 0, v169
	v_cvt_pk_bf16_f32 v170, v151, v158
	v_pk_mul_f32 v[176:177], v[178:179], v[178:179]
	v_cvt_pk_bf16_f32 v172, v166, v167
	s_nop 0
	v_cndmask_b32_e32 v169, v171, v173, vcc
	v_cvt_pk_bf16_f32 v171, v159, v165
	v_cvt_pk_bf16_f32 v173, v168, v169
	global_store_dwordx4 v[182:183], v[170:173], off sc1
	v_pk_mul_f32 v[176:177], v[176:177], s[58:59] op_sel_hi:[1,0]
	v_cmp_gt_f32_e32 vcc, 0, v178
	v_pk_fma_f32 v[170:171], v[180:181], s[42:43], v[156:157] op_sel_hi:[1,0,0]
	v_pk_mul_f32 v[172:173], v[56:57], v[174:175] op_sel_hi:[1,0]
	v_pk_fma_f32 v[170:171], v[180:181], v[170:171], s[52:53] op_sel_hi:[1,1,0]
	v_exp_f32_e32 v176, v176
; __device__ __forceinline__ float dot4(f32x4 v) { return (v[0] * v[0] + v[1] * v[1]) + (v[2] * v[2] + v[3] * v[3]); }
; __device__ __forceinline__ u32x2 pack4(f32x4 v) { u32x2 w; w.x = cvt_pk_bf16(v[0], v[1]); w.y = cvt_pk_bf16(v[2], v[3]); return w; }
; __device__ __forceinline__ float quad_sum(float s) { s += __shfl_xor(s, 16); s += __shfl_xor(s, 32); return s; }
; __device__ __forceinline__ f32x4 gelu4(f32x4 v) { f32x2 a = gelu_pk((f32x2){v[0], v[1]}), b = gelu_pk((f32x2){v[2], v[3]}); return (f32x4){a.x, a.y, b.x, b.y}; }
; template <int EK>
; __device__ __forceinline__ void epi_tile(const f32x4 (&acc)[2][2][4][2], const Unit& u, int wr, int wc, int fr, int fq, const EpiArgs& E, const LAS float* rt) {
;     ...
;             } else if (EK == EK_GELU) {
;                 const float r = rr[ai][m]; float ss = 0.f;
; #pragma unroll
;                 for (int bj = 0; bj < 2; ++bj) { const int col = u.pn * BM + bj * HALF + wc * 32 + fq * 8;
;                     const f32x4 z0 = gelu4(acc[ai][bj][m][0] * r), z1 = gelu4(acc[ai][bj][m][1] * r); ss += dot4(z0) + dot4(z1);
;                     const u32x2 lo = pack4(z0), hi = pack4(z1);
;                     *(u32x4*)(E.ob + (size_t)row * E.ldb + col) = (u32x4){lo.x, lo.y, hi.x, hi.y}; }
;                 if (u.pn >= 4) { ss = quad_sum(ss); if (fq == 0) E.stOut[(size_t)row * 16 + (u.pn - 4) * 4 + wc] = ss; }
	v_exp_f32_e32 v177, v177
	v_pk_fma_f32 v[170:171], v[180:181], v[170:171], s[54:55] op_sel_hi:[1,1,0]
	v_and_b32_e32 v185, 0x7fffffff, v173
	v_and_b32_e32 v184, 0x7fffffff, v172
	v_pk_fma_f32 v[170:171], v[180:181], v[170:171], s[56:57] op_sel_hi:[1,1,0]
	v_pk_fma_f32 v[184:185], v[184:185], s[40:41], 1.0 op_sel_hi:[1,0,0]
	v_pk_mul_f32 v[170:171], v[180:181], v[170:171]
	v_rcp_f32_e32 v184, v184
	v_rcp_f32_e32 v185, v185
	v_pk_mul_f32 v[170:171], v[176:177], v[170:171]
	v_pk_mul_f32 v[180:181], v[172:173], v[172:173]
	v_pk_mul_f32 v[176:177], v[178:179], v[170:171]
	v_pk_fma_f32 v[170:171], v[178:179], v[170:171], v[178:179] neg_lo:[1,0,0] neg_hi:[1,0,0]
	s_nop 0
	v_cndmask_b32_e32 v170, v170, v176, vcc
	v_cmp_gt_f32_e32 vcc, 0, v179
	v_pk_mul_f32 v[178:179], v[180:181], s[58:59] op_sel_hi:[1,0]
	v_pk_mul_f32 v[180:181], v[50:51], v[174:175] op_sel_hi:[1,0]
	v_cndmask_b32_e32 v171, v171, v177, vcc
	v_pk_fma_f32 v[176:177], v[184:185], s[42:43], v[156:157] op_sel_hi:[1,0,0]
	v_exp_f32_e32 v178, v178
	v_pk_fma_f32 v[176:177], v[184:185], v[176:177], s[52:53] op_sel_hi:[1,1,0]
	v_exp_f32_e32 v179, v179
	v_pk_fma_f32 v[176:177], v[184:185], v[176:177], s[54:55] op_sel_hi:[1,1,0]
	v_cmp_gt_f32_e32 vcc, 0, v172
	v_pk_fma_f32 v[176:177], v[184:185], v[176:177], s[56:57] op_sel_hi:[1,1,0]
	s_nop 0
	v_pk_mul_f32 v[176:177], v[184:185], v[176:177]
	v_and_b32_e32 v185, 0x7fffffff, v181
	v_and_b32_e32 v184, 0x7fffffff, v180
	v_pk_fma_f32 v[184:185], v[184:185], s[40:41], 1.0 op_sel_hi:[1,0,0]
	v_pk_mul_f32 v[176:177], v[178:179], v[176:177]
	v_rcp_f32_e32 v184, v184
	v_rcp_f32_e32 v185, v185
	v_pk_mul_f32 v[178:179], v[172:173], v[176:177]
	v_pk_fma_f32 v[176:177], v[172:173], v[176:177], v[172:173] neg_lo:[1,0,0] neg_hi:[1,0,0]
	s_nop 0
	v_cndmask_b32_e32 v172, v176, v178, vcc
	v_cmp_gt_f32_e32 vcc, 0, v173
	s_nop 1
	v_cndmask_b32_e32 v173, v177, v179, vcc
	v_pk_mul_f32 v[178:179], v[180:181], v[180:181]
	v_pk_mul_f32 v[176:177], v[52:53], v[174:175] op_sel_hi:[1,0]
	v_pk_fma_f32 v[174:175], v[184:185], s[42:43], v[156:157] op_sel_hi:[1,0,0]
	v_pk_mul_f32 v[178:179], v[178:179], s[58:59] op_sel_hi:[1,0]
	v_pk_fma_f32 v[174:175], v[184:185], v[174:175], s[52:53] op_sel_hi:[1,1,0]
	v_exp_f32_e32 v178, v178
	v_exp_f32_e32 v179, v179
	v_pk_fma_f32 v[174:175], v[184:185], v[174:175], s[54:55] op_sel_hi:[1,1,0]
	v_and_b32_e32 v187, 0x7fffffff, v177
	v_and_b32_e32 v186, 0x7fffffff, v176
	v_pk_fma_f32 v[174:175], v[184:185], v[174:175], s[56:57] op_sel_hi:[1,1,0]
	v_pk_fma_f32 v[186:187], v[186:187], s[40:41], 1.0 op_sel_hi:[1,0,0]
	v_pk_mul_f32 v[174:175], v[184:185], v[174:175]
	v_rcp_f32_e32 v186, v186
	v_rcp_f32_e32 v187, v187
	v_pk_mul_f32 v[174:175], v[178:179], v[174:175]
	v_cmp_gt_f32_e32 vcc, 0, v180
	v_pk_mul_f32 v[178:179], v[180:181], v[174:175]
	v_pk_fma_f32 v[174:175], v[180:181], v[174:175], v[180:181] neg_lo:[1,0,0] neg_hi:[1,0,0]
	v_pk_mul_f32 v[184:185], v[176:177], v[176:177]
	v_cndmask_b32_e32 v174, v174, v178, vcc
	v_cmp_gt_f32_e32 vcc, 0, v181
	v_pk_fma_f32 v[156:157], v[186:187], s[42:43], v[156:157] op_sel_hi:[1,0,0]
	s_nop 0
	v_cndmask_b32_e32 v175, v175, v179, vcc
	v_pk_mul_f32 v[178:179], v[184:185], s[58:59] op_sel_hi:[1,0]
	v_pk_fma_f32 v[156:157], v[186:187], v[156:157], s[52:53] op_sel_hi:[1,1,0]
	v_exp_f32_e32 v178, v178
	v_exp_f32_e32 v179, v179
	v_pk_fma_f32 v[156:157], v[186:187], v[156:157], s[54:55] op_sel_hi:[1,1,0]
	v_cmp_gt_f32_e32 vcc, 0, v176
	v_pk_fma_f32 v[156:157], v[186:187], v[156:157], s[56:57] op_sel_hi:[1,1,0]
	s_nop 0
	v_pk_mul_f32 v[156:157], v[186:187], v[156:157]
	s_nop 0
	v_pk_mul_f32 v[156:157], v[178:179], v[156:157]
	s_nop 0
	v_pk_mul_f32 v[178:179], v[176:177], v[156:157]
	v_pk_fma_f32 v[156:157], v[176:177], v[156:157], v[176:177] neg_lo:[1,0,0] neg_hi:[1,0,0]
	v_cvt_pk_bf16_f32 v176, v170, v171
	s_nop 0
	v_cndmask_b32_e32 v156, v156, v178, vcc
	v_cmp_gt_f32_e32 vcc, 0, v177
	v_cvt_pk_bf16_f32 v177, v172, v173
	v_cvt_pk_bf16_f32 v178, v174, v175
	s_nop 1
	v_cndmask_b32_e32 v157, v157, v179, vcc
	s_and_b64 vcc, exec, s[10:11]
	v_cvt_pk_bf16_f32 v179, v156, v157
	global_store_dwordx4 v[182:183], v[176:179], off offset:256 sc1
	s_cbranch_vccnz .LBB0_948
	v_mul_f32_e32 v158, v158, v158
	v_fmac_f32_e32 v158, v151, v151
	v_mul_f32_e32 v151, v165, v165
	v_fmac_f32_e32 v151, v159, v159
	v_add_f32_e32 v151, v158, v151
	v_mul_f32_e32 v158, v167, v167
	v_mul_f32_e32 v159, v169, v169
	v_fmac_f32_e32 v158, v166, v166
	v_fmac_f32_e32 v159, v168, v168
	v_add_f32_e32 v158, v158, v159
	v_add_f32_e32 v151, v151, v158
	v_mul_f32_e32 v158, v171, v171
	v_mul_f32_e32 v159, v173, v173
	v_fmac_f32_e32 v158, v170, v170
	v_fmac_f32_e32 v159, v172, v172
	v_add_f32_e32 v158, v158, v159
	v_mul_f32_e32 v159, v175, v175
	v_mul_f32_e32 v157, v157, v157
	v_fmac_f32_e32 v159, v174, v174
	v_fmac_f32_e32 v157, v156, v156
	v_add_f32_e32 v156, v159, v157
	v_add_f32_e32 v156, v158, v156
	v_and_b32_e32 v157, 64, v164
	v_add_f32_e32 v151, v151, v156
	v_xor_b32_e32 v156, 16, v164
	v_add_u32_e32 v157, 64, v157
	v_cmp_lt_i32_e32 vcc, v156, v157
	s_nop 1
	v_cndmask_b32_e32 v156, v164, v156, vcc
	v_lshlrev_b32_e32 v156, 2, v156
	ds_bpermute_b32 v156, v156, v151
	s_waitcnt lgkmcnt(0)
	v_add_f32_e32 v151, v151, v156
	v_xor_b32_e32 v156, 32, v164
	v_cmp_lt_i32_e32 vcc, v156, v157
	s_nop 1
	v_cndmask_b32_e32 v156, v164, v156, vcc
	v_lshlrev_b32_e32 v156, 2, v156
	ds_bpermute_b32 v156, v156, v151
	s_and_saveexec_b64 s[78:79], s[4:5]
	s_cbranch_execz .LBB0_947
	v_lshlrev_b64 v[154:155], 6, v[154:155]
	v_lshl_add_u64 v[154:155], s[18:19], 0, v[154:155]
	v_lshl_add_u64 v[154:155], s[76:77], 2, v[154:155]
	s_lshl_b32 s14, s59, 2
	v_lshl_add_u64 v[154:155], v[154:155], 0, s[14:15]
	s_waitcnt lgkmcnt(0)
	v_add_f32_e32 v151, v151, v156
	global_store_dword v[154:155], v151, off sc1

; __device__ __forceinline__ float dot4(f32x4 v) { return (v[0] * v[0] + v[1] * v[1]) + (v[2] * v[2] + v[3] * v[3]); }
; __device__ __forceinline__ u32x2 pack4(f32x4 v) { u32x2 w; w.x = cvt_pk_bf16(v[0], v[1]); w.y = cvt_pk_bf16(v[2], v[3]); return w; }
; __device__ __forceinline__ f32x2 gelu_pk(f32x2 v) {
;     const f32x2 av = __builtin_elementwise_abs(v), d = av * 0.2316418882f + 1.0f;
;     f32x2 t; t.x = __builtin_amdgcn_rcpf(d.x); t.y = __builtin_amdgcn_rcpf(d.y);
;     f32x2 q = t * 0.5307027145f + (-0.7265760135f); q = q * t + 0.7107068705f; q = q * t + (-0.142248368f); q = q * t + 0.127414796f; q = q * t;
;     const f32x2 s = (v * v) * (-0.72134752044f);
;     f32x2 e; e.x = __builtin_amdgcn_exp2f(s.x); e.y = __builtin_amdgcn_exp2f(s.y);
;     const f32x2 m = v * (q * e), r = v - m;
;     f32x2 o; o.x = v.x < 0.f ? m.x : r.x; o.y = v.y < 0.f ? m.y : r.y; return o;
; }
; __device__ __forceinline__ f32x4 gelu4(f32x4 v) { f32x2 a = gelu_pk((f32x2){v[0], v[1]}), b = gelu_pk((f32x2){v[2], v[3]}); return (f32x4){a.x, a.y, b.x, b.y}; }
; template <int EK>
; __device__ __forceinline__ void epi_tile(const f32x4 (&acc)[2][2][4][2], const Unit& u, int wr, int wc, int fr, int fq, const EpiArgs& E, const LAS float* rt) {
;     ...
;             } else if (EK == EK_GELU) {
;                 const float r = rr[ai][m]; float ss = 0.f;
; #pragma unroll
;                 for (int bj = 0; bj < 2; ++bj) { const int col = u.pn * BM + bj * HALF + wc * 32 + fq * 8;
;                     const f32x4 z0 = gelu4(acc[ai][bj][m][0] * r), z1 = gelu4(acc[ai][bj][m][1] * r); ss += dot4(z0) + dot4(z1);
;                     const u32x2 lo = pack4(z0), hi = pack4(z1);
;                     *(u32x4*)(E.ob + (size_t)row * E.ldb + col) = (u32x4){lo.x, lo.y, hi.x, hi.y}; }
.LBB0_948:
	v_pk_mul_f32 v[158:159], v[46:47], v[152:153] op_sel_hi:[1,0]
	v_pk_mul_f32 v[168:169], v[48:49], v[152:153] op_sel_hi:[1,0]
	v_and_b32_e32 v157, 0x7fffffff, v159
	s_waitcnt lgkmcnt(0)
	v_and_b32_e32 v156, 0x7fffffff, v158
	v_pk_fma_f32 v[156:157], v[156:157], s[40:41], 1.0 op_sel_hi:[1,0,0]
	v_pk_mul_f32 v[172:173], v[158:159], v[158:159]
	v_rcp_f32_e32 v166, v156
	v_rcp_f32_e32 v167, v157
	v_mov_b64_e32 v[156:157], s[44:45]
	v_pk_mul_f32 v[172:173], v[172:173], s[58:59] op_sel_hi:[1,0]
	v_and_b32_e32 v175, 0x7fffffff, v169
	v_pk_fma_f32 v[170:171], v[166:167], s[42:43], v[156:157] op_sel_hi:[1,0,0]
	v_exp_f32_e32 v172, v172
	v_pk_fma_f32 v[170:171], v[166:167], v[170:171], s[52:53] op_sel_hi:[1,1,0]
	v_exp_f32_e32 v173, v173
	v_pk_fma_f32 v[170:171], v[166:167], v[170:171], s[54:55] op_sel_hi:[1,1,0]
	v_and_b32_e32 v174, 0x7fffffff, v168
	v_pk_fma_f32 v[170:171], v[166:167], v[170:171], s[56:57] op_sel_hi:[1,1,0]
	v_pk_fma_f32 v[174:175], v[174:175], s[40:41], 1.0 op_sel_hi:[1,0,0]
	v_pk_mul_f32 v[166:167], v[166:167], v[170:171]
	v_rcp_f32_e32 v174, v174
	v_rcp_f32_e32 v175, v175
	v_pk_mul_f32 v[166:167], v[172:173], v[166:167]
	v_cmp_gt_f32_e32 vcc, 0, v158
	v_pk_mul_f32 v[172:173], v[158:159], v[166:167]
	v_pk_fma_f32 v[166:167], v[158:159], v[166:167], v[158:159] neg_lo:[1,0,0] neg_hi:[1,0,0]
	v_pk_mul_f32 v[170:171], v[168:169], v[168:169]
	v_cndmask_b32_e32 v151, v166, v172, vcc
	v_cmp_gt_f32_e32 vcc, 0, v159
	v_pk_mul_f32 v[170:171], v[170:171], s[58:59] op_sel_hi:[1,0]
	v_add_u32_e32 v154, 0x80, v150
	v_cndmask_b32_e32 v158, v167, v173, vcc
	v_pk_fma_f32 v[166:167], v[174:175], s[42:43], v[156:157] op_sel_hi:[1,0,0]
	v_exp_f32_e32 v170, v170
	v_pk_fma_f32 v[166:167], v[174:175], v[166:167], s[52:53] op_sel_hi:[1,1,0]
	v_exp_f32_e32 v171, v171
	v_pk_fma_f32 v[166:167], v[174:175], v[166:167], s[54:55] op_sel_hi:[1,1,0]
	v_pk_mul_f32 v[172:173], v[42:43], v[152:153] op_sel_hi:[1,0]
	v_pk_fma_f32 v[166:167], v[174:175], v[166:167], s[56:57] op_sel_hi:[1,1,0]
	v_cmp_gt_f32_e32 vcc, 0, v168
	v_pk_mul_f32 v[166:167], v[174:175], v[166:167]
	v_and_b32_e32 v175, 0x7fffffff, v173
	v_and_b32_e32 v174, 0x7fffffff, v172
	v_pk_fma_f32 v[174:175], v[174:175], s[40:41], 1.0 op_sel_hi:[1,0,0]
	v_pk_mul_f32 v[166:167], v[170:171], v[166:167]
	v_rcp_f32_e32 v174, v174
	v_rcp_f32_e32 v175, v175
	v_pk_mul_f32 v[170:171], v[168:169], v[166:167]
	v_pk_fma_f32 v[166:167], v[168:169], v[166:167], v[168:169] neg_lo:[1,0,0] neg_hi:[1,0,0]
	v_ashrrev_i32_e32 v155, 31, v154
	v_cndmask_b32_e32 v159, v166, v170, vcc
	v_cmp_gt_f32_e32 vcc, 0, v169
	v_pk_mul_f32 v[168:169], v[44:45], v[152:153] op_sel_hi:[1,0]
	s_nop 0
	v_cndmask_b32_e32 v165, v167, v171, vcc
	v_pk_mul_f32 v[170:171], v[172:173], v[172:173]
	v_pk_fma_f32 v[166:167], v[174:175], s[42:43], v[156:157] op_sel_hi:[1,0,0]
	v_pk_mul_f32 v[170:171], v[170:171], s[58:59] op_sel_hi:[1,0]
	v_pk_fma_f32 v[166:167], v[174:175], v[166:167], s[52:53] op_sel_hi:[1,1,0]
	v_exp_f32_e32 v170, v170
	v_exp_f32_e32 v171, v171
	v_pk_fma_f32 v[166:167], v[174:175], v[166:167], s[54:55] op_sel_hi:[1,1,0]
	v_and_b32_e32 v177, 0x7fffffff, v169
	v_and_b32_e32 v176, 0x7fffffff, v168
	v_pk_fma_f32 v[166:167], v[174:175], v[166:167], s[56:57] op_sel_hi:[1,1,0]
	v_pk_fma_f32 v[176:177], v[176:177], s[40:41], 1.0 op_sel_hi:[1,0,0]
	v_pk_mul_f32 v[166:167], v[174:175], v[166:167]
	v_rcp_f32_e32 v176, v176
	v_rcp_f32_e32 v177, v177
	v_pk_mul_f32 v[166:167], v[170:171], v[166:167]
	v_cmp_gt_f32_e32 vcc, 0, v172
	v_pk_mul_f32 v[170:171], v[172:173], v[166:167]
	v_pk_fma_f32 v[166:167], v[172:173], v[166:167], v[172:173] neg_lo:[1,0,0] neg_hi:[1,0,0]
	v_pk_mul_f32 v[174:175], v[168:169], v[168:169]
	v_cndmask_b32_e32 v166, v166, v170, vcc
	v_cmp_gt_f32_e32 vcc, 0, v173
	v_pk_mul_f32 v[172:173], v[174:175], s[58:59] op_sel_hi:[1,0]
	v_lshlrev_b64 v[174:175], 12, v[154:155]
	v_cndmask_b32_e32 v167, v167, v171, vcc
	v_pk_fma_f32 v[170:171], v[176:177], s[42:43], v[156:157] op_sel_hi:[1,0,0]
	v_exp_f32_e32 v172, v172
	v_pk_fma_f32 v[170:171], v[176:177], v[170:171], s[52:53] op_sel_hi:[1,1,0]
	v_exp_f32_e32 v173, v173
	v_pk_fma_f32 v[170:171], v[176:177], v[170:171], s[54:55] op_sel_hi:[1,1,0]
	v_cmp_gt_f32_e32 vcc, 0, v168
	v_pk_fma_f32 v[170:171], v[176:177], v[170:171], s[56:57] op_sel_hi:[1,1,0]
	v_lshl_add_u64 v[174:175], s[64:65], 0, v[174:175]
	v_pk_mul_f32 v[170:171], v[176:177], v[170:171]
	v_pk_mul_f32 v[176:177], v[14:15], v[152:153] op_sel_hi:[1,0]
	v_pk_mul_f32 v[170:171], v[172:173], v[170:171]
	v_and_b32_e32 v179, 0x7fffffff, v177
	v_and_b32_e32 v178, 0x7fffffff, v176
	v_pk_fma_f32 v[178:179], v[178:179], s[40:41], 1.0 op_sel_hi:[1,0,0]
	v_pk_mul_f32 v[172:173], v[168:169], v[170:171]
	v_rcp_f32_e32 v178, v178
	v_rcp_f32_e32 v179, v179
	v_pk_fma_f32 v[170:171], v[168:169], v[170:171], v[168:169] neg_lo:[1,0,0] neg_hi:[1,0,0]
	v_lshl_add_u64 v[180:181], v[146:147], 1, v[174:175]
	v_cndmask_b32_e32 v168, v170, v172, vcc
	v_cmp_gt_f32_e32 vcc, 0, v169
	v_cvt_pk_bf16_f32 v170, v151, v158
	v_pk_mul_f32 v[174:175], v[176:177], v[176:177]
	v_cvt_pk_bf16_f32 v172, v166, v167
	s_nop 0
	v_cndmask_b32_e32 v169, v171, v173, vcc
	v_cvt_pk_bf16_f32 v171, v159, v165
	v_cvt_pk_bf16_f32 v173, v168, v169
	global_store_dwordx4 v[180:181], v[170:173], off sc1
	v_pk_mul_f32 v[174:175], v[174:175], s[58:59] op_sel_hi:[1,0]
	v_cmp_gt_f32_e32 vcc, 0, v176
	v_pk_fma_f32 v[170:171], v[178:179], s[42:43], v[156:157] op_sel_hi:[1,0,0]
	v_pk_mul_f32 v[172:173], v[16:17], v[152:153] op_sel_hi:[1,0]
	v_pk_fma_f32 v[170:171], v[178:179], v[170:171], s[52:53] op_sel_hi:[1,1,0]
	v_exp_f32_e32 v174, v174
	v_exp_f32_e32 v175, v175
; __device__ __forceinline__ float dot4(f32x4 v) { return (v[0] * v[0] + v[1] * v[1]) + (v[2] * v[2] + v[3] * v[3]); }
; __device__ __forceinline__ u32x2 pack4(f32x4 v) { u32x2 w; w.x = cvt_pk_bf16(v[0], v[1]); w.y = cvt_pk_bf16(v[2], v[3]); return w; }
; __device__ __forceinline__ float quad_sum(float s) { s += __shfl_xor(s, 16); s += __shfl_xor(s, 32); return s; }
; __device__ __forceinline__ f32x4 gelu4(f32x4 v) { f32x2 a = gelu_pk((f32x2){v[0], v[1]}), b = gelu_pk((f32x2){v[2], v[3]}); return (f32x4){a.x, a.y, b.x, b.y}; }
; template <int EK>
; __device__ __forceinline__ void epi_tile(const f32x4 (&acc)[2][2][4][2], const Unit& u, int wr, int wc, int fr, int fq, const EpiArgs& E, const LAS float* rt) {
;     ...
;             } else if (EK == EK_GELU) {
;                 const float r = rr[ai][m]; float ss = 0.f;
; #pragma unroll
;                 for (int bj = 0; bj < 2; ++bj) { const int col = u.pn * BM + bj * HALF + wc * 32 + fq * 8;
;                     const f32x4 z0 = gelu4(acc[ai][bj][m][0] * r), z1 = gelu4(acc[ai][bj][m][1] * r); ss += dot4(z0) + dot4(z1);
;                     const u32x2 lo = pack4(z0), hi = pack4(z1);
;                     *(u32x4*)(E.ob + (size_t)row * E.ldb + col) = (u32x4){lo.x, lo.y, hi.x, hi.y}; }
;                 if (u.pn >= 4) { ss = quad_sum(ss); if (fq == 0) E.stOut[(size_t)row * 16 + (u.pn - 4) * 4 + wc] = ss; }
	v_pk_fma_f32 v[170:171], v[178:179], v[170:171], s[54:55] op_sel_hi:[1,1,0]
	v_and_b32_e32 v183, 0x7fffffff, v173
	v_and_b32_e32 v182, 0x7fffffff, v172
	v_pk_fma_f32 v[170:171], v[178:179], v[170:171], s[56:57] op_sel_hi:[1,1,0]
	v_pk_fma_f32 v[182:183], v[182:183], s[40:41], 1.0 op_sel_hi:[1,0,0]
	v_pk_mul_f32 v[170:171], v[178:179], v[170:171]
	v_rcp_f32_e32 v182, v182
	v_rcp_f32_e32 v183, v183
	v_pk_mul_f32 v[170:171], v[174:175], v[170:171]
	v_pk_mul_f32 v[178:179], v[172:173], v[172:173]
	v_pk_mul_f32 v[174:175], v[176:177], v[170:171]
	v_pk_fma_f32 v[170:171], v[176:177], v[170:171], v[176:177] neg_lo:[1,0,0] neg_hi:[1,0,0]
	s_nop 0
	v_cndmask_b32_e32 v170, v170, v174, vcc
	v_cmp_gt_f32_e32 vcc, 0, v177
	v_pk_mul_f32 v[176:177], v[178:179], s[58:59] op_sel_hi:[1,0]
	v_pk_mul_f32 v[178:179], v[10:11], v[152:153] op_sel_hi:[1,0]
	v_cndmask_b32_e32 v171, v171, v175, vcc
	v_pk_fma_f32 v[174:175], v[182:183], s[42:43], v[156:157] op_sel_hi:[1,0,0]
	v_exp_f32_e32 v176, v176
	v_pk_fma_f32 v[174:175], v[182:183], v[174:175], s[52:53] op_sel_hi:[1,1,0]
	v_exp_f32_e32 v177, v177
	v_pk_fma_f32 v[174:175], v[182:183], v[174:175], s[54:55] op_sel_hi:[1,1,0]
	v_cmp_gt_f32_e32 vcc, 0, v172
	v_pk_fma_f32 v[174:175], v[182:183], v[174:175], s[56:57] op_sel_hi:[1,1,0]
	v_pk_mul_f32 v[184:185], v[178:179], v[178:179]
	v_pk_mul_f32 v[174:175], v[182:183], v[174:175]
	v_and_b32_e32 v183, 0x7fffffff, v179
	v_and_b32_e32 v182, 0x7fffffff, v178
	v_pk_fma_f32 v[182:183], v[182:183], s[40:41], 1.0 op_sel_hi:[1,0,0]
	v_pk_mul_f32 v[174:175], v[176:177], v[174:175]
	v_rcp_f32_e32 v182, v182
	v_rcp_f32_e32 v183, v183
	v_pk_mul_f32 v[176:177], v[172:173], v[174:175]
	v_pk_fma_f32 v[174:175], v[172:173], v[174:175], v[172:173] neg_lo:[1,0,0] neg_hi:[1,0,0]
	v_pk_mul_f32 v[184:185], v[184:185], s[58:59] op_sel_hi:[1,0]
	v_cndmask_b32_e32 v172, v174, v176, vcc
	v_cmp_gt_f32_e32 vcc, 0, v173
	v_exp_f32_e32 v184, v184
	v_exp_f32_e32 v185, v185
	v_cndmask_b32_e32 v173, v175, v177, vcc
	v_pk_mul_f32 v[176:177], v[12:13], v[152:153] op_sel_hi:[1,0]
	v_pk_fma_f32 v[174:175], v[182:183], s[42:43], v[156:157] op_sel_hi:[1,0,0]
	v_and_b32_e32 v187, 0x7fffffff, v177
	v_pk_fma_f32 v[174:175], v[182:183], v[174:175], s[52:53] op_sel_hi:[1,1,0]
	v_and_b32_e32 v186, 0x7fffffff, v176
	v_pk_fma_f32 v[174:175], v[182:183], v[174:175], s[54:55] op_sel_hi:[1,1,0]
	v_pk_fma_f32 v[186:187], v[186:187], s[40:41], 1.0 op_sel_hi:[1,0,0]
	v_pk_fma_f32 v[174:175], v[182:183], v[174:175], s[56:57] op_sel_hi:[1,1,0]
	v_rcp_f32_e32 v186, v186
	v_rcp_f32_e32 v187, v187
	v_pk_mul_f32 v[174:175], v[182:183], v[174:175]
	v_pk_mul_f32 v[182:183], v[176:177], v[176:177]
	v_pk_mul_f32 v[174:175], v[184:185], v[174:175]
	v_cmp_gt_f32_e32 vcc, 0, v178
	v_pk_mul_f32 v[184:185], v[178:179], v[174:175]
	v_pk_fma_f32 v[174:175], v[178:179], v[174:175], v[178:179] neg_lo:[1,0,0] neg_hi:[1,0,0]
	v_pk_fma_f32 v[156:157], v[186:187], s[42:43], v[156:157] op_sel_hi:[1,0,0]
	v_cndmask_b32_e32 v152, v174, v184, vcc
	v_cmp_gt_f32_e32 vcc, 0, v179
	v_pk_mul_f32 v[178:179], v[182:183], s[58:59] op_sel_hi:[1,0]
	v_pk_fma_f32 v[156:157], v[186:187], v[156:157], s[52:53] op_sel_hi:[1,1,0]
	v_exp_f32_e32 v178, v178
	v_exp_f32_e32 v179, v179
	v_pk_fma_f32 v[156:157], v[186:187], v[156:157], s[54:55] op_sel_hi:[1,1,0]
	v_cndmask_b32_e32 v174, v175, v185, vcc
	v_pk_fma_f32 v[156:157], v[186:187], v[156:157], s[56:57] op_sel_hi:[1,1,0]
	v_cmp_gt_f32_e32 vcc, 0, v176
	v_pk_mul_f32 v[156:157], v[186:187], v[156:157]
	s_nop 0
	v_pk_mul_f32 v[156:157], v[178:179], v[156:157]
	s_nop 0
	v_pk_mul_f32 v[178:179], v[176:177], v[156:157]
	v_pk_fma_f32 v[156:157], v[176:177], v[156:157], v[176:177] neg_lo:[1,0,0] neg_hi:[1,0,0]
	v_cvt_pk_bf16_f32 v176, v170, v171
	s_nop 0
	v_cndmask_b32_e32 v156, v156, v178, vcc
	v_cmp_gt_f32_e32 vcc, 0, v177
	v_cvt_pk_bf16_f32 v177, v172, v173
	v_cvt_pk_bf16_f32 v178, v152, v174
	s_nop 1
	v_cndmask_b32_e32 v157, v157, v179, vcc
	s_and_b64 vcc, exec, s[10:11]
	v_cvt_pk_bf16_f32 v179, v156, v157
	global_store_dwordx4 v[180:181], v[176:179], off offset:256 sc1
	s_cbranch_vccnz .LBB0_952
	v_mul_f32_e32 v158, v158, v158
	v_fmac_f32_e32 v158, v151, v151
	v_mul_f32_e32 v151, v165, v165
	v_fmac_f32_e32 v151, v159, v159
	v_add_f32_e32 v151, v158, v151
	v_mul_f32_e32 v158, v167, v167
	v_mul_f32_e32 v159, v169, v169
	v_fmac_f32_e32 v158, v166, v166
	v_fmac_f32_e32 v159, v168, v168
	v_add_f32_e32 v158, v158, v159
	v_add_f32_e32 v151, v151, v158
	v_mul_f32_e32 v158, v171, v171
	v_mul_f32_e32 v159, v173, v173
	v_fmac_f32_e32 v158, v170, v170
	v_fmac_f32_e32 v159, v172, v172
	v_add_f32_e32 v158, v158, v159
	v_mul_f32_e32 v159, v174, v174
	v_fmac_f32_e32 v159, v152, v152
	v_mul_f32_e32 v152, v157, v157
	v_fmac_f32_e32 v152, v156, v156
	v_add_f32_e32 v152, v159, v152
	v_add_f32_e32 v152, v158, v152
	v_and_b32_e32 v156, 64, v164
	v_add_f32_e32 v151, v151, v152
	v_xor_b32_e32 v152, 16, v164
	v_add_u32_e32 v156, 64, v156
	v_cmp_lt_i32_e32 vcc, v152, v156
	s_nop 1
	v_cndmask_b32_e32 v152, v164, v152, vcc
	v_lshlrev_b32_e32 v152, 2, v152
	ds_bpermute_b32 v152, v152, v151
	s_waitcnt lgkmcnt(0)
	v_add_f32_e32 v151, v151, v152
	v_xor_b32_e32 v152, 32, v164
	v_cmp_lt_i32_e32 vcc, v152, v156
	s_nop 1
	v_cndmask_b32_e32 v152, v164, v152, vcc
	v_lshlrev_b32_e32 v152, 2, v152
	ds_bpermute_b32 v152, v152, v151
	s_and_saveexec_b64 s[78:79], s[4:5]
	s_cbranch_execz .LBB0_951
	v_lshlrev_b64 v[154:155], 6, v[154:155]
	v_lshl_add_u64 v[154:155], s[18:19], 0, v[154:155]
	v_lshl_add_u64 v[154:155], s[76:77], 2, v[154:155]
	s_lshl_b32 s14, s59, 2
	v_lshl_add_u64 v[154:155], v[154:155], 0, s[14:15]
	s_waitcnt lgkmcnt(0)
	v_add_f32_e32 v151, v151, v152
	global_store_dword v[154:155], v151, off sc1

; __device__ __forceinline__ float dot4(f32x4 v) { return (v[0] * v[0] + v[1] * v[1]) + (v[2] * v[2] + v[3] * v[3]); }
; __device__ __forceinline__ u32x2 pack4(f32x4 v) { u32x2 w; w.x = cvt_pk_bf16(v[0], v[1]); w.y = cvt_pk_bf16(v[2], v[3]); return w; }
; __device__ __forceinline__ f32x2 gelu_pk(f32x2 v) {
;     const f32x2 av = __builtin_elementwise_abs(v), d = av * 0.2316418882f + 1.0f;
;     f32x2 t; t.x = __builtin_amdgcn_rcpf(d.x); t.y = __builtin_amdgcn_rcpf(d.y);
;     f32x2 q = t * 0.5307027145f + (-0.7265760135f); q = q * t + 0.7107068705f; q = q * t + (-0.142248368f); q = q * t + 0.127414796f; q = q * t;
;     const f32x2 s = (v * v) * (-0.72134752044f);
;     f32x2 e; e.x = __builtin_amdgcn_exp2f(s.x); e.y = __builtin_amdgcn_exp2f(s.y);
;     const f32x2 m = v * (q * e), r = v - m;
;     f32x2 o; o.x = v.x < 0.f ? m.x : r.x; o.y = v.y < 0.f ? m.y : r.y; return o;
; }
; __device__ __forceinline__ f32x4 gelu4(f32x4 v) { f32x2 a = gelu_pk((f32x2){v[0], v[1]}), b = gelu_pk((f32x2){v[2], v[3]}); return (f32x4){a.x, a.y, b.x, b.y}; }
; template <int EK>
; __device__ __forceinline__ void epi_tile(const f32x4 (&acc)[2][2][4][2], const Unit& u, int wr, int wc, int fr, int fq, const EpiArgs& E, const LAS float* rt) {
;     ...
;             } else if (EK == EK_GELU) {
;                 const float r = rr[ai][m]; float ss = 0.f;
; #pragma unroll
;                 for (int bj = 0; bj < 2; ++bj) { const int col = u.pn * BM + bj * HALF + wc * 32 + fq * 8;
;                     const f32x4 z0 = gelu4(acc[ai][bj][m][0] * r), z1 = gelu4(acc[ai][bj][m][1] * r); ss += dot4(z0) + dot4(z1);
;                     const u32x2 lo = pack4(z0), hi = pack4(z1);
;                     *(u32x4*)(E.ob + (size_t)row * E.ldb + col) = (u32x4){lo.x, lo.y, hi.x, hi.y}; }
.LBB0_952:
	v_mov_b32_e32 v172, v153
	v_pk_mul_f32 v[156:157], v[38:39], v[172:173] op_sel_hi:[1,0]
	v_pk_mul_f32 v[166:167], v[40:41], v[172:173] op_sel_hi:[1,0]
	v_and_b32_e32 v155, 0x7fffffff, v157
	v_and_b32_e32 v154, 0x7fffffff, v156
	v_pk_fma_f32 v[154:155], v[154:155], s[40:41], 1.0 op_sel_hi:[1,0,0]
	v_pk_mul_f32 v[170:171], v[156:157], v[156:157]
	v_rcp_f32_e32 v158, v154
	v_rcp_f32_e32 v159, v155
	v_mov_b64_e32 v[154:155], s[44:45]
	v_pk_mul_f32 v[170:171], v[170:171], s[58:59] op_sel_hi:[1,0]
	v_and_b32_e32 v175, 0x7fffffff, v167
	v_pk_fma_f32 v[168:169], v[158:159], s[42:43], v[154:155] op_sel_hi:[1,0,0]
	v_exp_f32_e32 v170, v170
	v_pk_fma_f32 v[168:169], v[158:159], v[168:169], s[52:53] op_sel_hi:[1,1,0]
	v_exp_f32_e32 v171, v171
	v_pk_fma_f32 v[168:169], v[158:159], v[168:169], s[54:55] op_sel_hi:[1,1,0]
	v_and_b32_e32 v174, 0x7fffffff, v166
	v_pk_fma_f32 v[168:169], v[158:159], v[168:169], s[56:57] op_sel_hi:[1,1,0]
	v_pk_fma_f32 v[174:175], v[174:175], s[40:41], 1.0 op_sel_hi:[1,0,0]
	v_pk_mul_f32 v[158:159], v[158:159], v[168:169]
	v_rcp_f32_e32 v174, v174
	v_rcp_f32_e32 v175, v175
	v_pk_mul_f32 v[158:159], v[170:171], v[158:159]
	v_cmp_gt_f32_e32 vcc, 0, v156
	v_pk_mul_f32 v[170:171], v[156:157], v[158:159]
	v_pk_fma_f32 v[158:159], v[156:157], v[158:159], v[156:157] neg_lo:[1,0,0] neg_hi:[1,0,0]
	v_pk_mul_f32 v[168:169], v[166:167], v[166:167]
	v_cndmask_b32_e32 v151, v158, v170, vcc
	v_cmp_gt_f32_e32 vcc, 0, v157
	v_pk_mul_f32 v[168:169], v[168:169], s[58:59] op_sel_hi:[1,0]
	s_waitcnt lgkmcnt(0)
	v_add_u32_e32 v152, 0x90, v150
	v_cndmask_b32_e32 v156, v159, v171, vcc
	v_pk_fma_f32 v[158:159], v[174:175], s[42:43], v[154:155] op_sel_hi:[1,0,0]
	v_exp_f32_e32 v168, v168
	v_pk_fma_f32 v[158:159], v[174:175], v[158:159], s[52:53] op_sel_hi:[1,1,0]
	v_exp_f32_e32 v169, v169
	v_pk_fma_f32 v[158:159], v[174:175], v[158:159], s[54:55] op_sel_hi:[1,1,0]
	v_pk_mul_f32 v[170:171], v[34:35], v[172:173] op_sel_hi:[1,0]
	v_pk_fma_f32 v[158:159], v[174:175], v[158:159], s[56:57] op_sel_hi:[1,1,0]
	v_cmp_gt_f32_e32 vcc, 0, v166
	v_pk_mul_f32 v[158:159], v[174:175], v[158:159]
	v_and_b32_e32 v175, 0x7fffffff, v171
	v_and_b32_e32 v174, 0x7fffffff, v170
	v_pk_fma_f32 v[174:175], v[174:175], s[40:41], 1.0 op_sel_hi:[1,0,0]
	v_pk_mul_f32 v[158:159], v[168:169], v[158:159]
	v_rcp_f32_e32 v174, v174
	v_rcp_f32_e32 v175, v175
	v_pk_mul_f32 v[168:169], v[166:167], v[158:159]
	v_pk_fma_f32 v[158:159], v[166:167], v[158:159], v[166:167] neg_lo:[1,0,0] neg_hi:[1,0,0]
	v_pk_mul_f32 v[176:177], v[170:171], v[170:171]
	v_cndmask_b32_e32 v157, v158, v168, vcc
	v_cmp_gt_f32_e32 vcc, 0, v167
	v_pk_mul_f32 v[176:177], v[176:177], s[58:59] op_sel_hi:[1,0]
	v_pk_mul_f32 v[166:167], v[36:37], v[172:173] op_sel_hi:[1,0]
	v_cndmask_b32_e32 v158, v159, v169, vcc
	v_pk_fma_f32 v[168:169], v[174:175], s[42:43], v[154:155] op_sel_hi:[1,0,0]
	v_exp_f32_e32 v176, v176
	v_pk_fma_f32 v[168:169], v[174:175], v[168:169], s[52:53] op_sel_hi:[1,1,0]
	v_exp_f32_e32 v177, v177
	v_pk_fma_f32 v[168:169], v[174:175], v[168:169], s[54:55] op_sel_hi:[1,1,0]
	v_and_b32_e32 v179, 0x7fffffff, v167
	v_and_b32_e32 v178, 0x7fffffff, v166
	v_pk_fma_f32 v[168:169], v[174:175], v[168:169], s[56:57] op_sel_hi:[1,1,0]
	v_pk_fma_f32 v[178:179], v[178:179], s[40:41], 1.0 op_sel_hi:[1,0,0]
	v_pk_mul_f32 v[168:169], v[174:175], v[168:169]
	v_rcp_f32_e32 v178, v178
	v_rcp_f32_e32 v179, v179
	v_pk_mul_f32 v[168:169], v[176:177], v[168:169]
	v_cmp_gt_f32_e32 vcc, 0, v170
	v_pk_mul_f32 v[176:177], v[170:171], v[168:169]
	v_pk_fma_f32 v[168:169], v[170:171], v[168:169], v[170:171] neg_lo:[1,0,0] neg_hi:[1,0,0]
	v_pk_mul_f32 v[174:175], v[166:167], v[166:167]
	v_cndmask_b32_e32 v159, v168, v176, vcc
	v_cmp_gt_f32_e32 vcc, 0, v171
	v_pk_mul_f32 v[170:171], v[174:175], s[58:59] op_sel_hi:[1,0]
	v_ashrrev_i32_e32 v153, 31, v152
	v_cndmask_b32_e32 v165, v169, v177, vcc
	v_pk_fma_f32 v[168:169], v[178:179], s[42:43], v[154:155] op_sel_hi:[1,0,0]
	v_exp_f32_e32 v170, v170
	v_pk_fma_f32 v[168:169], v[178:179], v[168:169], s[52:53] op_sel_hi:[1,1,0]
	v_exp_f32_e32 v171, v171
	v_pk_fma_f32 v[168:169], v[178:179], v[168:169], s[54:55] op_sel_hi:[1,1,0]
	v_pk_mul_f32 v[176:177], v[6:7], v[172:173] op_sel_hi:[1,0]
	v_pk_fma_f32 v[168:169], v[178:179], v[168:169], s[56:57] op_sel_hi:[1,1,0]
	v_cmp_gt_f32_e32 vcc, 0, v166
	v_pk_mul_f32 v[168:169], v[178:179], v[168:169]
	v_and_b32_e32 v179, 0x7fffffff, v177
	v_and_b32_e32 v178, 0x7fffffff, v176
	v_pk_fma_f32 v[178:179], v[178:179], s[40:41], 1.0 op_sel_hi:[1,0,0]
	v_pk_mul_f32 v[168:169], v[170:171], v[168:169]
	v_rcp_f32_e32 v178, v178
	v_rcp_f32_e32 v179, v179
	v_pk_mul_f32 v[170:171], v[166:167], v[168:169]
	v_pk_fma_f32 v[168:169], v[166:167], v[168:169], v[166:167] neg_lo:[1,0,0] neg_hi:[1,0,0]
	v_lshlrev_b64 v[174:175], 12, v[152:153]
	v_cndmask_b32_e32 v166, v168, v170, vcc
	v_cmp_gt_f32_e32 vcc, 0, v167
	v_lshl_add_u64 v[174:175], s[64:65], 0, v[174:175]
	v_cvt_pk_bf16_f32 v168, v151, v156
	v_lshl_add_u64 v[180:181], v[146:147], 1, v[174:175]
	v_cndmask_b32_e32 v167, v169, v171, vcc
	v_cvt_pk_bf16_f32 v169, v157, v158
	v_pk_mul_f32 v[174:175], v[176:177], v[176:177]
	v_cvt_pk_bf16_f32 v170, v159, v165
	v_cvt_pk_bf16_f32 v171, v166, v167
	global_store_dwordx4 v[180:181], v[168:171], off sc1
	v_pk_mul_f32 v[174:175], v[174:175], s[58:59] op_sel_hi:[1,0]
	v_cmp_gt_f32_e32 vcc, 0, v176
	v_pk_fma_f32 v[168:169], v[178:179], s[42:43], v[154:155] op_sel_hi:[1,0,0]
	v_pk_mul_f32 v[170:171], v[8:9], v[172:173] op_sel_hi:[1,0]
	v_pk_fma_f32 v[168:169], v[178:179], v[168:169], s[52:53] op_sel_hi:[1,1,0]
	v_exp_f32_e32 v174, v174
	v_exp_f32_e32 v175, v175
; __device__ __forceinline__ float dot4(f32x4 v) { return (v[0] * v[0] + v[1] * v[1]) + (v[2] * v[2] + v[3] * v[3]); }
; __device__ __forceinline__ u32x2 pack4(f32x4 v) { u32x2 w; w.x = cvt_pk_bf16(v[0], v[1]); w.y = cvt_pk_bf16(v[2], v[3]); return w; }
; __device__ __forceinline__ float quad_sum(float s) { s += __shfl_xor(s, 16); s += __shfl_xor(s, 32); return s; }
; __device__ __forceinline__ f32x4 gelu4(f32x4 v) { f32x2 a = gelu_pk((f32x2){v[0], v[1]}), b = gelu_pk((f32x2){v[2], v[3]}); return (f32x4){a.x, a.y, b.x, b.y}; }
; __device__ __forceinline__ f32x2 gelu_pk(f32x2 v) {
;     const f32x2 av = __builtin_elementwise_abs(v), d = av * 0.2316418882f + 1.0f;
;     f32x2 t; t.x = __builtin_amdgcn_rcpf(d.x); t.y = __builtin_amdgcn_rcpf(d.y);
;     f32x2 q = t * 0.5307027145f + (-0.7265760135f); q = q * t + 0.7107068705f; q = q * t + (-0.142248368f); q = q * t + 0.127414796f; q = q * t;
;     const f32x2 s = (v * v) * (-0.72134752044f);
;     f32x2 e; e.x = __builtin_amdgcn_exp2f(s.x); e.y = __builtin_amdgcn_exp2f(s.y);
;     const f32x2 m = v * (q * e), r = v - m;
;     f32x2 o; o.x = v.x < 0.f ? m.x : r.x; o.y = v.y < 0.f ? m.y : r.y; return o;
; }
; template <int EK>
; __device__ __forceinline__ void epi_tile(const f32x4 (&acc)[2][2][4][2], const Unit& u, int wr, int wc, int fr, int fq, const EpiArgs& E, const LAS float* rt) {
;     ...
;             } else if (EK == EK_GELU) {
;                 const float r = rr[ai][m]; float ss = 0.f;
; #pragma unroll
;                 for (int bj = 0; bj < 2; ++bj) { const int col = u.pn * BM + bj * HALF + wc * 32 + fq * 8;
;                     const f32x4 z0 = gelu4(acc[ai][bj][m][0] * r), z1 = gelu4(acc[ai][bj][m][1] * r); ss += dot4(z0) + dot4(z1);
;                     const u32x2 lo = pack4(z0), hi = pack4(z1);
;                     *(u32x4*)(E.ob + (size_t)row * E.ldb + col) = (u32x4){lo.x, lo.y, hi.x, hi.y}; }
;                 if (u.pn >= 4) { ss = quad_sum(ss); if (fq == 0) E.stOut[(size_t)row * 16 + (u.pn - 4) * 4 + wc] = ss; }
	v_pk_fma_f32 v[168:169], v[178:179], v[168:169], s[54:55] op_sel_hi:[1,1,0]
	v_and_b32_e32 v183, 0x7fffffff, v171
	v_and_b32_e32 v182, 0x7fffffff, v170
	v_pk_fma_f32 v[168:169], v[178:179], v[168:169], s[56:57] op_sel_hi:[1,1,0]
	v_pk_fma_f32 v[182:183], v[182:183], s[40:41], 1.0 op_sel_hi:[1,0,0]
	v_pk_mul_f32 v[168:169], v[178:179], v[168:169]
	v_rcp_f32_e32 v182, v182
	v_rcp_f32_e32 v183, v183
	v_pk_mul_f32 v[168:169], v[174:175], v[168:169]
	v_pk_mul_f32 v[178:179], v[170:171], v[170:171]
	v_pk_mul_f32 v[174:175], v[176:177], v[168:169]
	v_pk_fma_f32 v[168:169], v[176:177], v[168:169], v[176:177] neg_lo:[1,0,0] neg_hi:[1,0,0]
	s_nop 0
	v_cndmask_b32_e32 v168, v168, v174, vcc
	v_cmp_gt_f32_e32 vcc, 0, v177
	v_pk_mul_f32 v[176:177], v[178:179], s[58:59] op_sel_hi:[1,0]
	v_pk_mul_f32 v[178:179], v[2:3], v[172:173] op_sel_hi:[1,0]
	v_cndmask_b32_e32 v169, v169, v175, vcc
	v_pk_fma_f32 v[174:175], v[182:183], s[42:43], v[154:155] op_sel_hi:[1,0,0]
	v_exp_f32_e32 v176, v176
	v_pk_fma_f32 v[174:175], v[182:183], v[174:175], s[52:53] op_sel_hi:[1,1,0]
	v_exp_f32_e32 v177, v177
	v_pk_fma_f32 v[174:175], v[182:183], v[174:175], s[54:55] op_sel_hi:[1,1,0]
	v_cmp_gt_f32_e32 vcc, 0, v170
	v_pk_fma_f32 v[174:175], v[182:183], v[174:175], s[56:57] op_sel_hi:[1,1,0]
	s_nop 0
	v_pk_mul_f32 v[174:175], v[182:183], v[174:175]
	v_and_b32_e32 v183, 0x7fffffff, v179
	v_and_b32_e32 v182, 0x7fffffff, v178
	v_pk_fma_f32 v[182:183], v[182:183], s[40:41], 1.0 op_sel_hi:[1,0,0]
	v_pk_mul_f32 v[174:175], v[176:177], v[174:175]
	v_rcp_f32_e32 v182, v182
	v_rcp_f32_e32 v183, v183
	v_pk_mul_f32 v[176:177], v[170:171], v[174:175]
	v_pk_fma_f32 v[174:175], v[170:171], v[174:175], v[170:171] neg_lo:[1,0,0] neg_hi:[1,0,0]
	s_nop 0
	v_cndmask_b32_e32 v170, v174, v176, vcc
	v_cmp_gt_f32_e32 vcc, 0, v171
	s_nop 1
	v_cndmask_b32_e32 v171, v175, v177, vcc
	v_pk_mul_f32 v[176:177], v[178:179], v[178:179]
	v_pk_mul_f32 v[174:175], v[4:5], v[172:173] op_sel_hi:[1,0]
	v_pk_fma_f32 v[172:173], v[182:183], s[42:43], v[154:155] op_sel_hi:[1,0,0]
	v_pk_mul_f32 v[176:177], v[176:177], s[58:59] op_sel_hi:[1,0]
	v_pk_fma_f32 v[172:173], v[182:183], v[172:173], s[52:53] op_sel_hi:[1,1,0]
	v_exp_f32_e32 v176, v176
	v_exp_f32_e32 v177, v177
	v_pk_fma_f32 v[172:173], v[182:183], v[172:173], s[54:55] op_sel_hi:[1,1,0]
	v_and_b32_e32 v185, 0x7fffffff, v175
	v_and_b32_e32 v184, 0x7fffffff, v174
	v_pk_fma_f32 v[172:173], v[182:183], v[172:173], s[56:57] op_sel_hi:[1,1,0]
	v_pk_fma_f32 v[184:185], v[184:185], s[40:41], 1.0 op_sel_hi:[1,0,0]
	v_pk_mul_f32 v[172:173], v[182:183], v[172:173]
	v_rcp_f32_e32 v184, v184
	v_rcp_f32_e32 v185, v185
	v_pk_mul_f32 v[172:173], v[176:177], v[172:173]
	v_cmp_gt_f32_e32 vcc, 0, v178
	v_pk_mul_f32 v[176:177], v[178:179], v[172:173]
	v_pk_fma_f32 v[172:173], v[178:179], v[172:173], v[178:179] neg_lo:[1,0,0] neg_hi:[1,0,0]
	v_pk_mul_f32 v[182:183], v[174:175], v[174:175]
	v_cndmask_b32_e32 v172, v172, v176, vcc
	v_cmp_gt_f32_e32 vcc, 0, v179
	v_pk_fma_f32 v[154:155], v[184:185], s[42:43], v[154:155] op_sel_hi:[1,0,0]
	s_nop 0
	v_cndmask_b32_e32 v173, v173, v177, vcc
	v_pk_mul_f32 v[176:177], v[182:183], s[58:59] op_sel_hi:[1,0]
	v_pk_fma_f32 v[154:155], v[184:185], v[154:155], s[52:53] op_sel_hi:[1,1,0]
	v_exp_f32_e32 v176, v176
	v_exp_f32_e32 v177, v177
	v_pk_fma_f32 v[154:155], v[184:185], v[154:155], s[54:55] op_sel_hi:[1,1,0]
	v_cmp_gt_f32_e32 vcc, 0, v174
	v_pk_fma_f32 v[154:155], v[184:185], v[154:155], s[56:57] op_sel_hi:[1,1,0]
	s_nop 0
	v_pk_mul_f32 v[154:155], v[184:185], v[154:155]
	s_nop 0
	v_pk_mul_f32 v[154:155], v[176:177], v[154:155]
	s_nop 0
	v_pk_mul_f32 v[176:177], v[174:175], v[154:155]
	v_pk_fma_f32 v[154:155], v[174:175], v[154:155], v[174:175] neg_lo:[1,0,0] neg_hi:[1,0,0]
	v_cvt_pk_bf16_f32 v174, v168, v169
	s_nop 0
	v_cndmask_b32_e32 v154, v154, v176, vcc
	v_cmp_gt_f32_e32 vcc, 0, v175
	v_cvt_pk_bf16_f32 v175, v170, v171
	v_cvt_pk_bf16_f32 v176, v172, v173
	s_nop 1
	v_cndmask_b32_e32 v155, v155, v177, vcc
	s_and_b64 vcc, exec, s[10:11]
	v_cvt_pk_bf16_f32 v177, v154, v155
	global_store_dwordx4 v[180:181], v[174:177], off offset:256 sc1
	s_cbranch_vccnz .LBB0_956
	v_mul_f32_e32 v156, v156, v156
	v_fmac_f32_e32 v156, v151, v151
	v_mul_f32_e32 v151, v158, v158
	v_fmac_f32_e32 v151, v157, v157
	v_add_f32_e32 v151, v156, v151
	v_mul_f32_e32 v156, v165, v165
	v_mul_f32_e32 v157, v167, v167
	v_fmac_f32_e32 v156, v159, v159
	v_fmac_f32_e32 v157, v166, v166
	v_add_f32_e32 v156, v156, v157
	v_add_f32_e32 v151, v151, v156
	v_mul_f32_e32 v156, v169, v169
	v_mul_f32_e32 v157, v171, v171
	v_fmac_f32_e32 v156, v168, v168
	v_fmac_f32_e32 v157, v170, v170
	v_add_f32_e32 v156, v156, v157
	v_mul_f32_e32 v157, v173, v173
	v_mul_f32_e32 v155, v155, v155
	v_fmac_f32_e32 v157, v172, v172
	v_fmac_f32_e32 v155, v154, v154
	v_add_f32_e32 v154, v157, v155
	v_add_f32_e32 v154, v156, v154
	v_and_b32_e32 v155, 64, v164
	v_add_f32_e32 v151, v151, v154
	v_xor_b32_e32 v154, 16, v164
	v_add_u32_e32 v155, 64, v155
	v_cmp_lt_i32_e32 vcc, v154, v155
	s_nop 1
	v_cndmask_b32_e32 v154, v164, v154, vcc
	v_lshlrev_b32_e32 v154, 2, v154
	ds_bpermute_b32 v154, v154, v151
	s_waitcnt lgkmcnt(0)
	v_add_f32_e32 v151, v151, v154
	v_xor_b32_e32 v154, 32, v164
	v_cmp_lt_i32_e32 vcc, v154, v155
	s_nop 1
	v_cndmask_b32_e32 v154, v164, v154, vcc
	v_lshlrev_b32_e32 v154, 2, v154
	ds_bpermute_b32 v154, v154, v151
	s_and_saveexec_b64 s[78:79], s[4:5]
	s_cbranch_execz .LBB0_955
	v_lshlrev_b64 v[152:153], 6, v[152:153]
	v_lshl_add_u64 v[152:153], s[18:19], 0, v[152:153]
	v_lshl_add_u64 v[152:153], s[76:77], 2, v[152:153]
	s_lshl_b32 s14, s59, 2
	v_lshl_add_u64 v[152:153], v[152:153], 0, s[14:15]
	s_waitcnt lgkmcnt(0)
	v_add_f32_e32 v151, v151, v154
	global_store_dword v[152:153], v151, off sc1

; __device__ __forceinline__ float dot4(f32x4 v) { return (v[0] * v[0] + v[1] * v[1]) + (v[2] * v[2] + v[3] * v[3]); }
; __device__ __forceinline__ u32x2 pack4(f32x4 v) { u32x2 w; w.x = cvt_pk_bf16(v[0], v[1]); w.y = cvt_pk_bf16(v[2], v[3]); return w; }
; __device__ __forceinline__ float quad_sum(float s) { s += __shfl_xor(s, 16); s += __shfl_xor(s, 32); return s; }
; __device__ __forceinline__ f32x4 gelu4(f32x4 v) { f32x2 a = gelu_pk((f32x2){v[0], v[1]}), b = gelu_pk((f32x2){v[2], v[3]}); return (f32x4){a.x, a.y, b.x, b.y}; }
; __device__ __forceinline__ f32x2 gelu_pk(f32x2 v) {
;     const f32x2 av = __builtin_elementwise_abs(v), d = av * 0.2316418882f + 1.0f;
;     f32x2 t; t.x = __builtin_amdgcn_rcpf(d.x); t.y = __builtin_amdgcn_rcpf(d.y);
;     f32x2 q = t * 0.5307027145f + (-0.7265760135f); q = q * t + 0.7107068705f; q = q * t + (-0.142248368f); q = q * t + 0.127414796f; q = q * t;
;     const f32x2 s = (v * v) * (-0.72134752044f);
;     f32x2 e; e.x = __builtin_amdgcn_exp2f(s.x); e.y = __builtin_amdgcn_exp2f(s.y);
;     const f32x2 m = v * (q * e), r = v - m;
;     f32x2 o; o.x = v.x < 0.f ? m.x : r.x; o.y = v.y < 0.f ? m.y : r.y; return o;
; }
; template <int EK>
; __device__ __forceinline__ void epi_tile(const f32x4 (&acc)[2][2][4][2], const Unit& u, int wr, int wc, int fr, int fq, const EpiArgs& E, const LAS float* rt) {
;     ...
;             } else if (EK == EK_GELU) {
;                 const float r = rr[ai][m]; float ss = 0.f;
; #pragma unroll
;                 for (int bj = 0; bj < 2; ++bj) { const int col = u.pn * BM + bj * HALF + wc * 32 + fq * 8;
;                     const f32x4 z0 = gelu4(acc[ai][bj][m][0] * r), z1 = gelu4(acc[ai][bj][m][1] * r); ss += dot4(z0) + dot4(z1);
;                     const u32x2 lo = pack4(z0), hi = pack4(z1);
;                     *(u32x4*)(E.ob + (size_t)row * E.ldb + col) = (u32x4){lo.x, lo.y, hi.x, hi.y}; }
;                 if (u.pn >= 4) { ss = quad_sum(ss); if (fq == 0) E.stOut[(size_t)row * 16 + (u.pn - 4) * 4 + wc] = ss; }
.LBB0_956:
	v_pk_mul_f32 v[156:157], v[30:31], v[148:149] op_sel_hi:[1,0]
	v_pk_mul_f32 v[166:167], v[32:33], v[148:149] op_sel_hi:[1,0]
	v_and_b32_e32 v155, 0x7fffffff, v157
	s_waitcnt lgkmcnt(0)
	v_and_b32_e32 v154, 0x7fffffff, v156
	v_pk_fma_f32 v[154:155], v[154:155], s[40:41], 1.0 op_sel_hi:[1,0,0]
	v_pk_mul_f32 v[170:171], v[156:157], v[156:157]
	v_rcp_f32_e32 v158, v154
	v_rcp_f32_e32 v159, v155
	v_mov_b64_e32 v[154:155], s[44:45]
	v_pk_mul_f32 v[170:171], v[170:171], s[58:59] op_sel_hi:[1,0]
	v_and_b32_e32 v173, 0x7fffffff, v167
	v_pk_fma_f32 v[168:169], v[158:159], s[42:43], v[154:155] op_sel_hi:[1,0,0]
	v_exp_f32_e32 v170, v170
	v_pk_fma_f32 v[168:169], v[158:159], v[168:169], s[52:53] op_sel_hi:[1,1,0]
	v_exp_f32_e32 v171, v171
	v_pk_fma_f32 v[168:169], v[158:159], v[168:169], s[54:55] op_sel_hi:[1,1,0]
	v_and_b32_e32 v172, 0x7fffffff, v166
	v_pk_fma_f32 v[168:169], v[158:159], v[168:169], s[56:57] op_sel_hi:[1,1,0]
	v_pk_fma_f32 v[172:173], v[172:173], s[40:41], 1.0 op_sel_hi:[1,0,0]
	v_pk_mul_f32 v[158:159], v[158:159], v[168:169]
	v_rcp_f32_e32 v172, v172
	v_rcp_f32_e32 v173, v173
	v_pk_mul_f32 v[158:159], v[170:171], v[158:159]
	v_cmp_gt_f32_e32 vcc, 0, v156
	v_pk_mul_f32 v[170:171], v[156:157], v[158:159]
	v_pk_fma_f32 v[158:159], v[156:157], v[158:159], v[156:157] neg_lo:[1,0,0] neg_hi:[1,0,0]
	v_pk_mul_f32 v[168:169], v[166:167], v[166:167]
	v_cndmask_b32_e32 v151, v158, v170, vcc
	v_cmp_gt_f32_e32 vcc, 0, v157
	v_pk_mul_f32 v[168:169], v[168:169], s[58:59] op_sel_hi:[1,0]
	v_add_u32_e32 v152, 0xa0, v150
	v_cndmask_b32_e32 v156, v159, v171, vcc
	v_pk_fma_f32 v[158:159], v[172:173], s[42:43], v[154:155] op_sel_hi:[1,0,0]
	v_exp_f32_e32 v168, v168
	v_pk_fma_f32 v[158:159], v[172:173], v[158:159], s[52:53] op_sel_hi:[1,1,0]
	v_exp_f32_e32 v169, v169
	v_pk_fma_f32 v[158:159], v[172:173], v[158:159], s[54:55] op_sel_hi:[1,1,0]
	v_pk_mul_f32 v[170:171], v[26:27], v[148:149] op_sel_hi:[1,0]
	v_pk_fma_f32 v[158:159], v[172:173], v[158:159], s[56:57] op_sel_hi:[1,1,0]
	v_cmp_gt_f32_e32 vcc, 0, v166
	v_pk_mul_f32 v[158:159], v[172:173], v[158:159]
	v_and_b32_e32 v173, 0x7fffffff, v171
	v_and_b32_e32 v172, 0x7fffffff, v170
	v_pk_fma_f32 v[172:173], v[172:173], s[40:41], 1.0 op_sel_hi:[1,0,0]
	v_pk_mul_f32 v[158:159], v[168:169], v[158:159]
	v_rcp_f32_e32 v172, v172
	v_rcp_f32_e32 v173, v173
	v_pk_mul_f32 v[168:169], v[166:167], v[158:159]
	v_pk_fma_f32 v[158:159], v[166:167], v[158:159], v[166:167] neg_lo:[1,0,0] neg_hi:[1,0,0]
	v_pk_mul_f32 v[174:175], v[170:171], v[170:171]
	v_cndmask_b32_e32 v157, v158, v168, vcc
	v_cmp_gt_f32_e32 vcc, 0, v167
	v_pk_mul_f32 v[174:175], v[174:175], s[58:59] op_sel_hi:[1,0]
	v_pk_mul_f32 v[166:167], v[28:29], v[148:149] op_sel_hi:[1,0]
	v_cndmask_b32_e32 v158, v159, v169, vcc
	v_pk_fma_f32 v[168:169], v[172:173], s[42:43], v[154:155] op_sel_hi:[1,0,0]
	v_exp_f32_e32 v174, v174
	v_pk_fma_f32 v[168:169], v[172:173], v[168:169], s[52:53] op_sel_hi:[1,1,0]
	v_exp_f32_e32 v175, v175
	v_pk_fma_f32 v[168:169], v[172:173], v[168:169], s[54:55] op_sel_hi:[1,1,0]
	v_and_b32_e32 v177, 0x7fffffff, v167
	v_and_b32_e32 v176, 0x7fffffff, v166
	v_pk_fma_f32 v[168:169], v[172:173], v[168:169], s[56:57] op_sel_hi:[1,1,0]
	v_pk_fma_f32 v[176:177], v[176:177], s[40:41], 1.0 op_sel_hi:[1,0,0]
	v_pk_mul_f32 v[168:169], v[172:173], v[168:169]
	v_rcp_f32_e32 v176, v176
	v_rcp_f32_e32 v177, v177
	v_pk_mul_f32 v[168:169], v[174:175], v[168:169]
	v_cmp_gt_f32_e32 vcc, 0, v170
	v_pk_mul_f32 v[174:175], v[170:171], v[168:169]
	v_pk_fma_f32 v[168:169], v[170:171], v[168:169], v[170:171] neg_lo:[1,0,0] neg_hi:[1,0,0]
	v_pk_mul_f32 v[172:173], v[166:167], v[166:167]
	v_cndmask_b32_e32 v159, v168, v174, vcc
	v_cmp_gt_f32_e32 vcc, 0, v171
	v_pk_mul_f32 v[170:171], v[172:173], s[58:59] op_sel_hi:[1,0]
	v_ashrrev_i32_e32 v153, 31, v152
	v_cndmask_b32_e32 v165, v169, v175, vcc
	v_pk_fma_f32 v[168:169], v[176:177], s[42:43], v[154:155] op_sel_hi:[1,0,0]
	v_exp_f32_e32 v170, v170
	v_pk_fma_f32 v[168:169], v[176:177], v[168:169], s[52:53] op_sel_hi:[1,1,0]
	v_exp_f32_e32 v171, v171
	v_pk_fma_f32 v[168:169], v[176:177], v[168:169], s[54:55] op_sel_hi:[1,1,0]
	v_pk_mul_f32 v[174:175], v[114:115], v[148:149] op_sel_hi:[1,0]
	v_pk_fma_f32 v[168:169], v[176:177], v[168:169], s[56:57] op_sel_hi:[1,1,0]
	v_cmp_gt_f32_e32 vcc, 0, v166
	v_pk_mul_f32 v[168:169], v[176:177], v[168:169]
	v_and_b32_e32 v177, 0x7fffffff, v175
	v_and_b32_e32 v176, 0x7fffffff, v174
	v_pk_fma_f32 v[176:177], v[176:177], s[40:41], 1.0 op_sel_hi:[1,0,0]
	v_pk_mul_f32 v[168:169], v[170:171], v[168:169]
	v_rcp_f32_e32 v176, v176
	v_rcp_f32_e32 v177, v177
	v_pk_mul_f32 v[170:171], v[166:167], v[168:169]
	v_pk_fma_f32 v[168:169], v[166:167], v[168:169], v[166:167] neg_lo:[1,0,0] neg_hi:[1,0,0]
	v_lshlrev_b64 v[172:173], 12, v[152:153]
	v_cndmask_b32_e32 v166, v168, v170, vcc
	v_cmp_gt_f32_e32 vcc, 0, v167
	v_lshl_add_u64 v[172:173], s[64:65], 0, v[172:173]
	v_cvt_pk_bf16_f32 v168, v151, v156
	v_lshl_add_u64 v[178:179], v[146:147], 1, v[172:173]
	v_cndmask_b32_e32 v167, v169, v171, vcc
	v_cvt_pk_bf16_f32 v169, v157, v158
	v_pk_mul_f32 v[172:173], v[174:175], v[174:175]
	v_cvt_pk_bf16_f32 v170, v159, v165
	v_cvt_pk_bf16_f32 v171, v166, v167
	global_store_dwordx4 v[178:179], v[168:171], off sc1
	v_pk_mul_f32 v[172:173], v[172:173], s[58:59] op_sel_hi:[1,0]
	v_cmp_gt_f32_e32 vcc, 0, v174
	v_pk_fma_f32 v[168:169], v[176:177], s[42:43], v[154:155] op_sel_hi:[1,0,0]
	v_pk_mul_f32 v[170:171], v[116:117], v[148:149] op_sel_hi:[1,0]
	v_pk_fma_f32 v[168:169], v[176:177], v[168:169], s[52:53] op_sel_hi:[1,1,0]
	v_exp_f32_e32 v172, v172
	v_exp_f32_e32 v173, v173
; __device__ __forceinline__ float dot4(f32x4 v) { return (v[0] * v[0] + v[1] * v[1]) + (v[2] * v[2] + v[3] * v[3]); }
; __device__ __forceinline__ u32x2 pack4(f32x4 v) { u32x2 w; w.x = cvt_pk_bf16(v[0], v[1]); w.y = cvt_pk_bf16(v[2], v[3]); return w; }
; __device__ __forceinline__ float quad_sum(float s) { s += __shfl_xor(s, 16); s += __shfl_xor(s, 32); return s; }
; __device__ __forceinline__ f32x4 gelu4(f32x4 v) { f32x2 a = gelu_pk((f32x2){v[0], v[1]}), b = gelu_pk((f32x2){v[2], v[3]}); return (f32x4){a.x, a.y, b.x, b.y}; }
; __device__ __forceinline__ f32x2 gelu_pk(f32x2 v) {
;     const f32x2 av = __builtin_elementwise_abs(v), d = av * 0.2316418882f + 1.0f;
;     f32x2 t; t.x = __builtin_amdgcn_rcpf(d.x); t.y = __builtin_amdgcn_rcpf(d.y);
;     f32x2 q = t * 0.5307027145f + (-0.7265760135f); q = q * t + 0.7107068705f; q = q * t + (-0.142248368f); q = q * t + 0.127414796f; q = q * t;
;     const f32x2 s = (v * v) * (-0.72134752044f);
;     f32x2 e; e.x = __builtin_amdgcn_exp2f(s.x); e.y = __builtin_amdgcn_exp2f(s.y);
;     const f32x2 m = v * (q * e), r = v - m;
;     f32x2 o; o.x = v.x < 0.f ? m.x : r.x; o.y = v.y < 0.f ? m.y : r.y; return o;
; }
; template <int EK>
; __device__ __forceinline__ void epi_tile(const f32x4 (&acc)[2][2][4][2], const Unit& u, int wr, int wc, int fr, int fq, const EpiArgs& E, const LAS float* rt) {
;     ...
;             } else if (EK == EK_GELU) {
;                 const float r = rr[ai][m]; float ss = 0.f;
; #pragma unroll
;                 for (int bj = 0; bj < 2; ++bj) { const int col = u.pn * BM + bj * HALF + wc * 32 + fq * 8;
;                     const f32x4 z0 = gelu4(acc[ai][bj][m][0] * r), z1 = gelu4(acc[ai][bj][m][1] * r); ss += dot4(z0) + dot4(z1);
;                     const u32x2 lo = pack4(z0), hi = pack4(z1);
;                     *(u32x4*)(E.ob + (size_t)row * E.ldb + col) = (u32x4){lo.x, lo.y, hi.x, hi.y}; }
;                 if (u.pn >= 4) { ss = quad_sum(ss); if (fq == 0) E.stOut[(size_t)row * 16 + (u.pn - 4) * 4 + wc] = ss; }
	v_pk_fma_f32 v[168:169], v[176:177], v[168:169], s[54:55] op_sel_hi:[1,1,0]
	v_and_b32_e32 v181, 0x7fffffff, v171
	v_and_b32_e32 v180, 0x7fffffff, v170
	v_pk_fma_f32 v[168:169], v[176:177], v[168:169], s[56:57] op_sel_hi:[1,1,0]
	v_pk_fma_f32 v[180:181], v[180:181], s[40:41], 1.0 op_sel_hi:[1,0,0]
	v_pk_mul_f32 v[168:169], v[176:177], v[168:169]
	v_rcp_f32_e32 v180, v180
	v_rcp_f32_e32 v181, v181
	v_pk_mul_f32 v[168:169], v[172:173], v[168:169]
	v_pk_mul_f32 v[176:177], v[170:171], v[170:171]
	v_pk_mul_f32 v[172:173], v[174:175], v[168:169]
	v_pk_fma_f32 v[168:169], v[174:175], v[168:169], v[174:175] neg_lo:[1,0,0] neg_hi:[1,0,0]
	s_nop 0
	v_cndmask_b32_e32 v168, v168, v172, vcc
	v_cmp_gt_f32_e32 vcc, 0, v175
	v_pk_mul_f32 v[174:175], v[176:177], s[58:59] op_sel_hi:[1,0]
	v_pk_mul_f32 v[176:177], v[118:119], v[148:149] op_sel_hi:[1,0]
	v_cndmask_b32_e32 v169, v169, v173, vcc
	v_pk_fma_f32 v[172:173], v[180:181], s[42:43], v[154:155] op_sel_hi:[1,0,0]
	v_exp_f32_e32 v174, v174
	v_pk_fma_f32 v[172:173], v[180:181], v[172:173], s[52:53] op_sel_hi:[1,1,0]
	v_exp_f32_e32 v175, v175
	v_pk_fma_f32 v[172:173], v[180:181], v[172:173], s[54:55] op_sel_hi:[1,1,0]
	v_cmp_gt_f32_e32 vcc, 0, v170
	v_pk_fma_f32 v[172:173], v[180:181], v[172:173], s[56:57] op_sel_hi:[1,1,0]
	v_pk_mul_f32 v[182:183], v[176:177], v[176:177]
	v_pk_mul_f32 v[172:173], v[180:181], v[172:173]
	v_and_b32_e32 v181, 0x7fffffff, v177
	v_and_b32_e32 v180, 0x7fffffff, v176
	v_pk_fma_f32 v[180:181], v[180:181], s[40:41], 1.0 op_sel_hi:[1,0,0]
	v_pk_mul_f32 v[172:173], v[174:175], v[172:173]
	v_rcp_f32_e32 v180, v180
	v_rcp_f32_e32 v181, v181
	v_pk_mul_f32 v[174:175], v[170:171], v[172:173]
	v_pk_fma_f32 v[172:173], v[170:171], v[172:173], v[170:171] neg_lo:[1,0,0] neg_hi:[1,0,0]
	v_pk_mul_f32 v[182:183], v[182:183], s[58:59] op_sel_hi:[1,0]
	v_cndmask_b32_e32 v170, v172, v174, vcc
	v_cmp_gt_f32_e32 vcc, 0, v171
	v_exp_f32_e32 v182, v182
	v_exp_f32_e32 v183, v183
	v_cndmask_b32_e32 v171, v173, v175, vcc
	v_pk_mul_f32 v[174:175], v[120:121], v[148:149] op_sel_hi:[1,0]
	v_pk_fma_f32 v[172:173], v[180:181], s[42:43], v[154:155] op_sel_hi:[1,0,0]
	v_and_b32_e32 v185, 0x7fffffff, v175
	v_pk_fma_f32 v[172:173], v[180:181], v[172:173], s[52:53] op_sel_hi:[1,1,0]
	v_and_b32_e32 v184, 0x7fffffff, v174
	v_pk_fma_f32 v[172:173], v[180:181], v[172:173], s[54:55] op_sel_hi:[1,1,0]
	v_pk_fma_f32 v[184:185], v[184:185], s[40:41], 1.0 op_sel_hi:[1,0,0]
	v_pk_fma_f32 v[172:173], v[180:181], v[172:173], s[56:57] op_sel_hi:[1,1,0]
	v_rcp_f32_e32 v184, v184
	v_rcp_f32_e32 v185, v185
	v_pk_mul_f32 v[172:173], v[180:181], v[172:173]
	v_pk_mul_f32 v[180:181], v[174:175], v[174:175]
	v_pk_mul_f32 v[172:173], v[182:183], v[172:173]
	v_cmp_gt_f32_e32 vcc, 0, v176
	v_pk_mul_f32 v[182:183], v[176:177], v[172:173]
	v_pk_fma_f32 v[172:173], v[176:177], v[172:173], v[176:177] neg_lo:[1,0,0] neg_hi:[1,0,0]
	v_pk_fma_f32 v[154:155], v[184:185], s[42:43], v[154:155] op_sel_hi:[1,0,0]
	v_cndmask_b32_e32 v148, v172, v182, vcc
	v_cmp_gt_f32_e32 vcc, 0, v177
	v_pk_mul_f32 v[176:177], v[180:181], s[58:59] op_sel_hi:[1,0]
	v_pk_fma_f32 v[154:155], v[184:185], v[154:155], s[52:53] op_sel_hi:[1,1,0]
	v_exp_f32_e32 v176, v176
	v_exp_f32_e32 v177, v177
	v_pk_fma_f32 v[154:155], v[184:185], v[154:155], s[54:55] op_sel_hi:[1,1,0]
	v_cndmask_b32_e32 v172, v173, v183, vcc
	v_pk_fma_f32 v[154:155], v[184:185], v[154:155], s[56:57] op_sel_hi:[1,1,0]
	v_cmp_gt_f32_e32 vcc, 0, v174
	v_pk_mul_f32 v[154:155], v[184:185], v[154:155]
	s_nop 0
	v_pk_mul_f32 v[154:155], v[176:177], v[154:155]
	s_nop 0
	v_pk_mul_f32 v[176:177], v[174:175], v[154:155]
	v_pk_fma_f32 v[154:155], v[174:175], v[154:155], v[174:175] neg_lo:[1,0,0] neg_hi:[1,0,0]
	v_cvt_pk_bf16_f32 v174, v168, v169
	s_nop 0
	v_cndmask_b32_e32 v154, v154, v176, vcc
	v_cmp_gt_f32_e32 vcc, 0, v175
	v_cvt_pk_bf16_f32 v175, v170, v171
	v_cvt_pk_bf16_f32 v176, v148, v172
	s_nop 1
	v_cndmask_b32_e32 v155, v155, v177, vcc
	s_and_b64 vcc, exec, s[10:11]
	v_cvt_pk_bf16_f32 v177, v154, v155
	global_store_dwordx4 v[178:179], v[174:177], off offset:256 sc1
	s_cbranch_vccnz .LBB0_960
	v_mul_f32_e32 v156, v156, v156
	v_fmac_f32_e32 v156, v151, v151
	v_mul_f32_e32 v151, v158, v158
	v_fmac_f32_e32 v151, v157, v157
	v_add_f32_e32 v151, v156, v151
	v_mul_f32_e32 v156, v165, v165
	v_mul_f32_e32 v157, v167, v167
	v_fmac_f32_e32 v156, v159, v159
	v_fmac_f32_e32 v157, v166, v166
	v_add_f32_e32 v156, v156, v157
	v_add_f32_e32 v151, v151, v156
	v_mul_f32_e32 v156, v169, v169
	v_mul_f32_e32 v157, v171, v171
	v_fmac_f32_e32 v156, v168, v168
	v_fmac_f32_e32 v157, v170, v170
	v_add_f32_e32 v156, v156, v157
	v_mul_f32_e32 v157, v172, v172
	v_fmac_f32_e32 v157, v148, v148
	v_mul_f32_e32 v148, v155, v155
	v_fmac_f32_e32 v148, v154, v154
	v_add_f32_e32 v148, v157, v148
	v_add_f32_e32 v148, v156, v148
	v_and_b32_e32 v154, 64, v164
	v_add_f32_e32 v148, v151, v148
	v_xor_b32_e32 v151, 16, v164
	v_add_u32_e32 v154, 64, v154
	v_cmp_lt_i32_e32 vcc, v151, v154
	s_nop 1
	v_cndmask_b32_e32 v151, v164, v151, vcc
	v_lshlrev_b32_e32 v151, 2, v151
	ds_bpermute_b32 v151, v151, v148
	s_waitcnt lgkmcnt(0)
	v_add_f32_e32 v148, v148, v151
	v_xor_b32_e32 v151, 32, v164
	v_cmp_lt_i32_e32 vcc, v151, v154
	s_nop 1
	v_cndmask_b32_e32 v151, v164, v151, vcc
	v_lshlrev_b32_e32 v151, 2, v151
	ds_bpermute_b32 v151, v151, v148
	s_and_saveexec_b64 s[78:79], s[4:5]
	s_cbranch_execz .LBB0_959
	v_lshlrev_b64 v[152:153], 6, v[152:153]
	v_lshl_add_u64 v[152:153], s[18:19], 0, v[152:153]
	v_lshl_add_u64 v[152:153], s[76:77], 2, v[152:153]
	s_lshl_b32 s14, s59, 2
	v_lshl_add_u64 v[152:153], v[152:153], 0, s[14:15]
	s_waitcnt lgkmcnt(0)
	v_add_f32_e32 v148, v148, v151
	global_store_dword v[152:153], v148, off sc1

; __device__ __forceinline__ float dot4(f32x4 v) { return (v[0] * v[0] + v[1] * v[1]) + (v[2] * v[2] + v[3] * v[3]); }
; __device__ __forceinline__ u32x2 pack4(f32x4 v) { u32x2 w; w.x = cvt_pk_bf16(v[0], v[1]); w.y = cvt_pk_bf16(v[2], v[3]); return w; }
; __device__ __forceinline__ float quad_sum(float s) { s += __shfl_xor(s, 16); s += __shfl_xor(s, 32); return s; }
; __device__ __forceinline__ f32x4 gelu4(f32x4 v) { f32x2 a = gelu_pk((f32x2){v[0], v[1]}), b = gelu_pk((f32x2){v[2], v[3]}); return (f32x4){a.x, a.y, b.x, b.y}; }
; __device__ __forceinline__ f32x2 gelu_pk(f32x2 v) {
;     const f32x2 av = __builtin_elementwise_abs(v), d = av * 0.2316418882f + 1.0f;
;     f32x2 t; t.x = __builtin_amdgcn_rcpf(d.x); t.y = __builtin_amdgcn_rcpf(d.y);
;     f32x2 q = t * 0.5307027145f + (-0.7265760135f); q = q * t + 0.7107068705f; q = q * t + (-0.142248368f); q = q * t + 0.127414796f; q = q * t;
;     const f32x2 s = (v * v) * (-0.72134752044f);
;     f32x2 e; e.x = __builtin_amdgcn_exp2f(s.x); e.y = __builtin_amdgcn_exp2f(s.y);
;     const f32x2 m = v * (q * e), r = v - m;
;     f32x2 o; o.x = v.x < 0.f ? m.x : r.x; o.y = v.y < 0.f ? m.y : r.y; return o;
; }
; template <int EK>
; __device__ __forceinline__ void epi_tile(const f32x4 (&acc)[2][2][4][2], const Unit& u, int wr, int wc, int fr, int fq, const EpiArgs& E, const LAS float* rt) {
;     ...
;             } else if (EK == EK_GELU) {
;                 const float r = rr[ai][m]; float ss = 0.f;
; #pragma unroll
;                 for (int bj = 0; bj < 2; ++bj) { const int col = u.pn * BM + bj * HALF + wc * 32 + fq * 8;
;                     const f32x4 z0 = gelu4(acc[ai][bj][m][0] * r), z1 = gelu4(acc[ai][bj][m][1] * r); ss += dot4(z0) + dot4(z1);
;                     const u32x2 lo = pack4(z0), hi = pack4(z1);
;                     *(u32x4*)(E.ob + (size_t)row * E.ldb + col) = (u32x4){lo.x, lo.y, hi.x, hi.y}; }
;                 if (u.pn >= 4) { ss = quad_sum(ss); if (fq == 0) E.stOut[(size_t)row * 16 + (u.pn - 4) * 4 + wc] = ss; }
.LBB0_960:
	v_mov_b32_e32 v170, v149
	v_pk_mul_f32 v[152:153], v[22:23], v[170:171] op_sel_hi:[1,0]
	v_add_u32_e32 v148, 0xb0, v150
	s_waitcnt lgkmcnt(0)
	v_and_b32_e32 v151, 0x7fffffff, v153
	v_and_b32_e32 v150, 0x7fffffff, v152
	v_pk_fma_f32 v[150:151], v[150:151], s[40:41], 1.0 op_sel_hi:[1,0,0]
	v_pk_mul_f32 v[166:167], v[152:153], v[152:153]
	v_rcp_f32_e32 v154, v150
	v_rcp_f32_e32 v155, v151
	v_mov_b64_e32 v[150:151], s[44:45]
	v_pk_mul_f32 v[166:167], v[166:167], s[58:59] op_sel_hi:[1,0]
	v_pk_mul_f32 v[156:157], v[24:25], v[170:171] op_sel_hi:[1,0]
	v_pk_fma_f32 v[158:159], v[154:155], s[42:43], v[150:151] op_sel_hi:[1,0,0]
	v_exp_f32_e32 v166, v166
	v_pk_fma_f32 v[158:159], v[154:155], v[158:159], s[52:53] op_sel_hi:[1,1,0]
	v_exp_f32_e32 v167, v167
	v_pk_fma_f32 v[158:159], v[154:155], v[158:159], s[54:55] op_sel_hi:[1,1,0]
	v_and_b32_e32 v169, 0x7fffffff, v157
	v_and_b32_e32 v168, 0x7fffffff, v156
	v_pk_fma_f32 v[158:159], v[154:155], v[158:159], s[56:57] op_sel_hi:[1,1,0]
	v_pk_fma_f32 v[168:169], v[168:169], s[40:41], 1.0 op_sel_hi:[1,0,0]
	v_pk_mul_f32 v[154:155], v[154:155], v[158:159]
	v_rcp_f32_e32 v168, v168
	v_rcp_f32_e32 v169, v169
	v_pk_mul_f32 v[154:155], v[166:167], v[154:155]
	v_cmp_gt_f32_e32 vcc, 0, v152
	v_pk_mul_f32 v[166:167], v[152:153], v[154:155]
	v_pk_fma_f32 v[154:155], v[152:153], v[154:155], v[152:153] neg_lo:[1,0,0] neg_hi:[1,0,0]
	v_pk_mul_f32 v[158:159], v[156:157], v[156:157]
	v_cndmask_b32_e32 v152, v154, v166, vcc
	v_cmp_gt_f32_e32 vcc, 0, v153
	v_pk_mul_f32 v[158:159], v[158:159], s[58:59] op_sel_hi:[1,0]
	v_ashrrev_i32_e32 v149, 31, v148
	v_cndmask_b32_e32 v153, v155, v167, vcc
	v_pk_fma_f32 v[154:155], v[168:169], s[42:43], v[150:151] op_sel_hi:[1,0,0]
	v_exp_f32_e32 v158, v158
	v_pk_fma_f32 v[154:155], v[168:169], v[154:155], s[52:53] op_sel_hi:[1,1,0]
	v_exp_f32_e32 v159, v159
	v_pk_fma_f32 v[154:155], v[168:169], v[154:155], s[54:55] op_sel_hi:[1,1,0]
	v_pk_mul_f32 v[166:167], v[18:19], v[170:171] op_sel_hi:[1,0]
	v_pk_fma_f32 v[154:155], v[168:169], v[154:155], s[56:57] op_sel_hi:[1,1,0]
	v_cmp_gt_f32_e32 vcc, 0, v156
	v_pk_mul_f32 v[154:155], v[168:169], v[154:155]
	v_and_b32_e32 v169, 0x7fffffff, v167
	v_and_b32_e32 v168, 0x7fffffff, v166
	v_pk_fma_f32 v[168:169], v[168:169], s[40:41], 1.0 op_sel_hi:[1,0,0]
	v_pk_mul_f32 v[154:155], v[158:159], v[154:155]
	v_rcp_f32_e32 v168, v168
	v_rcp_f32_e32 v169, v169
	v_pk_mul_f32 v[158:159], v[156:157], v[154:155]
	v_pk_fma_f32 v[154:155], v[156:157], v[154:155], v[156:157] neg_lo:[1,0,0] neg_hi:[1,0,0]
	v_pk_mul_f32 v[172:173], v[166:167], v[166:167]
	v_cndmask_b32_e32 v154, v154, v158, vcc
	v_cmp_gt_f32_e32 vcc, 0, v157
	v_pk_fma_f32 v[156:157], v[168:169], s[42:43], v[150:151] op_sel_hi:[1,0,0]
	v_pk_mul_f32 v[172:173], v[172:173], s[58:59] op_sel_hi:[1,0]
	v_cndmask_b32_e32 v155, v155, v159, vcc
	v_pk_mul_f32 v[158:159], v[20:21], v[170:171] op_sel_hi:[1,0]
	v_pk_fma_f32 v[156:157], v[168:169], v[156:157], s[52:53] op_sel_hi:[1,1,0]
	v_exp_f32_e32 v172, v172
	v_exp_f32_e32 v173, v173
	v_and_b32_e32 v175, 0x7fffffff, v159
	v_and_b32_e32 v174, 0x7fffffff, v158
	v_pk_fma_f32 v[156:157], v[168:169], v[156:157], s[54:55] op_sel_hi:[1,1,0]
	v_pk_fma_f32 v[174:175], v[174:175], s[40:41], 1.0 op_sel_hi:[1,0,0]
	v_pk_fma_f32 v[156:157], v[168:169], v[156:157], s[56:57] op_sel_hi:[1,1,0]
	v_rcp_f32_e32 v174, v174
	v_rcp_f32_e32 v175, v175
	v_pk_mul_f32 v[156:157], v[168:169], v[156:157]
	v_cmp_gt_f32_e32 vcc, 0, v166
	v_pk_mul_f32 v[156:157], v[172:173], v[156:157]
	v_pk_mul_f32 v[168:169], v[158:159], v[158:159]
	v_pk_mul_f32 v[172:173], v[166:167], v[156:157]
	v_pk_fma_f32 v[156:157], v[166:167], v[156:157], v[166:167] neg_lo:[1,0,0] neg_hi:[1,0,0]
	v_pk_mul_f32 v[168:169], v[168:169], s[58:59] op_sel_hi:[1,0]
	v_cndmask_b32_e32 v156, v156, v172, vcc
	v_cmp_gt_f32_e32 vcc, 0, v167
	v_pk_fma_f32 v[166:167], v[174:175], s[42:43], v[150:151] op_sel_hi:[1,0,0]
	v_exp_f32_e32 v168, v168
	v_pk_fma_f32 v[166:167], v[174:175], v[166:167], s[52:53] op_sel_hi:[1,1,0]
	v_exp_f32_e32 v169, v169
	v_pk_fma_f32 v[166:167], v[174:175], v[166:167], s[54:55] op_sel_hi:[1,1,0]
	v_cndmask_b32_e32 v157, v157, v173, vcc
	v_pk_fma_f32 v[166:167], v[174:175], v[166:167], s[56:57] op_sel_hi:[1,1,0]
	v_cmp_gt_f32_e32 vcc, 0, v158
	v_pk_mul_f32 v[166:167], v[174:175], v[166:167]
	v_pk_mul_f32 v[174:175], v[122:123], v[170:171] op_sel_hi:[1,0]
	v_pk_mul_f32 v[166:167], v[168:169], v[166:167]
	v_and_b32_e32 v177, 0x7fffffff, v175
	v_and_b32_e32 v176, 0x7fffffff, v174
	v_pk_fma_f32 v[176:177], v[176:177], s[40:41], 1.0 op_sel_hi:[1,0,0]
	v_pk_mul_f32 v[168:169], v[158:159], v[166:167]
	v_rcp_f32_e32 v176, v176
	v_rcp_f32_e32 v177, v177
	v_pk_fma_f32 v[166:167], v[158:159], v[166:167], v[158:159] neg_lo:[1,0,0] neg_hi:[1,0,0]
	v_lshlrev_b64 v[172:173], 12, v[148:149]
	v_cndmask_b32_e32 v158, v166, v168, vcc
	v_cmp_gt_f32_e32 vcc, 0, v159
	v_lshl_add_u64 v[172:173], s[64:65], 0, v[172:173]
	v_cvt_pk_bf16_f32 v168, v156, v157
	v_lshl_add_u64 v[178:179], v[146:147], 1, v[172:173]
	v_cndmask_b32_e32 v159, v167, v169, vcc
	v_cvt_pk_bf16_f32 v169, v158, v159
	v_pk_fma_f32 v[146:147], v[176:177], s[42:43], v[150:151] op_sel_hi:[1,0,0]
	v_cvt_pk_bf16_f32 v166, v152, v153
	v_cvt_pk_bf16_f32 v167, v154, v155
	global_store_dwordx4 v[178:179], v[166:169], off sc1
	v_pk_fma_f32 v[146:147], v[176:177], v[146:147], s[52:53] op_sel_hi:[1,1,0]
	v_cmp_gt_f32_e32 vcc, 0, v174
	v_pk_mul_f32 v[168:169], v[174:175], v[174:175]
	v_pk_fma_f32 v[146:147], v[176:177], v[146:147], s[54:55] op_sel_hi:[1,1,0]
	v_pk_mul_f32 v[168:169], v[168:169], s[58:59] op_sel_hi:[1,0]
	v_pk_mul_f32 v[166:167], v[124:125], v[170:171] op_sel_hi:[1,0]
; __device__ __forceinline__ float dot4(f32x4 v) { return (v[0] * v[0] + v[1] * v[1]) + (v[2] * v[2] + v[3] * v[3]); }
; __device__ __forceinline__ u32x2 pack4(f32x4 v) { u32x2 w; w.x = cvt_pk_bf16(v[0], v[1]); w.y = cvt_pk_bf16(v[2], v[3]); return w; }
; __device__ __forceinline__ float quad_sum(float s) { s += __shfl_xor(s, 16); s += __shfl_xor(s, 32); return s; }
; __device__ __forceinline__ f32x4 gelu4(f32x4 v) { f32x2 a = gelu_pk((f32x2){v[0], v[1]}), b = gelu_pk((f32x2){v[2], v[3]}); return (f32x4){a.x, a.y, b.x, b.y}; }
; __device__ __forceinline__ f32x2 gelu_pk(f32x2 v) {
;     const f32x2 av = __builtin_elementwise_abs(v), d = av * 0.2316418882f + 1.0f;
;     f32x2 t; t.x = __builtin_amdgcn_rcpf(d.x); t.y = __builtin_amdgcn_rcpf(d.y);
;     f32x2 q = t * 0.5307027145f + (-0.7265760135f); q = q * t + 0.7107068705f; q = q * t + (-0.142248368f); q = q * t + 0.127414796f; q = q * t;
;     const f32x2 s = (v * v) * (-0.72134752044f);
;     f32x2 e; e.x = __builtin_amdgcn_exp2f(s.x); e.y = __builtin_amdgcn_exp2f(s.y);
;     const f32x2 m = v * (q * e), r = v - m;
;     f32x2 o; o.x = v.x < 0.f ? m.x : r.x; o.y = v.y < 0.f ? m.y : r.y; return o;
; }
; template <int EK>
; __device__ __forceinline__ void epi_tile(const f32x4 (&acc)[2][2][4][2], const Unit& u, int wr, int wc, int fr, int fq, const EpiArgs& E, const LAS float* rt) {
;     ...
;             } else if (EK == EK_GELU) {
;                 const float r = rr[ai][m]; float ss = 0.f;
; #pragma unroll
;                 for (int bj = 0; bj < 2; ++bj) { const int col = u.pn * BM + bj * HALF + wc * 32 + fq * 8;
;                     const f32x4 z0 = gelu4(acc[ai][bj][m][0] * r), z1 = gelu4(acc[ai][bj][m][1] * r); ss += dot4(z0) + dot4(z1);
;                     const u32x2 lo = pack4(z0), hi = pack4(z1);
;                     *(u32x4*)(E.ob + (size_t)row * E.ldb + col) = (u32x4){lo.x, lo.y, hi.x, hi.y}; }
;                 if (u.pn >= 4) { ss = quad_sum(ss); if (fq == 0) E.stOut[(size_t)row * 16 + (u.pn - 4) * 4 + wc] = ss; }
	v_exp_f32_e32 v168, v168
	v_exp_f32_e32 v169, v169
	v_pk_fma_f32 v[146:147], v[176:177], v[146:147], s[56:57] op_sel_hi:[1,1,0]
	v_pk_mul_f32 v[172:173], v[166:167], v[166:167]
	v_pk_mul_f32 v[146:147], v[176:177], v[146:147]
	v_and_b32_e32 v177, 0x7fffffff, v167
	v_and_b32_e32 v176, 0x7fffffff, v166
	v_pk_fma_f32 v[176:177], v[176:177], s[40:41], 1.0 op_sel_hi:[1,0,0]
	v_pk_mul_f32 v[146:147], v[168:169], v[146:147]
	v_rcp_f32_e32 v176, v176
	v_rcp_f32_e32 v177, v177
	v_pk_mul_f32 v[168:169], v[174:175], v[146:147]
	v_pk_fma_f32 v[146:147], v[174:175], v[146:147], v[174:175] neg_lo:[1,0,0] neg_hi:[1,0,0]
	v_pk_mul_f32 v[172:173], v[172:173], s[58:59] op_sel_hi:[1,0]
	v_cndmask_b32_e32 v146, v146, v168, vcc
	v_cmp_gt_f32_e32 vcc, 0, v175
	v_exp_f32_e32 v172, v172
	v_exp_f32_e32 v173, v173
	v_cndmask_b32_e32 v147, v147, v169, vcc
	v_pk_fma_f32 v[168:169], v[176:177], s[42:43], v[150:151] op_sel_hi:[1,0,0]
	v_pk_mul_f32 v[174:175], v[126:127], v[170:171] op_sel_hi:[1,0]
	v_pk_fma_f32 v[168:169], v[176:177], v[168:169], s[52:53] op_sel_hi:[1,1,0]
	v_cmp_gt_f32_e32 vcc, 0, v166
	v_pk_fma_f32 v[168:169], v[176:177], v[168:169], s[54:55] op_sel_hi:[1,1,0]
	v_pk_mul_f32 v[170:171], v[128:129], v[170:171] op_sel_hi:[1,0]
	v_pk_fma_f32 v[168:169], v[176:177], v[168:169], s[56:57] op_sel_hi:[1,1,0]
	v_and_b32_e32 v181, 0x7fffffff, v171
	v_pk_mul_f32 v[168:169], v[176:177], v[168:169]
	v_and_b32_e32 v177, 0x7fffffff, v175
	v_and_b32_e32 v176, 0x7fffffff, v174
	v_pk_fma_f32 v[176:177], v[176:177], s[40:41], 1.0 op_sel_hi:[1,0,0]
	v_pk_mul_f32 v[168:169], v[172:173], v[168:169]
	v_rcp_f32_e32 v176, v176
	v_rcp_f32_e32 v177, v177
	v_pk_mul_f32 v[172:173], v[166:167], v[168:169]
	v_pk_fma_f32 v[168:169], v[166:167], v[168:169], v[166:167] neg_lo:[1,0,0] neg_hi:[1,0,0]
	v_and_b32_e32 v180, 0x7fffffff, v170
	v_cndmask_b32_e32 v165, v168, v172, vcc
	v_cmp_gt_f32_e32 vcc, 0, v167
	v_pk_fma_f32 v[180:181], v[180:181], s[40:41], 1.0 op_sel_hi:[1,0,0]
	s_nop 0
	v_cndmask_b32_e32 v166, v169, v173, vcc
	v_pk_mul_f32 v[172:173], v[174:175], v[174:175]
	v_pk_fma_f32 v[168:169], v[176:177], s[42:43], v[150:151] op_sel_hi:[1,0,0]
	v_pk_mul_f32 v[172:173], v[172:173], s[58:59] op_sel_hi:[1,0]
	v_pk_fma_f32 v[168:169], v[176:177], v[168:169], s[52:53] op_sel_hi:[1,1,0]
	v_exp_f32_e32 v172, v172
	v_exp_f32_e32 v173, v173
	v_pk_fma_f32 v[168:169], v[176:177], v[168:169], s[54:55] op_sel_hi:[1,1,0]
	v_rcp_f32_e32 v180, v180
	v_pk_fma_f32 v[168:169], v[176:177], v[168:169], s[56:57] op_sel_hi:[1,1,0]
	v_rcp_f32_e32 v181, v181
	v_pk_mul_f32 v[168:169], v[176:177], v[168:169]
	v_cmp_gt_f32_e32 vcc, 0, v174
	v_pk_mul_f32 v[168:169], v[172:173], v[168:169]
	v_pk_mul_f32 v[176:177], v[170:171], v[170:171]
	v_pk_mul_f32 v[172:173], v[174:175], v[168:169]
	v_pk_fma_f32 v[168:169], v[174:175], v[168:169], v[174:175] neg_lo:[1,0,0] neg_hi:[1,0,0]
	v_pk_fma_f32 v[150:151], v[180:181], s[42:43], v[150:151] op_sel_hi:[1,0,0]
	v_cndmask_b32_e32 v167, v168, v172, vcc
	v_cmp_gt_f32_e32 vcc, 0, v175
	v_pk_fma_f32 v[150:151], v[180:181], v[150:151], s[52:53] op_sel_hi:[1,1,0]
	s_nop 0
	v_cndmask_b32_e32 v168, v169, v173, vcc
	v_pk_mul_f32 v[172:173], v[176:177], s[58:59] op_sel_hi:[1,0]
	v_pk_fma_f32 v[150:151], v[180:181], v[150:151], s[54:55] op_sel_hi:[1,1,0]
	v_exp_f32_e32 v172, v172
	v_exp_f32_e32 v173, v173
	v_pk_fma_f32 v[150:151], v[180:181], v[150:151], s[56:57] op_sel_hi:[1,1,0]
	v_cmp_gt_f32_e32 vcc, 0, v170
	v_pk_mul_f32 v[150:151], v[180:181], v[150:151]
	s_nop 0
	v_pk_mul_f32 v[150:151], v[172:173], v[150:151]
	s_nop 0
	v_pk_mul_f32 v[172:173], v[170:171], v[150:151]
	v_pk_fma_f32 v[150:151], v[170:171], v[150:151], v[170:171] neg_lo:[1,0,0] neg_hi:[1,0,0]
	v_cvt_pk_bf16_f32 v170, v146, v147
	s_nop 0
	v_cndmask_b32_e32 v150, v150, v172, vcc
	v_cmp_gt_f32_e32 vcc, 0, v171
	v_cvt_pk_bf16_f32 v171, v165, v166
	v_cvt_pk_bf16_f32 v172, v167, v168
	s_nop 1
	v_cndmask_b32_e32 v151, v151, v173, vcc
	s_and_b64 vcc, exec, s[10:11]
	v_cvt_pk_bf16_f32 v173, v150, v151
	global_store_dwordx4 v[178:179], v[170:173], off offset:256 sc1
	s_cbranch_vccnz .LBB0_964
	v_mul_f32_e32 v147, v147, v147
	v_fmac_f32_e32 v147, v146, v146
	v_mul_f32_e32 v146, v166, v166
	v_mul_f32_e32 v153, v153, v153
	v_fmac_f32_e32 v146, v165, v165
	v_fmac_f32_e32 v153, v152, v152
	v_mul_f32_e32 v152, v155, v155
	v_add_f32_e32 v146, v147, v146
	v_mul_f32_e32 v147, v168, v168
	v_mul_f32_e32 v151, v151, v151
	v_fmac_f32_e32 v152, v154, v154
	v_fmac_f32_e32 v147, v167, v167
	v_fmac_f32_e32 v151, v150, v150
	v_add_f32_e32 v152, v153, v152
	v_mul_f32_e32 v153, v157, v157
	v_mul_f32_e32 v154, v159, v159
	v_add_f32_e32 v147, v147, v151
	v_and_b32_e32 v150, 64, v164
	v_fmac_f32_e32 v153, v156, v156
	v_fmac_f32_e32 v154, v158, v158
	v_add_f32_e32 v146, v146, v147
	v_xor_b32_e32 v147, 16, v164
	v_add_u32_e32 v150, 64, v150
	v_add_f32_e32 v153, v153, v154
	v_cmp_lt_i32_e32 vcc, v147, v150
	v_add_f32_e32 v152, v152, v153
	v_add_f32_e32 v146, v152, v146
	v_cndmask_b32_e32 v147, v164, v147, vcc
	v_lshlrev_b32_e32 v147, 2, v147
	ds_bpermute_b32 v147, v147, v146
	s_waitcnt lgkmcnt(0)
	v_add_f32_e32 v146, v146, v147
	v_xor_b32_e32 v147, 32, v164
	v_cmp_lt_i32_e32 vcc, v147, v150
	s_nop 1
	v_cndmask_b32_e32 v147, v164, v147, vcc
	v_lshlrev_b32_e32 v147, 2, v147
	ds_bpermute_b32 v147, v147, v146
	s_and_saveexec_b64 s[10:11], s[4:5]
	s_cbranch_execz .LBB0_963
	v_lshlrev_b64 v[148:149], 6, v[148:149]
	v_lshl_add_u64 v[148:149], s[18:19], 0, v[148:149]
	v_lshl_add_u64 v[148:149], s[76:77], 2, v[148:149]
	s_lshl_b32 s14, s59, 2
	v_lshl_add_u64 v[148:149], v[148:149], 0, s[14:15]
	s_waitcnt lgkmcnt(0)
	v_add_f32_e32 v146, v146, v147
	global_store_dword v[148:149], v146, off sc1
